# back-edge rotation (asm guide 7.11) on the four GEMM mainloops: loop-back barrier becomes the loop head, branch issued before it
# baseline (speedup 1.0000x reference)
.LBB0_211:
	s_add_i32 s60, s60, 1
	s_mov_b64 s[36:37], s[18:19]
	s_mul_i32 s18, s60, s26
	s_add_i32 s38, s18, s2
	s_cmpk_gt_i32 s38, 0x1ff
	s_cselect_b64 s[44:45], -1, 0
	s_lshl_b32 s18, s38, 3
	s_and_b32 s18, s18, 56
	s_bfe_u32 s19, s38, 0x30003
	s_mov_b32 s27, s61
	s_or_b32 s61, s18, s19
	s_mov_b32 s3, s42
	s_ashr_i32 s42, s38, 6
	s_lshl_b32 s18, s61, 19
	s_mov_b64 s[4:5], s[20:21]
	s_add_u32 s20, s14, s18
	s_addc_u32 s21, s15, 0
	s_ashr_i32 s43, s42, 31
	s_lshl_b64 s[18:19], s[42:43], 19
	s_add_u32 s18, s16, s18
	s_addc_u32 s19, s17, s19
	s_cmpk_lt_i32 s38, 0x200
	s_cselect_b32 s38, s21, s5
	s_cselect_b32 s43, s20, s4
	s_cselect_b32 s62, s19, s37
	s_cselect_b32 s63, s18, s36
	s_add_u32 s64, s36, 0x100
	s_addc_u32 s65, s37, 0
	s_mov_b32 s66, -2
	s_waitcnt lgkmcnt(0)
	s_add_u32 s36, s4, 0x100
	s_addc_u32 s37, s5, 0
	s_add_i32 s67, 0, 0x10000
	v_add_u32_e32 v1, s67, v191
	ds_read_b128 v[34:37], v1
	ds_read_b128 v[38:41], v1 offset:1024
	ds_read_b128 v[42:45], v1 offset:2048
	ds_read_b128 v[46:49], v1 offset:3072
	s_cmp_eq_u32 s66, 12
	s_cselect_b32 s49, s38, s37
	s_cselect_b32 s48, s43, s36
	s_cselect_b32 s47, s62, s65
	s_cselect_b32 s46, s63, s64
	v_lshl_add_u64 v[186:187], s[4:5], 0, v[168:169]
	s_add_i32 m0, s53, 0xc000
	ds_read_b128 v[50:53], v206
	ds_read_b128 v[58:61], v206 offset:1024
	ds_read_b128 v[62:65], v206 offset:2048
	ds_read_b128 v[66:69], v206 offset:3072
	ds_read_b128 v[170:173], v206 offset:4096
	ds_read_b128 v[174:177], v206 offset:5120
	ds_read_b128 v[178:181], v206 offset:6144
	ds_read_b128 v[182:185], v206 offset:7168
	global_load_lds_dwordx4 v[186:187], off
	v_lshl_add_u64 v[186:187], s[4:5], 0, v[166:167]
	s_add_i32 m0, s53, 0xe000
	s_nop 0
	global_load_lds_dwordx4 v[186:187], off
	s_waitcnt lgkmcnt(8)
	s_barrier
	s_waitcnt lgkmcnt(0)
	s_setprio 1
	s_waitcnt lgkmcnt(0)
	v_mfma_f32_16x16x32_bf16 v[158:161], v[34:37], v[50:53], 0
	v_mfma_f32_16x16x32_bf16 v[154:157], v[42:45], v[50:53], 0
	v_mfma_f32_16x16x32_bf16 v[142:145], v[34:37], v[62:65], 0
	v_mfma_f32_16x16x32_bf16 v[138:141], v[42:45], v[62:65], 0
	v_mfma_f32_16x16x32_bf16 v[126:129], v[34:37], v[170:173], 0
	v_mfma_f32_16x16x32_bf16 v[122:125], v[42:45], v[170:173], 0
	v_mfma_f32_16x16x32_bf16 v[110:113], v[34:37], v[178:181], 0
	v_mfma_f32_16x16x32_bf16 v[106:109], v[42:45], v[178:181], 0
	v_mfma_f32_16x16x32_bf16 v[158:161], v[38:41], v[58:61], v[158:161]
	v_mfma_f32_16x16x32_bf16 v[154:157], v[46:49], v[58:61], v[154:157]
	v_mfma_f32_16x16x32_bf16 v[142:145], v[38:41], v[66:69], v[142:145]
	v_mfma_f32_16x16x32_bf16 v[138:141], v[46:49], v[66:69], v[138:141]
	v_mfma_f32_16x16x32_bf16 v[126:129], v[38:41], v[174:177], v[126:129]
	v_mfma_f32_16x16x32_bf16 v[122:125], v[46:49], v[174:177], v[122:125]
	v_mfma_f32_16x16x32_bf16 v[110:113], v[38:41], v[182:185], v[110:113]
	v_mfma_f32_16x16x32_bf16 v[106:109], v[46:49], v[182:185], v[106:109]
	s_setprio 0
	s_barrier
	s_add_i32 s68, 0, 0x14000
	s_add_i32 s4, s67, s52
	v_add_u32_e32 v1, s68, v191
	v_lshl_add_u64 v[214:215], s[46:47], 0, v[164:165]
	s_mov_b32 m0, s4
	ds_read_b128 v[186:189], v1
	ds_read_b128 v[208:211], v1 offset:1024
	ds_read_b128 v[222:225], v1 offset:2048
	ds_read_b128 v[226:229], v1 offset:3072
	global_load_lds_dwordx4 v[214:215], off
	v_lshl_add_u64 v[238:239], s[46:47], 0, v[162:163]
	s_add_i32 m0, s4, 0x2000
	s_nop 0
	global_load_lds_dwordx4 v[238:239], off
	s_barrier
	s_waitcnt lgkmcnt(0)
	s_setprio 1
	s_waitcnt lgkmcnt(0)
	v_mfma_f32_16x16x32_bf16 v[150:153], v[186:189], v[50:53], 0
	v_mfma_f32_16x16x32_bf16 v[50:53], v[222:225], v[50:53], 0
	v_mfma_f32_16x16x32_bf16 v[150:153], v[208:211], v[58:61], v[150:153]
	v_mfma_f32_16x16x32_bf16 v[50:53], v[226:229], v[58:61], v[50:53]
	v_mfma_f32_16x16x32_bf16 v[58:61], v[186:189], v[62:65], 0
	v_mfma_f32_16x16x32_bf16 v[62:65], v[222:225], v[62:65], 0
	v_mfma_f32_16x16x32_bf16 v[114:117], v[222:225], v[170:173], 0
	v_mfma_f32_16x16x32_bf16 v[102:105], v[186:189], v[178:181], 0
	v_mfma_f32_16x16x32_bf16 v[98:101], v[222:225], v[178:181], 0
	v_mfma_f32_16x16x32_bf16 v[58:61], v[208:211], v[66:69], v[58:61]
	v_mfma_f32_16x16x32_bf16 v[62:65], v[226:229], v[66:69], v[62:65]
	v_mfma_f32_16x16x32_bf16 v[66:69], v[186:189], v[170:173], 0
	v_mfma_f32_16x16x32_bf16 v[114:117], v[226:229], v[174:177], v[114:117]
	v_mfma_f32_16x16x32_bf16 v[102:105], v[208:211], v[182:185], v[102:105]
	v_mfma_f32_16x16x32_bf16 v[98:101], v[226:229], v[182:185], v[98:101]
	v_mfma_f32_16x16x32_bf16 v[66:69], v[208:211], v[174:177], v[66:69]
	s_setprio 0
	s_mov_b32 m0, s53
	v_lshl_add_u64 v[240:241], s[48:49], 0, v[164:165]
	s_barrier
	ds_read_b128 v[118:121], v206 offset:16384
	ds_read_b128 v[130:133], v206 offset:17408
	ds_read_b128 v[134:137], v206 offset:18432
	ds_read_b128 v[146:149], v206 offset:19456
	ds_read_b128 v[170:173], v206 offset:20480
	ds_read_b128 v[174:177], v206 offset:21504
	ds_read_b128 v[178:181], v206 offset:22528
	ds_read_b128 v[182:185], v206 offset:23552
	global_load_lds_dwordx4 v[240:241], off
	v_lshl_add_u64 v[242:243], s[48:49], 0, v[162:163]
	s_mov_b32 m0, s54
	s_nop 0
	global_load_lds_dwordx4 v[242:243], off
	s_barrier
	s_waitcnt lgkmcnt(0)
	s_setprio 1
	s_waitcnt lgkmcnt(0)
	v_mfma_f32_16x16x32_bf16 v[94:97], v[34:37], v[118:121], 0
	v_mfma_f32_16x16x32_bf16 v[90:93], v[42:45], v[118:121], 0
	v_mfma_f32_16x16x32_bf16 v[78:81], v[34:37], v[134:137], 0
	v_mfma_f32_16x16x32_bf16 v[74:77], v[42:45], v[134:137], 0
	v_mfma_f32_16x16x32_bf16 v[30:33], v[34:37], v[170:173], 0
	v_mfma_f32_16x16x32_bf16 v[26:29], v[42:45], v[170:173], 0
	v_mfma_f32_16x16x32_bf16 v[14:17], v[34:37], v[178:181], 0
	v_mfma_f32_16x16x32_bf16 v[10:13], v[42:45], v[178:181], 0
	v_mfma_f32_16x16x32_bf16 v[94:97], v[38:41], v[130:133], v[94:97]
	v_mfma_f32_16x16x32_bf16 v[90:93], v[46:49], v[130:133], v[90:93]
	v_mfma_f32_16x16x32_bf16 v[78:81], v[38:41], v[146:149], v[78:81]
	v_mfma_f32_16x16x32_bf16 v[74:77], v[46:49], v[146:149], v[74:77]
	v_mfma_f32_16x16x32_bf16 v[30:33], v[38:41], v[174:177], v[30:33]
	v_mfma_f32_16x16x32_bf16 v[26:29], v[46:49], v[174:177], v[26:29]
	v_mfma_f32_16x16x32_bf16 v[14:17], v[38:41], v[182:185], v[14:17]
	v_mfma_f32_16x16x32_bf16 v[10:13], v[46:49], v[182:185], v[10:13]
	s_setprio 0
	s_barrier
	s_add_u32 s4, s46, 0x40000
	s_addc_u32 s5, s47, 0
	s_add_i32 s67, s68, s52
	v_lshl_add_u64 v[34:35], s[4:5], 0, v[164:165]
	s_mov_b32 m0, s67
	s_nop 0
	global_load_lds_dwordx4 v[34:35], off
	v_lshl_add_u64 v[34:35], s[4:5], 0, v[162:163]
	s_add_i32 m0, s67, 0x2000
	s_nop 0
	global_load_lds_dwordx4 v[34:35], off
	s_waitcnt vmcnt(6)
	s_barrier
	s_setprio 1
	v_mfma_f32_16x16x32_bf16 v[22:25], v[186:189], v[170:173], 0
	v_mfma_f32_16x16x32_bf16 v[18:21], v[222:225], v[170:173], 0
	v_mfma_f32_16x16x32_bf16 v[6:9], v[186:189], v[178:181], 0
	v_mfma_f32_16x16x32_bf16 v[2:5], v[222:225], v[178:181], 0
	v_mfma_f32_16x16x32_bf16 v[34:37], v[186:189], v[118:121], 0
	v_mfma_f32_16x16x32_bf16 v[38:41], v[222:225], v[118:121], 0
	v_mfma_f32_16x16x32_bf16 v[42:45], v[186:189], v[134:137], 0
	v_mfma_f32_16x16x32_bf16 v[46:49], v[222:225], v[134:137], 0
	v_mfma_f32_16x16x32_bf16 v[22:25], v[208:211], v[174:177], v[22:25]
	v_mfma_f32_16x16x32_bf16 v[18:21], v[226:229], v[174:177], v[18:21]
	v_mfma_f32_16x16x32_bf16 v[6:9], v[208:211], v[182:185], v[6:9]
	v_mfma_f32_16x16x32_bf16 v[2:5], v[226:229], v[182:185], v[2:5]
	v_mfma_f32_16x16x32_bf16 v[34:37], v[208:211], v[130:133], v[34:37]
	v_mfma_f32_16x16x32_bf16 v[38:41], v[226:229], v[130:133], v[38:41]
	v_mfma_f32_16x16x32_bf16 v[42:45], v[208:211], v[146:149], v[42:45]
	v_mfma_f32_16x16x32_bf16 v[46:49], v[226:229], v[146:149], v[46:49]
	s_setprio 0
	s_add_i32 s67, 0, 0x18000
	v_add_u32_e32 v1, s67, v191
	s_barrier
	ds_read_b128 v[54:57], v1
	ds_read_b128 v[70:73], v1 offset:1024
	ds_read_b128 v[82:85], v1 offset:2048
	ds_read_b128 v[86:89], v1 offset:3072
	s_add_u32 s4, s48, 0x40000
	s_addc_u32 s5, s49, 0
	s_mov_b32 m0, s55
	v_lshl_add_u64 v[134:135], s[4:5], 0, v[164:165]
	ds_read_b128 v[118:121], v206 offset:32768
	ds_read_b128 v[130:133], v206 offset:33792
	ds_read_b128 v[170:173], v206 offset:34816
	ds_read_b128 v[174:177], v206 offset:35840
	ds_read_b128 v[178:181], v206 offset:36864
	ds_read_b128 v[182:185], v206 offset:37888
	ds_read_b128 v[186:189], v206 offset:38912
	ds_read_b128 v[208:211], v206 offset:39936
	global_load_lds_dwordx4 v[134:135], off
	v_lshl_add_u64 v[134:135], s[4:5], 0, v[162:163]
	s_mov_b32 m0, s56
	s_nop 0
	global_load_lds_dwordx4 v[134:135], off
	s_waitcnt lgkmcnt(8)
	s_barrier
	s_waitcnt lgkmcnt(0)
	s_setprio 1
	s_waitcnt lgkmcnt(0)
	v_mfma_f32_16x16x32_bf16 v[134:137], v[54:57], v[118:121], v[158:161]
	v_mfma_f32_16x16x32_bf16 v[158:161], v[70:73], v[130:133], v[134:137]
	v_mfma_f32_16x16x32_bf16 v[134:137], v[82:85], v[118:121], v[154:157]
	v_mfma_f32_16x16x32_bf16 v[154:157], v[86:89], v[130:133], v[134:137]
	v_mfma_f32_16x16x32_bf16 v[134:137], v[54:57], v[170:173], v[142:145]
	v_mfma_f32_16x16x32_bf16 v[142:145], v[70:73], v[174:177], v[134:137]
	v_mfma_f32_16x16x32_bf16 v[134:137], v[82:85], v[170:173], v[138:141]
	v_mfma_f32_16x16x32_bf16 v[126:129], v[54:57], v[178:181], v[126:129]
	v_mfma_f32_16x16x32_bf16 v[122:125], v[82:85], v[178:181], v[122:125]
	v_mfma_f32_16x16x32_bf16 v[110:113], v[54:57], v[186:189], v[110:113]
	v_mfma_f32_16x16x32_bf16 v[106:109], v[82:85], v[186:189], v[106:109]
	v_mfma_f32_16x16x32_bf16 v[138:141], v[86:89], v[174:177], v[134:137]
	v_mfma_f32_16x16x32_bf16 v[126:129], v[70:73], v[182:185], v[126:129]
	v_mfma_f32_16x16x32_bf16 v[122:125], v[86:89], v[182:185], v[122:125]
	v_mfma_f32_16x16x32_bf16 v[110:113], v[70:73], v[208:211], v[110:113]
	v_mfma_f32_16x16x32_bf16 v[106:109], v[86:89], v[208:211], v[106:109]
	s_setprio 0
	s_barrier
	s_add_i32 s48, 0, 0x1c000
	s_add_i32 s4, s67, s52
	v_add_u32_e32 v1, s48, v191
	v_lshl_add_u64 v[134:135], v[214:215], 0, s[22:23]
	s_mov_b32 m0, s4
	ds_read_b128 v[222:225], v1
	ds_read_b128 v[226:229], v1 offset:1024
	ds_read_b128 v[230:233], v1 offset:2048
	ds_read_b128 v[234:237], v1 offset:3072
	global_load_lds_dwordx4 v[134:135], off
	v_lshl_add_u64 v[134:135], v[238:239], 0, s[22:23]
	s_add_i32 m0, s4, 0x2000
	s_nop 0
	global_load_lds_dwordx4 v[134:135], off
	s_barrier
	s_waitcnt lgkmcnt(0)
	s_setprio 1
	s_waitcnt lgkmcnt(0)
	v_mfma_f32_16x16x32_bf16 v[50:53], v[230:233], v[118:121], v[50:53]
	v_mfma_f32_16x16x32_bf16 v[134:137], v[222:225], v[118:121], v[150:153]
	v_mfma_f32_16x16x32_bf16 v[146:149], v[234:237], v[130:133], v[50:53]
	v_mfma_f32_16x16x32_bf16 v[50:53], v[222:225], v[170:173], v[58:61]
	v_mfma_f32_16x16x32_bf16 v[150:153], v[226:229], v[130:133], v[134:137]
	v_mfma_f32_16x16x32_bf16 v[134:137], v[226:229], v[174:177], v[50:53]
	v_mfma_f32_16x16x32_bf16 v[50:53], v[230:233], v[170:173], v[62:65]
	v_mfma_f32_16x16x32_bf16 v[130:133], v[234:237], v[174:177], v[50:53]
	v_mfma_f32_16x16x32_bf16 v[50:53], v[222:225], v[178:181], v[66:69]
	v_mfma_f32_16x16x32_bf16 v[118:121], v[226:229], v[182:185], v[50:53]
	v_mfma_f32_16x16x32_bf16 v[50:53], v[230:233], v[178:181], v[114:117]
	v_mfma_f32_16x16x32_bf16 v[114:117], v[234:237], v[182:185], v[50:53]
	v_mfma_f32_16x16x32_bf16 v[50:53], v[222:225], v[186:189], v[102:105]
	v_mfma_f32_16x16x32_bf16 v[102:105], v[226:229], v[208:211], v[50:53]
	v_mfma_f32_16x16x32_bf16 v[50:53], v[230:233], v[186:189], v[98:101]
	v_mfma_f32_16x16x32_bf16 v[98:101], v[234:237], v[208:211], v[50:53]
	s_setprio 0
	s_mov_b32 m0, s58
	v_lshl_add_u64 v[186:187], v[240:241], 0, s[22:23]
	s_barrier
	s_nop 2
	ds_read_b128 v[50:53], v206 offset:49152
	ds_read_b128 v[58:61], v206 offset:50176
	ds_read_b128 v[62:65], v206 offset:51200
	ds_read_b128 v[66:69], v206 offset:52224
	ds_read_b128 v[170:173], v206 offset:53248
	ds_read_b128 v[174:177], v206 offset:54272
	ds_read_b128 v[178:181], v206 offset:55296
	ds_read_b128 v[182:185], v206 offset:56320
	global_load_lds_dwordx4 v[186:187], off
	v_lshl_add_u64 v[186:187], v[242:243], 0, s[22:23]
	s_mov_b32 m0, s59
	s_nop 0
	global_load_lds_dwordx4 v[186:187], off
	s_barrier
	s_waitcnt lgkmcnt(0)
	s_setprio 1
	s_waitcnt lgkmcnt(0)
	v_mfma_f32_16x16x32_bf16 v[94:97], v[54:57], v[50:53], v[94:97]
	v_mfma_f32_16x16x32_bf16 v[90:93], v[82:85], v[50:53], v[90:93]
	v_mfma_f32_16x16x32_bf16 v[78:81], v[54:57], v[62:65], v[78:81]
	v_mfma_f32_16x16x32_bf16 v[74:77], v[82:85], v[62:65], v[74:77]
	v_mfma_f32_16x16x32_bf16 v[30:33], v[54:57], v[170:173], v[30:33]
	v_mfma_f32_16x16x32_bf16 v[26:29], v[82:85], v[170:173], v[26:29]
	v_mfma_f32_16x16x32_bf16 v[14:17], v[54:57], v[178:181], v[14:17]
	v_mfma_f32_16x16x32_bf16 v[10:13], v[82:85], v[178:181], v[10:13]
	v_mfma_f32_16x16x32_bf16 v[94:97], v[70:73], v[58:61], v[94:97]
	v_mfma_f32_16x16x32_bf16 v[90:93], v[86:89], v[58:61], v[90:93]
	v_mfma_f32_16x16x32_bf16 v[78:81], v[70:73], v[66:69], v[78:81]
	v_mfma_f32_16x16x32_bf16 v[74:77], v[86:89], v[66:69], v[74:77]
	v_mfma_f32_16x16x32_bf16 v[30:33], v[70:73], v[174:177], v[30:33]
	v_mfma_f32_16x16x32_bf16 v[26:29], v[86:89], v[174:177], v[26:29]
	v_mfma_f32_16x16x32_bf16 v[14:17], v[70:73], v[182:185], v[14:17]
	v_mfma_f32_16x16x32_bf16 v[10:13], v[86:89], v[182:185], v[10:13]
	s_setprio 0
	s_barrier
	s_add_u32 s4, s46, 0x40080
	s_addc_u32 s5, s47, 0
	s_add_i32 s46, s48, s52
	v_lshl_add_u64 v[54:55], s[4:5], 0, v[164:165]
	s_mov_b32 m0, s46
	s_nop 0
	global_load_lds_dwordx4 v[54:55], off
	v_lshl_add_u64 v[54:55], s[4:5], 0, v[162:163]
	s_add_i32 m0, s46, 0x2000
	s_nop 0
	global_load_lds_dwordx4 v[54:55], off
	s_waitcnt vmcnt(6)
	s_barrier
	s_setprio 1
	v_mfma_f32_16x16x32_bf16 v[34:37], v[222:225], v[50:53], v[34:37]
	v_mfma_f32_16x16x32_bf16 v[86:89], v[226:229], v[58:61], v[34:37]
	v_mfma_f32_16x16x32_bf16 v[34:37], v[230:233], v[50:53], v[38:41]
	v_mfma_f32_16x16x32_bf16 v[82:85], v[234:237], v[58:61], v[34:37]
	v_mfma_f32_16x16x32_bf16 v[34:37], v[222:225], v[62:65], v[42:45]
	v_mfma_f32_16x16x32_bf16 v[70:73], v[226:229], v[66:69], v[34:37]
	v_mfma_f32_16x16x32_bf16 v[34:37], v[230:233], v[62:65], v[46:49]
	v_mfma_f32_16x16x32_bf16 v[22:25], v[222:225], v[170:173], v[22:25]
	v_mfma_f32_16x16x32_bf16 v[18:21], v[230:233], v[170:173], v[18:21]
	v_mfma_f32_16x16x32_bf16 v[6:9], v[222:225], v[178:181], v[6:9]
	v_mfma_f32_16x16x32_bf16 v[2:5], v[230:233], v[178:181], v[2:5]
	v_mfma_f32_16x16x32_bf16 v[54:57], v[234:237], v[66:69], v[34:37]
	v_mfma_f32_16x16x32_bf16 v[22:25], v[226:229], v[174:177], v[22:25]
	v_mfma_f32_16x16x32_bf16 v[18:21], v[234:237], v[174:177], v[18:21]
	v_mfma_f32_16x16x32_bf16 v[6:9], v[226:229], v[182:185], v[6:9]
	v_mfma_f32_16x16x32_bf16 v[2:5], v[234:237], v[182:185], v[2:5]
	s_setprio 0
	s_add_i32 s66, s66, 2
	s_add_u32 s64, s64, 0x100
	s_addc_u32 s65, s65, 0
	s_cmp_gt_u32 s66, 13
	s_mov_b64 s[4:5], s[36:37]

.LBB0_212:
	s_add_u32 s36, s4, 0x100
	s_addc_u32 s37, s5, 0
	s_add_i32 s67, 0, 0x10000
	v_add_u32_e32 v1, s67, v191
	ds_read_b128 v[34:37], v1
	ds_read_b128 v[38:41], v1 offset:1024
	ds_read_b128 v[42:45], v1 offset:2048
	ds_read_b128 v[46:49], v1 offset:3072
	s_cmp_eq_u32 s66, 12
	s_cselect_b32 s49, s38, s37
	s_cselect_b32 s48, s43, s36
	s_cselect_b32 s47, s62, s65
	s_cselect_b32 s46, s63, s64
	v_lshl_add_u64 v[186:187], s[4:5], 0, v[168:169]
	s_add_i32 m0, s53, 0xc000
	ds_read_b128 v[50:53], v206
	ds_read_b128 v[58:61], v206 offset:1024
	ds_read_b128 v[62:65], v206 offset:2048
	ds_read_b128 v[66:69], v206 offset:3072
	ds_read_b128 v[170:173], v206 offset:4096
	ds_read_b128 v[174:177], v206 offset:5120
	ds_read_b128 v[178:181], v206 offset:6144
	ds_read_b128 v[182:185], v206 offset:7168
	global_load_lds_dwordx4 v[186:187], off
	v_lshl_add_u64 v[186:187], s[4:5], 0, v[166:167]
	s_add_i32 m0, s53, 0xe000
	s_nop 0
	global_load_lds_dwordx4 v[186:187], off
	s_waitcnt lgkmcnt(8)
	s_barrier
	s_waitcnt lgkmcnt(0)
	s_setprio 1
	s_waitcnt lgkmcnt(0)
	v_mfma_f32_16x16x32_bf16 v[158:161], v[34:37], v[50:53], v[158:161]
	v_mfma_f32_16x16x32_bf16 v[154:157], v[42:45], v[50:53], v[154:157]
	v_mfma_f32_16x16x32_bf16 v[142:145], v[34:37], v[62:65], v[142:145]
	v_mfma_f32_16x16x32_bf16 v[138:141], v[42:45], v[62:65], v[138:141]
	v_mfma_f32_16x16x32_bf16 v[126:129], v[34:37], v[170:173], v[126:129]
	v_mfma_f32_16x16x32_bf16 v[122:125], v[42:45], v[170:173], v[122:125]
	v_mfma_f32_16x16x32_bf16 v[110:113], v[34:37], v[178:181], v[110:113]
	v_mfma_f32_16x16x32_bf16 v[106:109], v[42:45], v[178:181], v[106:109]
	v_mfma_f32_16x16x32_bf16 v[158:161], v[38:41], v[58:61], v[158:161]
	v_mfma_f32_16x16x32_bf16 v[154:157], v[46:49], v[58:61], v[154:157]
	v_mfma_f32_16x16x32_bf16 v[142:145], v[38:41], v[66:69], v[142:145]
	v_mfma_f32_16x16x32_bf16 v[138:141], v[46:49], v[66:69], v[138:141]
	v_mfma_f32_16x16x32_bf16 v[126:129], v[38:41], v[174:177], v[126:129]
	v_mfma_f32_16x16x32_bf16 v[122:125], v[46:49], v[174:177], v[122:125]
	v_mfma_f32_16x16x32_bf16 v[110:113], v[38:41], v[182:185], v[110:113]
	v_mfma_f32_16x16x32_bf16 v[106:109], v[46:49], v[182:185], v[106:109]
	s_setprio 0
	s_barrier
	s_add_i32 s68, 0, 0x14000
	s_add_i32 s4, s67, s52
	v_add_u32_e32 v1, s68, v191
	v_lshl_add_u64 v[214:215], s[46:47], 0, v[164:165]
	s_mov_b32 m0, s4
	ds_read_b128 v[186:189], v1
	ds_read_b128 v[208:211], v1 offset:1024
	ds_read_b128 v[222:225], v1 offset:2048
	ds_read_b128 v[226:229], v1 offset:3072
	global_load_lds_dwordx4 v[214:215], off
	v_lshl_add_u64 v[238:239], s[46:47], 0, v[162:163]
	s_add_i32 m0, s4, 0x2000
	s_nop 0
	global_load_lds_dwordx4 v[238:239], off
	s_barrier
	s_waitcnt lgkmcnt(0)
	s_setprio 1
	s_waitcnt lgkmcnt(0)
	v_mfma_f32_16x16x32_bf16 v[150:153], v[186:189], v[50:53], v[150:153]
	v_mfma_f32_16x16x32_bf16 v[50:53], v[222:225], v[50:53], v[146:149]
	v_mfma_f32_16x16x32_bf16 v[150:153], v[208:211], v[58:61], v[150:153]
	v_mfma_f32_16x16x32_bf16 v[50:53], v[226:229], v[58:61], v[50:53]
	v_mfma_f32_16x16x32_bf16 v[58:61], v[186:189], v[62:65], v[134:137]
	v_mfma_f32_16x16x32_bf16 v[62:65], v[222:225], v[62:65], v[130:133]
	v_mfma_f32_16x16x32_bf16 v[114:117], v[222:225], v[170:173], v[114:117]
	v_mfma_f32_16x16x32_bf16 v[102:105], v[186:189], v[178:181], v[102:105]
	v_mfma_f32_16x16x32_bf16 v[98:101], v[222:225], v[178:181], v[98:101]
	v_mfma_f32_16x16x32_bf16 v[58:61], v[208:211], v[66:69], v[58:61]
	v_mfma_f32_16x16x32_bf16 v[62:65], v[226:229], v[66:69], v[62:65]
	v_mfma_f32_16x16x32_bf16 v[66:69], v[186:189], v[170:173], v[118:121]
	v_mfma_f32_16x16x32_bf16 v[114:117], v[226:229], v[174:177], v[114:117]
	v_mfma_f32_16x16x32_bf16 v[102:105], v[208:211], v[182:185], v[102:105]
	v_mfma_f32_16x16x32_bf16 v[98:101], v[226:229], v[182:185], v[98:101]
	v_mfma_f32_16x16x32_bf16 v[66:69], v[208:211], v[174:177], v[66:69]
	s_setprio 0
	s_mov_b32 m0, s53
	v_lshl_add_u64 v[240:241], s[48:49], 0, v[164:165]
	s_barrier
	ds_read_b128 v[118:121], v206 offset:16384
	ds_read_b128 v[130:133], v206 offset:17408
	ds_read_b128 v[134:137], v206 offset:18432
	ds_read_b128 v[146:149], v206 offset:19456
	ds_read_b128 v[170:173], v206 offset:20480
	ds_read_b128 v[174:177], v206 offset:21504
	ds_read_b128 v[178:181], v206 offset:22528
	ds_read_b128 v[182:185], v206 offset:23552
	global_load_lds_dwordx4 v[240:241], off
	v_lshl_add_u64 v[242:243], s[48:49], 0, v[162:163]
	s_mov_b32 m0, s54
	s_nop 0
	global_load_lds_dwordx4 v[242:243], off
	s_barrier
	s_waitcnt lgkmcnt(0)
	s_setprio 1
	s_waitcnt lgkmcnt(0)
	v_mfma_f32_16x16x32_bf16 v[94:97], v[34:37], v[118:121], v[94:97]
	v_mfma_f32_16x16x32_bf16 v[90:93], v[42:45], v[118:121], v[90:93]
	v_mfma_f32_16x16x32_bf16 v[78:81], v[34:37], v[134:137], v[78:81]
	v_mfma_f32_16x16x32_bf16 v[74:77], v[42:45], v[134:137], v[74:77]
	v_mfma_f32_16x16x32_bf16 v[30:33], v[34:37], v[170:173], v[30:33]
	v_mfma_f32_16x16x32_bf16 v[26:29], v[42:45], v[170:173], v[26:29]
	v_mfma_f32_16x16x32_bf16 v[14:17], v[34:37], v[178:181], v[14:17]
	v_mfma_f32_16x16x32_bf16 v[10:13], v[42:45], v[178:181], v[10:13]
	v_mfma_f32_16x16x32_bf16 v[94:97], v[38:41], v[130:133], v[94:97]
	v_mfma_f32_16x16x32_bf16 v[90:93], v[46:49], v[130:133], v[90:93]
	v_mfma_f32_16x16x32_bf16 v[78:81], v[38:41], v[146:149], v[78:81]
	v_mfma_f32_16x16x32_bf16 v[74:77], v[46:49], v[146:149], v[74:77]
	v_mfma_f32_16x16x32_bf16 v[30:33], v[38:41], v[174:177], v[30:33]
	v_mfma_f32_16x16x32_bf16 v[26:29], v[46:49], v[174:177], v[26:29]
	v_mfma_f32_16x16x32_bf16 v[14:17], v[38:41], v[182:185], v[14:17]
	v_mfma_f32_16x16x32_bf16 v[10:13], v[46:49], v[182:185], v[10:13]
	s_setprio 0
	s_barrier
	s_add_u32 s4, s46, 0x40000
	s_addc_u32 s5, s47, 0
	s_add_i32 s67, s68, s52
	v_lshl_add_u64 v[34:35], s[4:5], 0, v[164:165]
	s_mov_b32 m0, s67
	s_nop 0
	global_load_lds_dwordx4 v[34:35], off
	v_lshl_add_u64 v[34:35], s[4:5], 0, v[162:163]
	s_add_i32 m0, s67, 0x2000
	s_nop 0
	global_load_lds_dwordx4 v[34:35], off
	s_waitcnt vmcnt(6)
	s_barrier
	s_setprio 1
	v_mfma_f32_16x16x32_bf16 v[22:25], v[186:189], v[170:173], v[22:25]
	v_mfma_f32_16x16x32_bf16 v[18:21], v[222:225], v[170:173], v[18:21]
	v_mfma_f32_16x16x32_bf16 v[6:9], v[186:189], v[178:181], v[6:9]
	v_mfma_f32_16x16x32_bf16 v[2:5], v[222:225], v[178:181], v[2:5]
	v_mfma_f32_16x16x32_bf16 v[34:37], v[186:189], v[118:121], v[86:89]
	v_mfma_f32_16x16x32_bf16 v[38:41], v[222:225], v[118:121], v[82:85]
	v_mfma_f32_16x16x32_bf16 v[42:45], v[186:189], v[134:137], v[70:73]
	v_mfma_f32_16x16x32_bf16 v[46:49], v[222:225], v[134:137], v[54:57]
	v_mfma_f32_16x16x32_bf16 v[22:25], v[208:211], v[174:177], v[22:25]
	v_mfma_f32_16x16x32_bf16 v[18:21], v[226:229], v[174:177], v[18:21]
	v_mfma_f32_16x16x32_bf16 v[6:9], v[208:211], v[182:185], v[6:9]
	v_mfma_f32_16x16x32_bf16 v[2:5], v[226:229], v[182:185], v[2:5]
	v_mfma_f32_16x16x32_bf16 v[34:37], v[208:211], v[130:133], v[34:37]
	v_mfma_f32_16x16x32_bf16 v[38:41], v[226:229], v[130:133], v[38:41]
	v_mfma_f32_16x16x32_bf16 v[42:45], v[208:211], v[146:149], v[42:45]
	v_mfma_f32_16x16x32_bf16 v[46:49], v[226:229], v[146:149], v[46:49]
	s_setprio 0
	s_add_i32 s67, 0, 0x18000
	v_add_u32_e32 v1, s67, v191
	s_barrier
	ds_read_b128 v[54:57], v1
	ds_read_b128 v[70:73], v1 offset:1024
	ds_read_b128 v[82:85], v1 offset:2048
	ds_read_b128 v[86:89], v1 offset:3072
	s_add_u32 s4, s48, 0x40000
	s_addc_u32 s5, s49, 0
	s_mov_b32 m0, s55
	v_lshl_add_u64 v[134:135], s[4:5], 0, v[164:165]
	ds_read_b128 v[118:121], v206 offset:32768
	ds_read_b128 v[130:133], v206 offset:33792
	ds_read_b128 v[170:173], v206 offset:34816
	ds_read_b128 v[174:177], v206 offset:35840
	ds_read_b128 v[178:181], v206 offset:36864
	ds_read_b128 v[182:185], v206 offset:37888
	ds_read_b128 v[186:189], v206 offset:38912
	ds_read_b128 v[208:211], v206 offset:39936
	global_load_lds_dwordx4 v[134:135], off
	v_lshl_add_u64 v[134:135], s[4:5], 0, v[162:163]
	s_mov_b32 m0, s56
	s_nop 0
	global_load_lds_dwordx4 v[134:135], off
	s_waitcnt lgkmcnt(8)
	s_barrier
	s_waitcnt lgkmcnt(0)
	s_setprio 1
	s_waitcnt lgkmcnt(0)
	v_mfma_f32_16x16x32_bf16 v[134:137], v[54:57], v[118:121], v[158:161]
	v_mfma_f32_16x16x32_bf16 v[158:161], v[70:73], v[130:133], v[134:137]
	v_mfma_f32_16x16x32_bf16 v[134:137], v[82:85], v[118:121], v[154:157]
	v_mfma_f32_16x16x32_bf16 v[154:157], v[86:89], v[130:133], v[134:137]
	v_mfma_f32_16x16x32_bf16 v[134:137], v[54:57], v[170:173], v[142:145]
	v_mfma_f32_16x16x32_bf16 v[142:145], v[70:73], v[174:177], v[134:137]
	v_mfma_f32_16x16x32_bf16 v[134:137], v[82:85], v[170:173], v[138:141]
	v_mfma_f32_16x16x32_bf16 v[126:129], v[54:57], v[178:181], v[126:129]
	v_mfma_f32_16x16x32_bf16 v[122:125], v[82:85], v[178:181], v[122:125]
	v_mfma_f32_16x16x32_bf16 v[110:113], v[54:57], v[186:189], v[110:113]
	v_mfma_f32_16x16x32_bf16 v[106:109], v[82:85], v[186:189], v[106:109]
	v_mfma_f32_16x16x32_bf16 v[138:141], v[86:89], v[174:177], v[134:137]
	v_mfma_f32_16x16x32_bf16 v[126:129], v[70:73], v[182:185], v[126:129]
	v_mfma_f32_16x16x32_bf16 v[122:125], v[86:89], v[182:185], v[122:125]
	v_mfma_f32_16x16x32_bf16 v[110:113], v[70:73], v[208:211], v[110:113]
	v_mfma_f32_16x16x32_bf16 v[106:109], v[86:89], v[208:211], v[106:109]
	s_setprio 0
	s_barrier
	s_add_i32 s48, 0, 0x1c000
	s_add_i32 s4, s67, s52
	v_add_u32_e32 v1, s48, v191
	v_lshl_add_u64 v[134:135], v[214:215], 0, s[22:23]
	s_mov_b32 m0, s4
	ds_read_b128 v[222:225], v1
	ds_read_b128 v[226:229], v1 offset:1024
	ds_read_b128 v[230:233], v1 offset:2048
	ds_read_b128 v[234:237], v1 offset:3072
	global_load_lds_dwordx4 v[134:135], off
	v_lshl_add_u64 v[134:135], v[238:239], 0, s[22:23]
	s_add_i32 m0, s4, 0x2000
	s_nop 0
	global_load_lds_dwordx4 v[134:135], off
	s_barrier
	s_waitcnt lgkmcnt(0)
	s_setprio 1
	s_waitcnt lgkmcnt(0)
	v_mfma_f32_16x16x32_bf16 v[50:53], v[230:233], v[118:121], v[50:53]
	v_mfma_f32_16x16x32_bf16 v[134:137], v[222:225], v[118:121], v[150:153]
	v_mfma_f32_16x16x32_bf16 v[146:149], v[234:237], v[130:133], v[50:53]
	v_mfma_f32_16x16x32_bf16 v[50:53], v[222:225], v[170:173], v[58:61]
	v_mfma_f32_16x16x32_bf16 v[150:153], v[226:229], v[130:133], v[134:137]
	v_mfma_f32_16x16x32_bf16 v[134:137], v[226:229], v[174:177], v[50:53]
	v_mfma_f32_16x16x32_bf16 v[50:53], v[230:233], v[170:173], v[62:65]
	v_mfma_f32_16x16x32_bf16 v[130:133], v[234:237], v[174:177], v[50:53]
	v_mfma_f32_16x16x32_bf16 v[50:53], v[222:225], v[178:181], v[66:69]
	v_mfma_f32_16x16x32_bf16 v[118:121], v[226:229], v[182:185], v[50:53]
	v_mfma_f32_16x16x32_bf16 v[50:53], v[230:233], v[178:181], v[114:117]
	v_mfma_f32_16x16x32_bf16 v[114:117], v[234:237], v[182:185], v[50:53]
	v_mfma_f32_16x16x32_bf16 v[50:53], v[222:225], v[186:189], v[102:105]
	v_mfma_f32_16x16x32_bf16 v[102:105], v[226:229], v[208:211], v[50:53]
	v_mfma_f32_16x16x32_bf16 v[50:53], v[230:233], v[186:189], v[98:101]
	v_mfma_f32_16x16x32_bf16 v[98:101], v[234:237], v[208:211], v[50:53]
	s_setprio 0
	s_mov_b32 m0, s58
	v_lshl_add_u64 v[186:187], v[240:241], 0, s[22:23]
	s_barrier
	s_nop 2
	ds_read_b128 v[50:53], v206 offset:49152
	ds_read_b128 v[58:61], v206 offset:50176
	ds_read_b128 v[62:65], v206 offset:51200
	ds_read_b128 v[66:69], v206 offset:52224
	ds_read_b128 v[170:173], v206 offset:53248
	ds_read_b128 v[174:177], v206 offset:54272
	ds_read_b128 v[178:181], v206 offset:55296
	ds_read_b128 v[182:185], v206 offset:56320
	global_load_lds_dwordx4 v[186:187], off
	v_lshl_add_u64 v[186:187], v[242:243], 0, s[22:23]
	s_mov_b32 m0, s59
	s_nop 0
	global_load_lds_dwordx4 v[186:187], off
	s_barrier
	s_waitcnt lgkmcnt(0)
	s_setprio 1
	s_waitcnt lgkmcnt(0)
	v_mfma_f32_16x16x32_bf16 v[94:97], v[54:57], v[50:53], v[94:97]
	v_mfma_f32_16x16x32_bf16 v[90:93], v[82:85], v[50:53], v[90:93]
	v_mfma_f32_16x16x32_bf16 v[78:81], v[54:57], v[62:65], v[78:81]
	v_mfma_f32_16x16x32_bf16 v[74:77], v[82:85], v[62:65], v[74:77]
	v_mfma_f32_16x16x32_bf16 v[30:33], v[54:57], v[170:173], v[30:33]
	v_mfma_f32_16x16x32_bf16 v[26:29], v[82:85], v[170:173], v[26:29]
	v_mfma_f32_16x16x32_bf16 v[14:17], v[54:57], v[178:181], v[14:17]
	v_mfma_f32_16x16x32_bf16 v[10:13], v[82:85], v[178:181], v[10:13]
	v_mfma_f32_16x16x32_bf16 v[94:97], v[70:73], v[58:61], v[94:97]
	v_mfma_f32_16x16x32_bf16 v[90:93], v[86:89], v[58:61], v[90:93]
	v_mfma_f32_16x16x32_bf16 v[78:81], v[70:73], v[66:69], v[78:81]
	v_mfma_f32_16x16x32_bf16 v[74:77], v[86:89], v[66:69], v[74:77]
	v_mfma_f32_16x16x32_bf16 v[30:33], v[70:73], v[174:177], v[30:33]
	v_mfma_f32_16x16x32_bf16 v[26:29], v[86:89], v[174:177], v[26:29]
	v_mfma_f32_16x16x32_bf16 v[14:17], v[70:73], v[182:185], v[14:17]
	v_mfma_f32_16x16x32_bf16 v[10:13], v[86:89], v[182:185], v[10:13]
	s_setprio 0
	s_barrier
	s_add_u32 s4, s46, 0x40080
	s_addc_u32 s5, s47, 0
	s_add_i32 s46, s48, s52
	v_lshl_add_u64 v[54:55], s[4:5], 0, v[164:165]
	s_mov_b32 m0, s46
	s_nop 0
	global_load_lds_dwordx4 v[54:55], off
	v_lshl_add_u64 v[54:55], s[4:5], 0, v[162:163]
	s_add_i32 m0, s46, 0x2000
	s_nop 0
	global_load_lds_dwordx4 v[54:55], off
	s_waitcnt vmcnt(6)
	s_barrier
	s_setprio 1
	v_mfma_f32_16x16x32_bf16 v[34:37], v[222:225], v[50:53], v[34:37]
	v_mfma_f32_16x16x32_bf16 v[86:89], v[226:229], v[58:61], v[34:37]
	v_mfma_f32_16x16x32_bf16 v[34:37], v[230:233], v[50:53], v[38:41]
	v_mfma_f32_16x16x32_bf16 v[82:85], v[234:237], v[58:61], v[34:37]
	v_mfma_f32_16x16x32_bf16 v[34:37], v[222:225], v[62:65], v[42:45]
	v_mfma_f32_16x16x32_bf16 v[70:73], v[226:229], v[66:69], v[34:37]
	v_mfma_f32_16x16x32_bf16 v[34:37], v[230:233], v[62:65], v[46:49]
	v_mfma_f32_16x16x32_bf16 v[22:25], v[222:225], v[170:173], v[22:25]
	v_mfma_f32_16x16x32_bf16 v[18:21], v[230:233], v[170:173], v[18:21]
	v_mfma_f32_16x16x32_bf16 v[6:9], v[222:225], v[178:181], v[6:9]
	v_mfma_f32_16x16x32_bf16 v[2:5], v[230:233], v[178:181], v[2:5]
	v_mfma_f32_16x16x32_bf16 v[54:57], v[234:237], v[66:69], v[34:37]
	v_mfma_f32_16x16x32_bf16 v[22:25], v[226:229], v[174:177], v[22:25]
	v_mfma_f32_16x16x32_bf16 v[18:21], v[234:237], v[174:177], v[18:21]
	v_mfma_f32_16x16x32_bf16 v[6:9], v[226:229], v[182:185], v[6:9]
	v_mfma_f32_16x16x32_bf16 v[2:5], v[234:237], v[182:185], v[2:5]
	s_setprio 0
	s_add_i32 s66, s66, 2
	s_add_u32 s64, s64, 0x100
	s_addc_u32 s65, s65, 0
	s_cmp_gt_u32 s66, 13
	s_mov_b64 s[4:5], s[36:37]
	s_cbranch_scc0 .Lrot_3
	s_barrier
	v_lshl_or_b32 v208, s3, 8, v192
	v_mov_b32_e32 v1, v190
	v_ashrrev_i32_e32 v209, 31, v208
	v_lshlrev_b64 v[34:35], 2, v[208:209]
	v_lshl_add_u64 v[36:37], s[8:9], 0, v[34:35]
	flat_load_dwordx4 v[62:65], v[36:37]
	flat_load_dwordx4 v[50:53], v[36:37] offset:16
	v_lshl_add_u64 v[34:35], s[10:11], 0, v[34:35]
	flat_load_dwordx4 v[66:69], v[34:35]
	flat_load_dwordx4 v[42:45], v[34:35] offset:16
	flat_load_dwordx4 v[58:61], v[36:37] offset:512
	flat_load_dwordx4 v[38:41], v[36:37] offset:528
	flat_load_dwordx4 v[46:49], v[34:35] offset:512
	s_nop 0
	flat_load_dwordx4 v[34:37], v[34:35] offset:528
	s_lshl_b32 s37, s27, 8
	v_lshl_add_u32 v170, v1, 3, 0
	v_add_u32_e32 v170, 0x20040, v170
	s_waitcnt vmcnt(0)
	ds_read_b64 v[188:189], v170
	s_mov_b32 s4, 0xbf3a00e3
	s_cmp_gt_i32 s3, 3
	v_mov_b64_e32 v[176:177], s[4:5]
	s_cselect_b64 s[4:5], -1, 0
	s_and_b64 s[46:47], s[40:41], s[4:5]
	s_mov_b32 s4, 0x3f07dc22
	s_mov_b32 s38, 0x3f35f0e3
	s_mov_b32 s48, 0xbe11a98e
	s_mov_b32 s62, 0x3e027906
	s_lshl_b32 s3, s3, 2
	s_and_b32 s36, s3, 12
	s_mov_b32 s3, 0x1020000
	v_add_u32_e32 v170, s37, v1
	v_lshlrev_b32_e32 v1, 10, v170
	s_waitcnt lgkmcnt(0)
	v_xor_b32_e32 v65, 0x80000000, v65
	v_xor_b32_e32 v64, 0x80000000, v64
	v_pk_fma_f32 v[158:159], v[62:63], v[188:189], v[158:159] op_sel_hi:[1,0,1] neg_lo:[1,0,0] neg_hi:[1,0,0]
	v_xor_b32_e32 v53, 0x80000000, v53
	v_xor_b32_e32 v52, 0x80000000, v52
	v_pk_fma_f32 v[154:155], v[50:51], v[188:189], v[154:155] op_sel_hi:[1,0,1] neg_lo:[1,0,0] neg_hi:[1,0,0]
	v_pk_fma_f32 v[160:161], v[64:65], v[188:189], v[160:161] op_sel_hi:[1,0,1]
	v_pk_fma_f32 v[158:159], v[188:189], v[158:159], v[66:67] op_sel:[1,0,0]
	v_pk_fma_f32 v[172:173], v[52:53], v[188:189], v[156:157] op_sel_hi:[1,0,1]
	v_pk_fma_f32 v[156:157], v[188:189], v[154:155], v[42:43] op_sel:[1,0,0]
	v_pk_fma_f32 v[154:155], v[188:189], v[160:161], v[68:69] op_sel:[1,0,0]
	v_fma_f32 v175, |v159|, s1, 1.0
	v_fma_f32 v171, |v158|, s1, 1.0
	v_pk_fma_f32 v[160:161], v[188:189], v[172:173], v[44:45] op_sel:[1,0,0]
	v_fma_f32 v172, |v156|, s1, 1.0
	v_rcp_f32_e32 v175, v175
	v_fma_f32 v187, |v155|, s1, 1.0
	v_mul_f32_e32 v174, v158, v158
	v_rcp_f32_e32 v182, v171
	v_rcp_f32_e32 v183, v172
	v_rcp_f32_e32 v215, v187
	v_mul_f32_e32 v173, v156, v156
	v_fma_f32 v179, |v157|, s1, 1.0
	v_mul_f32_e32 v180, v157, v157
	v_mul_f32_e32 v171, 0xbf38aa3b, v174
	v_mul_f32_e32 v186, v154, v154
	v_fma_f32 v181, |v154|, s1, 1.0
	v_mul_f32_e32 v172, 0xbf38aa3b, v173
	v_rcp_f32_e32 v185, v179
	v_mul_f32_e32 v173, 0xbf38aa3b, v180
	v_fma_f32 v179, |v160|, s1, 1.0
	v_mul_f32_e32 v209, v160, v160
	v_exp_f32_e32 v180, v171
	v_mul_f32_e32 v171, 0xbf38aa3b, v186
	v_fma_f32 v211, |v161|, s1, 1.0
	v_rcp_f32_e32 v184, v181
	v_exp_f32_e32 v181, v172
	v_rcp_f32_e32 v210, v179
	v_mul_f32_e32 v179, 0xbf38aa3b, v209
	v_exp_f32_e32 v172, v171
	v_fmamk_f32 v171, v175, 0x3f07dc22, v218
	v_rcp_f32_e32 v211, v211
	v_exp_f32_e32 v214, v179
	v_pk_fma_f32 v[186:187], v[182:183], s[4:5], v[176:177] op_sel_hi:[1,0,0]
	v_fmaak_f32 v171, v175, v171, 0x3f35f0e3
	v_fmamk_f32 v179, v215, 0x3f07dc22, v218
	v_pk_fma_f32 v[186:187], v[182:183], v[186:187], s[38:39] op_sel_hi:[1,1,0]
	v_fmaak_f32 v171, v175, v171, 0xbe11a98e
	v_fmaak_f32 v179, v215, v179, 0x3f35f0e3
	v_pk_fma_f32 v[186:187], v[182:183], v[186:187], s[48:49] op_sel_hi:[1,1,0]
	v_fmaak_f32 v171, v175, v171, 0x3e027906
	v_fmaak_f32 v179, v215, v179, 0xbe11a98e
	v_mul_f32_e32 v212, v161, v161
	v_pk_fma_f32 v[224:225], v[182:183], v[186:187], s[62:63] op_sel_hi:[1,1,0]
	v_mul_f32_e32 v186, v175, v171
	v_fmaak_f32 v171, v215, v179, 0x3e027906
	v_pk_fma_f32 v[222:223], v[184:185], s[4:5], v[176:177] op_sel_hi:[1,0,0]
	v_pk_mul_f32 v[224:225], v[182:183], v[224:225]
	v_mul_f32_e32 v182, v215, v171
	v_mul_f32_e32 v171, 0xbf38aa3b, v212
	v_pk_fma_f32 v[176:177], v[210:211], s[4:5], v[176:177] op_sel_hi:[1,0,0]
	v_exp_f32_e32 v215, v171
	v_pk_fma_f32 v[176:177], v[210:211], v[176:177], s[38:39] op_sel_hi:[1,1,0]
	v_cmp_gt_f32_e32 vcc, 0, v161
	v_pk_fma_f32 v[176:177], v[210:211], v[176:177], s[48:49] op_sel_hi:[1,1,0]
	v_pk_fma_f32 v[150:151], v[58:59], v[188:189], v[150:151] op_sel_hi:[1,0,1] neg_lo:[1,0,0] neg_hi:[1,0,0]
	v_pk_fma_f32 v[176:177], v[210:211], v[176:177], s[62:63] op_sel_hi:[1,1,0]
	v_pk_fma_f32 v[150:151], v[188:189], v[150:151], v[46:47] op_sel:[1,0,0]
	v_pk_mul_f32 v[176:177], v[210:211], v[176:177]
	v_fma_f32 v175, |v150|, s1, 1.0
	v_pk_mul_f32 v[176:177], v[214:215], v[176:177]
	v_rcp_f32_e32 v175, v175
	v_pk_mul_f32 v[210:211], v[160:161], v[176:177]
	v_pk_fma_f32 v[176:177], v[160:161], v[176:177], v[160:161] neg_lo:[1,0,0] neg_hi:[1,0,0]
	v_mul_f32_e32 v178, v159, v159
	v_cndmask_b32_e32 v177, v177, v211, vcc
	v_cmp_gt_f32_e32 vcc, 0, v160
	v_xor_b32_e32 v61, 0x80000000, v61
	v_xor_b32_e32 v60, 0x80000000, v60
	v_cndmask_b32_e32 v176, v176, v210, vcc
	v_mul_f32_e32 v160, v176, v176
	v_pk_fma_f32 v[160:161], v[176:177], v[176:177], v[160:161] op_sel_hi:[1,1,0]
	v_mul_f32_e32 v174, 0xbf38aa3b, v178
	v_lshrrev_b32_e32 v160, 10, v208
	v_mul_f32_e32 v207, v155, v155
	v_mul_lo_u32 v160, v160, s3
	s_movk_i32 s4, 0x3ff
	v_pk_fma_f32 v[152:153], v[60:61], v[188:189], v[152:153] op_sel_hi:[1,0,1]
	v_exp_f32_e32 v178, v174
	v_mul_f32_e32 v174, 0xbf38aa3b, v207
	v_and_or_b32 v207, v208, s4, v160
	v_add_u32_e32 v171, 0x80, v208
	v_pk_fma_f32 v[208:209], v[188:189], v[152:153], v[48:49] op_sel:[1,0,0]
	v_fmamk_f32 v152, v175, 0x3f07dc22, v218
	v_fmaak_f32 v152, v175, v152, 0x3f35f0e3
	v_mul_f32_e32 v153, v150, v150
	v_mul_f32_e32 v153, 0xbf38aa3b, v153
	v_fmaak_f32 v152, v175, v152, 0xbe11a98e
	v_exp_f32_e32 v153, v153
	v_fmaak_f32 v152, v175, v152, 0x3e027906
	v_mul_f32_e32 v152, v175, v152
	v_fma_f32 v175, |v151|, s1, 1.0
	v_rcp_f32_e32 v175, v175
	v_mul_f32_e32 v152, v153, v152
	v_mul_f32_e32 v153, v150, v152
	v_fma_f32 v152, -v150, v152, v150
	v_cmp_gt_f32_e32 vcc, 0, v150
	v_pk_fma_f32 v[146:147], v[38:39], v[188:189], v[146:147] op_sel_hi:[1,0,1] neg_lo:[1,0,0] neg_hi:[1,0,0]
	v_xor_b32_e32 v41, 0x80000000, v41
	v_cndmask_b32_e32 v150, v152, v153, vcc
	v_fmamk_f32 v152, v175, 0x3f07dc22, v218
	v_fmaak_f32 v152, v175, v152, 0x3f35f0e3
	v_mul_f32_e32 v153, v151, v151
	v_fmaak_f32 v152, v175, v152, 0xbe11a98e
	v_mul_f32_e32 v153, 0xbf38aa3b, v153
	v_fmaak_f32 v152, v175, v152, 0x3e027906
	v_exp_f32_e32 v153, v153
	v_mul_f32_e32 v152, v175, v152
	v_fma_f32 v175, |v208|, s1, 1.0
	v_rcp_f32_e32 v175, v175
	v_mul_f32_e32 v152, v153, v152
	v_mul_f32_e32 v153, v151, v152
	v_fma_f32 v152, -v151, v152, v151
	v_cmp_gt_f32_e32 vcc, 0, v151
	v_fmamk_f32 v151, v175, 0x3f07dc22, v218
	v_fmaak_f32 v151, v175, v151, 0x3f35f0e3
	v_cndmask_b32_e32 v152, v152, v153, vcc
	v_mul_f32_e32 v153, v208, v208
	v_mul_f32_e32 v153, 0xbf38aa3b, v153
	v_fmaak_f32 v151, v175, v151, 0xbe11a98e
	v_exp_f32_e32 v153, v153
	v_fmaak_f32 v151, v175, v151, 0x3e027906
	v_mul_f32_e32 v151, v175, v151
	v_fma_f32 v175, |v209|, s1, 1.0
	v_rcp_f32_e32 v175, v175
	v_mul_f32_e32 v151, v153, v151
	v_mul_f32_e32 v153, v208, v151
	v_fma_f32 v151, -v208, v151, v208
	v_cmp_gt_f32_e32 vcc, 0, v208
	v_pk_fma_f32 v[146:147], v[188:189], v[146:147], v[34:35] op_sel:[1,0,0]
	v_xor_b32_e32 v40, 0x80000000, v40
	v_cndmask_b32_e32 v208, v151, v153, vcc
	v_fmamk_f32 v151, v175, 0x3f07dc22, v218
	v_fmaak_f32 v151, v175, v151, 0x3f35f0e3
	v_fmaak_f32 v151, v175, v151, 0xbe11a98e
	v_fmaak_f32 v151, v175, v151, 0x3e027906
	v_mul_f32_e32 v151, v175, v151
	v_fma_f32 v175, |v146|, s1, 1.0
	v_rcp_f32_e32 v175, v175
	v_mul_f32_e32 v183, v146, v146
	v_mul_f32_e32 v153, v209, v209
	v_mul_f32_e32 v183, 0xbf38aa3b, v183
	v_fmamk_f32 v179, v175, 0x3f07dc22, v218
	v_mul_f32_e32 v153, 0xbf38aa3b, v153
	v_fmaak_f32 v179, v175, v179, 0x3f35f0e3
	v_exp_f32_e32 v183, v183
	v_exp_f32_e32 v153, v153
	v_fmaak_f32 v179, v175, v179, 0xbe11a98e
	v_fmaak_f32 v179, v175, v179, 0x3e027906
	v_mul_f32_e32 v175, v175, v179
	v_mul_f32_e32 v175, v183, v175
	v_fma_f32 v183, |v147|, s1, 1.0
	v_mul_f32_e32 v151, v153, v151
	v_rcp_f32_e32 v183, v183
	v_mul_f32_e32 v153, v209, v151
	v_fma_f32 v151, -v209, v151, v209
	v_cmp_gt_f32_e32 vcc, 0, v209
	v_mul_f32_e32 v179, v146, v175
	v_fma_f32 v175, -v146, v175, v146
	v_cndmask_b32_e32 v210, v151, v153, vcc
	v_cmp_gt_f32_e32 vcc, 0, v146
	v_pk_fma_f32 v[148:149], v[40:41], v[188:189], v[148:149] op_sel_hi:[1,0,1]
	v_fmamk_f32 v146, v183, 0x3f07dc22, v218
	v_cndmask_b32_e32 v214, v175, v179, vcc
	v_mul_f32_e32 v175, v147, v147
	v_mul_f32_e32 v175, 0xbf38aa3b, v175
	v_pk_fma_f32 v[148:149], v[188:189], v[148:149], v[36:37] op_sel:[1,0,0]
	v_fmaak_f32 v146, v183, v146, 0x3f35f0e3
	v_exp_f32_e32 v175, v175
	v_fmaak_f32 v146, v183, v146, 0xbe11a98e
	v_fma_f32 v179, |v148|, s1, 1.0
	v_fmaak_f32 v146, v183, v146, 0x3e027906
	v_rcp_f32_e32 v179, v179
	v_pk_fma_f32 v[222:223], v[184:185], v[222:223], s[38:39] op_sel_hi:[1,1,0]
	v_mul_f32_e32 v146, v183, v146
	v_pk_fma_f32 v[222:223], v[184:185], v[222:223], s[48:49] op_sel_hi:[1,1,0]
	v_mul_f32_e32 v146, v175, v146
	v_pk_fma_f32 v[222:223], v[184:185], v[222:223], s[62:63] op_sel_hi:[1,1,0]
	v_mul_f32_e32 v175, v147, v146
	v_fma_f32 v146, -v147, v146, v147
	v_cmp_gt_f32_e32 vcc, 0, v147
	v_mul_f32_e32 v147, v148, v148
	v_pk_mul_f32 v[184:185], v[184:185], v[222:223]
	v_cndmask_b32_e32 v222, v146, v175, vcc
	v_fmamk_f32 v146, v179, 0x3f07dc22, v218
	v_mul_f32_e32 v147, 0xbf38aa3b, v147
	v_fmaak_f32 v146, v179, v146, 0x3f35f0e3
	v_exp_f32_e32 v147, v147
	v_fmaak_f32 v146, v179, v146, 0xbe11a98e
	v_fmaak_f32 v146, v179, v146, 0x3e027906
	v_fma_f32 v175, |v149|, s1, 1.0
	v_mul_f32_e32 v146, v179, v146
	v_rcp_f32_e32 v175, v175
	v_mul_f32_e32 v146, v147, v146
	v_mul_f32_e32 v147, v148, v146
	v_fma_f32 v146, -v148, v146, v148
	v_cmp_gt_f32_e32 vcc, 0, v148
	v_exp_f32_e32 v173, v173
	v_exp_f32_e32 v174, v174
	v_cndmask_b32_e32 v226, v146, v147, vcc
	v_mul_f32_e32 v147, v149, v149
	v_fmamk_f32 v146, v175, 0x3f07dc22, v218
	v_mul_f32_e32 v147, 0xbf38aa3b, v147
	v_fmaak_f32 v146, v175, v146, 0x3f35f0e3
	v_exp_f32_e32 v147, v147
	v_fmaak_f32 v146, v175, v146, 0xbe11a98e
	v_fmaak_f32 v146, v175, v146, 0x3e027906
	v_mul_f32_e32 v146, v175, v146
	v_mul_f32_e32 v146, v147, v146
	v_mul_f32_e32 v147, v149, v146
	v_fma_f32 v146, -v149, v146, v149
	v_cmp_gt_f32_e32 vcc, 0, v149
	v_mov_b32_e32 v179, v181
	v_mov_b32_e32 v187, v225
	v_cndmask_b32_e32 v228, v146, v147, vcc
	v_lshrrev_b32_e32 v146, 10, v171
	v_mul_lo_u32 v146, v146, s3
	v_and_or_b32 v188, v171, s4, v146
	v_pk_mul_f32 v[146:147], v[180:181], v[224:225]
	v_pk_mul_f32 v[148:149], v[178:179], v[186:187]
	v_mov_b32_e32 v178, v158
	v_mov_b32_e32 v179, v156
	v_pk_mov_b32 v[186:187], v[158:159], v[156:157] op_sel:[1,0]
	v_pk_mul_f32 v[180:181], v[178:179], v[146:147]
	v_pk_mul_f32 v[224:225], v[186:187], v[148:149]
	v_pk_fma_f32 v[146:147], v[178:179], v[146:147], v[178:179] neg_lo:[1,0,0] neg_hi:[1,0,0]
	v_pk_fma_f32 v[148:149], v[186:187], v[148:149], v[186:187] neg_lo:[1,0,0] neg_hi:[1,0,0]
	v_cmp_gt_f32_e32 vcc, 0, v156
	v_cmp_gt_f32_e64 s[4:5], 0, v158
	v_mov_b32_e32 v175, v173
	v_cndmask_b32_e32 v179, v147, v181, vcc
	v_cndmask_b32_e32 v181, v149, v225, vcc
	v_cmp_gt_f32_e32 vcc, 0, v159
	v_mov_b32_e32 v183, v185
	v_cndmask_b32_e64 v178, v146, v180, s[4:5]
	v_cndmask_b32_e32 v180, v148, v224, vcc
	v_pk_mul_f32 v[148:149], v[172:173], v[184:185]
	v_pk_mul_f32 v[158:159], v[174:175], v[182:183]
	v_mov_b32_e32 v156, v154
	v_mov_b32_e32 v174, v155
	v_mov_b32_e32 v175, v157
	v_pk_mul_f32 v[172:173], v[156:157], v[148:149]
	v_pk_mul_f32 v[182:183], v[174:175], v[158:159]
	v_pk_fma_f32 v[148:149], v[156:157], v[148:149], v[156:157] neg_lo:[1,0,0] neg_hi:[1,0,0]
	v_pk_fma_f32 v[158:159], v[174:175], v[158:159], v[174:175] neg_lo:[1,0,0] neg_hi:[1,0,0]
	v_cmp_gt_f32_e32 vcc, 0, v157
	v_cmp_gt_f32_e64 s[4:5], 0, v154
	v_add_lshl_u32 v160, v1, v207, 1
	v_cndmask_b32_e32 v157, v149, v173, vcc
	v_cndmask_b32_e64 v156, v148, v172, s[4:5]
	v_cndmask_b32_e32 v159, v159, v183, vcc
	v_cmp_gt_f32_e32 vcc, 0, v155
	v_pk_mul_f32 v[174:175], v[156:157], v[156:157]
	v_mul_f32_e32 v151, v150, v150
	v_cndmask_b32_e32 v158, v158, v182, vcc
	v_mul_f32_e32 v153, v152, v152
	v_mul_f32_e32 v209, v208, v208
	v_mul_f32_e32 v211, v210, v210
	v_mul_f32_e32 v215, v214, v214
	v_mul_f32_e32 v223, v222, v222
	v_mul_f32_e32 v227, v226, v226
	v_mul_f32_e32 v229, v228, v228
	v_add_lshl_u32 v171, v1, v188, 1
	v_cvt_pk_bf16_f32 v146, v178, v180
	v_cvt_pk_bf16_f32 v147, v156, v158
	v_pk_mul_f32 v[154:155], v[178:179], v[178:179]
	v_pk_mul_f32 v[172:173], v[180:181], v[180:181]
	v_pk_mul_f32 v[182:183], v[158:159], v[158:159]
	v_pk_mov_b32 v[154:155], v[178:179], v[154:155] op_sel:[1,0]
	v_pk_mov_b32 v[172:173], v[156:157], v[172:173] op_sel:[1,0]
	v_cvt_pk_bf16_f32 v148, v179, v157
	v_mov_b32_e32 v1, v161
	v_pk_add_f32 v[154:155], v[154:155], v[172:173]
	v_mov_b32_e32 v172, v176
	v_mov_b32_e32 v173, v174
	v_pk_mov_b32 v[174:175], v[176:177], v[182:183] op_sel:[1,0]
	v_cvt_pk_bf16_f32 v149, v176, v177
	buffer_store_dwordx4 v[146:149], v160, s[28:31], 0 offen sc1
	v_pk_add_f32 v[172:173], v[172:173], v[174:175]
	v_pk_mul_f32 v[174:175], v[178:179], v[180:181]
	v_pk_add_f32 v[154:155], v[154:155], v[172:173]
	v_pk_add_f32 v[172:173], v[178:179], v[180:181]
	s_nop 0
	v_mov_b32_e32 v173, v175
	v_pk_add_f32 v[174:175], v[156:157], v[158:159]
	v_pk_mul_f32 v[156:157], v[156:157], v[158:159]
	s_nop 0
	v_mov_b32_e32 v175, v157
	v_pk_add_f32 v[156:157], v[172:173], v[174:175]
	s_nop 0
	v_pk_add_f32 v[156:157], v[156:157], v[0:1]
	s_nop 0
	v_pk_add_f32 v[154:155], v[154:155], v[156:157]
	v_cvt_pk_bf16_f32 v146, v150, v152
	v_pk_add_f32 v[148:149], v[150:151], v[152:153]
	v_pk_add_f32 v[150:151], v[208:209], v[210:211]
	v_cvt_pk_bf16_f32 v147, v208, v210
	s_nop 0
	v_pk_add_f32 v[148:149], v[148:149], v[150:151]
	s_nop 0
	v_pk_add_f32 v[150:151], v[148:149], v[154:155]
	v_pk_add_f32 v[152:153], v[214:215], v[222:223]
	v_pk_add_f32 v[154:155], v[226:227], v[228:229]
	v_cvt_pk_bf16_f32 v148, v214, v222
	v_cvt_pk_bf16_f32 v149, v226, v228
	buffer_store_dwordx4 v[146:149], v171, s[28:31], 0 offen sc1
	v_pk_add_f32 v[152:153], v[152:153], v[154:155]
	s_nop 0
	v_pk_add_f32 v[150:151], v[152:153], v[150:151]
	v_and_b32_e32 v146, 64, v216
	v_xor_b32_e32 v1, 16, v216
	v_add_u32_e32 v148, 64, v146
	v_cmp_lt_i32_e32 vcc, v1, v148
	s_nop 1
	v_cndmask_b32_e32 v1, v216, v1, vcc
	v_lshlrev_b32_e32 v174, 2, v1
	ds_bpermute_b32 v146, v174, v150
	ds_bpermute_b32 v147, v174, v151
	v_xor_b32_e32 v1, 32, v216
	v_cmp_lt_i32_e32 vcc, v1, v148
	s_waitcnt lgkmcnt(0)
	v_pk_add_f32 v[146:147], v[150:151], v[146:147]
	v_cndmask_b32_e32 v1, v216, v1, vcc
	v_lshlrev_b32_e32 v175, 2, v1
	ds_bpermute_b32 v148, v175, v146
	ds_bpermute_b32 v149, v175, v147
	s_and_saveexec_b64 s[4:5], s[46:47]
	s_cbranch_execz .LBB0_215
	v_ashrrev_i32_e32 v171, 31, v170
	v_lshlrev_b64 v[150:151], 7, v[170:171]
	v_lshl_add_u64 v[150:151], s[12:13], 0, v[150:151]
	s_lshl_b32 s38, s36, 3
	v_lshl_add_u64 v[150:151], v[150:151], 0, s[38:39]
	s_lshl_b32 s38, s57, 3
	v_lshl_add_u64 v[150:151], v[150:151], 0, s[38:39]
	s_waitcnt lgkmcnt(0)
	v_pk_add_f32 v[146:147], v[146:147], v[148:149]
	flat_store_dwordx2 v[150:151], v[146:147]

.LBB0_395:
	s_add_i32 s66, s66, 1
	s_mov_b64 s[36:37], s[20:21]
	s_mul_i32 s20, s66, s26
	s_add_i32 s42, s20, s2
	s_cmpk_gt_i32 s42, 0x3ff
	s_cselect_b64 s[52:53], -1, 0
	s_lshl_b32 s20, s42, 3
	s_and_b32 s20, s20, 56
	s_bfe_u32 s21, s42, 0x30003
	s_mov_b32 s3, s67
	s_or_b32 s67, s20, s21
	s_mov_b32 s27, s50
	s_ashr_i32 s50, s42, 6
	s_lshl_b32 s20, s67, 19
	s_mov_b64 s[4:5], s[48:49]
	s_add_u32 s48, s18, s20
	s_addc_u32 s49, s19, 0
	s_ashr_i32 s51, s50, 31
	s_lshl_b64 s[20:21], s[50:51], 19
	s_add_u32 s20, s16, s20
	s_addc_u32 s21, s17, s21
	s_cmpk_lt_i32 s42, 0x400
	s_cselect_b32 s46, s49, s5
	s_cselect_b32 s47, s48, s4
	s_cselect_b32 s51, s21, s37
	s_cselect_b32 s54, s20, s36
	s_add_u32 s55, s36, 0x100
	s_addc_u32 s56, s37, 0
	s_mov_b32 s57, -2
	s_add_u32 s36, s4, 0x100
	s_addc_u32 s37, s5, 0
	s_add_i32 s68, 0, 0x10000
	v_add_u32_e32 v30, s68, v204
	ds_read_b128 v[14:17], v30
	ds_read_b128 v[22:25], v30 offset:1024
	ds_read_b128 v[26:29], v30 offset:2048
	ds_read_b128 v[30:33], v30 offset:3072
	s_cmp_eq_u32 s57, 12
	s_cselect_b32 s45, s46, s37
	s_cselect_b32 s44, s47, s36
	s_cselect_b32 s43, s51, s56
	s_cselect_b32 s42, s54, s55
	v_lshl_add_u64 v[178:179], s[4:5], 0, v[188:189]
	s_add_i32 m0, s60, 0xc000
	ds_read_b128 v[38:41], v209
	ds_read_b128 v[42:45], v209 offset:1024
	ds_read_b128 v[46:49], v209 offset:2048
	ds_read_b128 v[54:57], v209 offset:3072
	ds_read_b128 v[58:61], v209 offset:4096
	ds_read_b128 v[62:65], v209 offset:5120
	ds_read_b128 v[66:69], v209 offset:6144
	ds_read_b128 v[70:73], v209 offset:7168
	global_load_lds_dwordx4 v[178:179], off
	v_lshl_add_u64 v[178:179], s[4:5], 0, v[186:187]
	s_add_i32 m0, s60, 0xe000
	s_nop 0
	global_load_lds_dwordx4 v[178:179], off
	s_waitcnt lgkmcnt(8)
	s_barrier
	s_waitcnt lgkmcnt(0)
	s_setprio 1
	s_waitcnt lgkmcnt(0)
	v_mfma_f32_16x16x32_bf16 v[174:177], v[14:17], v[38:41], 0
	v_mfma_f32_16x16x32_bf16 v[170:173], v[26:29], v[38:41], 0
	v_mfma_f32_16x16x32_bf16 v[158:161], v[14:17], v[46:49], 0
	v_mfma_f32_16x16x32_bf16 v[154:157], v[26:29], v[46:49], 0
	v_mfma_f32_16x16x32_bf16 v[142:145], v[14:17], v[58:61], 0
	v_mfma_f32_16x16x32_bf16 v[138:141], v[26:29], v[58:61], 0
	v_mfma_f32_16x16x32_bf16 v[126:129], v[14:17], v[66:69], 0
	v_mfma_f32_16x16x32_bf16 v[122:125], v[26:29], v[66:69], 0
	v_mfma_f32_16x16x32_bf16 v[174:177], v[22:25], v[42:45], v[174:177]
	v_mfma_f32_16x16x32_bf16 v[170:173], v[30:33], v[42:45], v[170:173]
	v_mfma_f32_16x16x32_bf16 v[158:161], v[22:25], v[54:57], v[158:161]
	v_mfma_f32_16x16x32_bf16 v[154:157], v[30:33], v[54:57], v[154:157]
	v_mfma_f32_16x16x32_bf16 v[142:145], v[22:25], v[62:65], v[142:145]
	v_mfma_f32_16x16x32_bf16 v[138:141], v[30:33], v[62:65], v[138:141]
	v_mfma_f32_16x16x32_bf16 v[126:129], v[22:25], v[70:73], v[126:129]
	v_mfma_f32_16x16x32_bf16 v[122:125], v[30:33], v[70:73], v[122:125]
	s_setprio 0
	s_barrier
	s_add_i32 s69, 0, 0x14000
	v_add_u32_e32 v210, s69, v204
	s_add_i32 s4, s68, s59
	ds_read_b128 v[178:181], v210
	ds_read_b128 v[190:193], v210 offset:1024
	ds_read_b128 v[200:203], v210 offset:2048
	ds_read_b128 v[222:225], v210 offset:3072
	v_lshl_add_u64 v[210:211], s[42:43], 0, v[184:185]
	s_mov_b32 m0, s4
	v_lshl_add_u64 v[214:215], s[42:43], 0, v[182:183]
	global_load_lds_dwordx4 v[210:211], off
	s_add_i32 m0, s4, 0x2000
	s_nop 0
	global_load_lds_dwordx4 v[214:215], off
	s_barrier
	s_waitcnt lgkmcnt(0)
	s_setprio 1
	s_waitcnt lgkmcnt(0)
	v_mfma_f32_16x16x32_bf16 v[166:169], v[178:181], v[38:41], 0
	v_mfma_f32_16x16x32_bf16 v[38:41], v[200:203], v[38:41], 0
	v_mfma_f32_16x16x32_bf16 v[166:169], v[190:193], v[42:45], v[166:169]
	v_mfma_f32_16x16x32_bf16 v[38:41], v[222:225], v[42:45], v[38:41]
	v_mfma_f32_16x16x32_bf16 v[42:45], v[178:181], v[46:49], 0
	v_mfma_f32_16x16x32_bf16 v[46:49], v[200:203], v[46:49], 0
	v_mfma_f32_16x16x32_bf16 v[42:45], v[190:193], v[54:57], v[42:45]
	v_mfma_f32_16x16x32_bf16 v[46:49], v[222:225], v[54:57], v[46:49]
	v_mfma_f32_16x16x32_bf16 v[54:57], v[178:181], v[58:61], 0
	v_mfma_f32_16x16x32_bf16 v[58:61], v[200:203], v[58:61], 0
	v_mfma_f32_16x16x32_bf16 v[54:57], v[190:193], v[62:65], v[54:57]
	v_mfma_f32_16x16x32_bf16 v[58:61], v[222:225], v[62:65], v[58:61]
	v_mfma_f32_16x16x32_bf16 v[62:65], v[178:181], v[66:69], 0
	v_mfma_f32_16x16x32_bf16 v[66:69], v[200:203], v[66:69], 0
	v_mfma_f32_16x16x32_bf16 v[62:65], v[190:193], v[70:73], v[62:65]
	v_mfma_f32_16x16x32_bf16 v[66:69], v[222:225], v[70:73], v[66:69]
	s_setprio 0
	s_mov_b32 m0, s60
	v_lshl_add_u64 v[242:243], s[44:45], 0, v[184:185]
	s_barrier
	ds_read_b128 v[70:73], v209 offset:16384
	ds_read_b128 v[114:117], v209 offset:17408
	ds_read_b128 v[118:121], v209 offset:18432
	ds_read_b128 v[130:133], v209 offset:19456
	ds_read_b128 v[134:137], v209 offset:20480
	ds_read_b128 v[146:149], v209 offset:21504
	ds_read_b128 v[150:153], v209 offset:22528
	ds_read_b128 v[162:165], v209 offset:23552
	global_load_lds_dwordx4 v[242:243], off
	v_lshl_add_u64 v[244:245], s[44:45], 0, v[182:183]
	s_mov_b32 m0, s61
	s_nop 0
	global_load_lds_dwordx4 v[244:245], off
	s_barrier
	s_waitcnt lgkmcnt(0)
	s_setprio 1
	s_waitcnt lgkmcnt(0)
	v_mfma_f32_16x16x32_bf16 v[110:113], v[14:17], v[70:73], 0
	v_mfma_f32_16x16x32_bf16 v[106:109], v[26:29], v[70:73], 0
	v_mfma_f32_16x16x32_bf16 v[94:97], v[14:17], v[118:121], 0
	v_mfma_f32_16x16x32_bf16 v[90:93], v[26:29], v[118:121], 0
	v_mfma_f32_16x16x32_bf16 v[78:81], v[14:17], v[134:137], 0
	v_mfma_f32_16x16x32_bf16 v[74:77], v[26:29], v[134:137], 0
	v_mfma_f32_16x16x32_bf16 v[10:13], v[26:29], v[150:153], 0
	v_mfma_f32_16x16x32_bf16 v[110:113], v[22:25], v[114:117], v[110:113]
	v_mfma_f32_16x16x32_bf16 v[106:109], v[30:33], v[114:117], v[106:109]
	v_mfma_f32_16x16x32_bf16 v[94:97], v[22:25], v[130:133], v[94:97]
	v_mfma_f32_16x16x32_bf16 v[90:93], v[30:33], v[130:133], v[90:93]
	v_mfma_f32_16x16x32_bf16 v[78:81], v[22:25], v[146:149], v[78:81]
	v_mfma_f32_16x16x32_bf16 v[74:77], v[30:33], v[146:149], v[74:77]
	v_mfma_f32_16x16x32_bf16 v[14:17], v[14:17], v[150:153], 0
	v_mfma_f32_16x16x32_bf16 v[10:13], v[30:33], v[162:165], v[10:13]
	v_mfma_f32_16x16x32_bf16 v[14:17], v[22:25], v[162:165], v[14:17]
	s_setprio 0
	s_barrier
	s_add_u32 s4, s42, 0x40000
	s_addc_u32 s5, s43, 0
	s_add_i32 s68, s69, s59
	v_lshl_add_u64 v[18:19], s[4:5], 0, v[184:185]
	s_mov_b32 m0, s68
	s_nop 0
	global_load_lds_dwordx4 v[18:19], off
	v_lshl_add_u64 v[18:19], s[4:5], 0, v[182:183]
	s_add_i32 m0, s68, 0x2000
	s_nop 0
	global_load_lds_dwordx4 v[18:19], off
	s_waitcnt vmcnt(6)
	s_barrier
	s_setprio 1
	v_mfma_f32_16x16x32_bf16 v[18:21], v[178:181], v[70:73], 0
	v_mfma_f32_16x16x32_bf16 v[22:25], v[190:193], v[114:117], v[18:21]
	v_mfma_f32_16x16x32_bf16 v[18:21], v[200:203], v[70:73], 0
	v_mfma_f32_16x16x32_bf16 v[26:29], v[222:225], v[114:117], v[18:21]
	v_mfma_f32_16x16x32_bf16 v[18:21], v[178:181], v[118:121], 0
	v_mfma_f32_16x16x32_bf16 v[30:33], v[190:193], v[130:133], v[18:21]
	v_mfma_f32_16x16x32_bf16 v[18:21], v[200:203], v[118:121], 0
	v_mfma_f32_16x16x32_bf16 v[70:73], v[222:225], v[130:133], v[18:21]
	v_mfma_f32_16x16x32_bf16 v[18:21], v[178:181], v[134:137], 0
	v_mfma_f32_16x16x32_bf16 v[50:53], v[190:193], v[146:149], v[18:21]
	v_mfma_f32_16x16x32_bf16 v[18:21], v[200:203], v[134:137], 0
	v_mfma_f32_16x16x32_bf16 v[6:9], v[178:181], v[150:153], 0
	v_mfma_f32_16x16x32_bf16 v[2:5], v[200:203], v[150:153], 0
	v_mfma_f32_16x16x32_bf16 v[34:37], v[222:225], v[146:149], v[18:21]
	v_mfma_f32_16x16x32_bf16 v[6:9], v[190:193], v[162:165], v[6:9]
	v_mfma_f32_16x16x32_bf16 v[2:5], v[222:225], v[162:165], v[2:5]
	s_setprio 0
	s_add_i32 s68, 0, 0x18000
	v_add_u32_e32 v98, s68, v204
	s_barrier
	ds_read_b128 v[18:21], v98
	ds_read_b128 v[82:85], v98 offset:1024
	ds_read_b128 v[86:89], v98 offset:2048
	ds_read_b128 v[98:101], v98 offset:3072
	s_add_u32 s4, s44, 0x40000
	s_addc_u32 s5, s45, 0
	s_mov_b32 m0, s62
	v_lshl_add_u64 v[134:135], s[4:5], 0, v[184:185]
	ds_read_b128 v[102:105], v209 offset:32768
	ds_read_b128 v[114:117], v209 offset:33792
	ds_read_b128 v[118:121], v209 offset:34816
	ds_read_b128 v[130:133], v209 offset:35840
	ds_read_b128 v[178:181], v209 offset:36864
	ds_read_b128 v[190:193], v209 offset:37888
	ds_read_b128 v[200:203], v209 offset:38912
	ds_read_b128 v[222:225], v209 offset:39936
	global_load_lds_dwordx4 v[134:135], off
	v_lshl_add_u64 v[134:135], s[4:5], 0, v[182:183]
	s_mov_b32 m0, s63
	s_nop 0
	global_load_lds_dwordx4 v[134:135], off
	s_waitcnt lgkmcnt(8)
	s_barrier
	s_waitcnt lgkmcnt(0)
	s_setprio 1
	s_waitcnt lgkmcnt(0)
	v_mfma_f32_16x16x32_bf16 v[134:137], v[18:21], v[102:105], v[174:177]
	v_mfma_f32_16x16x32_bf16 v[174:177], v[82:85], v[114:117], v[134:137]
	v_mfma_f32_16x16x32_bf16 v[134:137], v[86:89], v[102:105], v[170:173]
	v_mfma_f32_16x16x32_bf16 v[170:173], v[98:101], v[114:117], v[134:137]
	v_mfma_f32_16x16x32_bf16 v[134:137], v[18:21], v[118:121], v[158:161]
	v_mfma_f32_16x16x32_bf16 v[158:161], v[82:85], v[130:133], v[134:137]
	v_mfma_f32_16x16x32_bf16 v[134:137], v[86:89], v[118:121], v[154:157]
	v_mfma_f32_16x16x32_bf16 v[154:157], v[98:101], v[130:133], v[134:137]
	v_mfma_f32_16x16x32_bf16 v[134:137], v[18:21], v[178:181], v[142:145]
	v_mfma_f32_16x16x32_bf16 v[142:145], v[82:85], v[190:193], v[134:137]
	v_mfma_f32_16x16x32_bf16 v[134:137], v[86:89], v[178:181], v[138:141]
	v_mfma_f32_16x16x32_bf16 v[126:129], v[18:21], v[200:203], v[126:129]
	v_mfma_f32_16x16x32_bf16 v[122:125], v[86:89], v[200:203], v[122:125]
	v_mfma_f32_16x16x32_bf16 v[138:141], v[98:101], v[190:193], v[134:137]
	v_mfma_f32_16x16x32_bf16 v[126:129], v[82:85], v[222:225], v[126:129]
	v_mfma_f32_16x16x32_bf16 v[122:125], v[98:101], v[222:225], v[122:125]
	s_setprio 0
	s_barrier
	s_add_i32 s44, 0, 0x1c000
	v_add_u32_e32 v134, s44, v204
	s_add_i32 s4, s68, s59
	ds_read_b128 v[226:229], v134
	ds_read_b128 v[230:233], v134 offset:1024
	ds_read_b128 v[234:237], v134 offset:2048
	ds_read_b128 v[238:241], v134 offset:3072
	v_lshl_add_u64 v[134:135], v[210:211], 0, s[22:23]
	s_mov_b32 m0, s4
	s_nop 0
	global_load_lds_dwordx4 v[134:135], off
	v_lshl_add_u64 v[134:135], v[214:215], 0, s[22:23]
	s_add_i32 m0, s4, 0x2000
	s_nop 0
	global_load_lds_dwordx4 v[134:135], off
	s_barrier
	s_waitcnt lgkmcnt(0)
	s_setprio 1
	s_waitcnt lgkmcnt(0)
	v_mfma_f32_16x16x32_bf16 v[38:41], v[234:237], v[102:105], v[38:41]
	v_mfma_f32_16x16x32_bf16 v[162:165], v[238:241], v[114:117], v[38:41]
	v_mfma_f32_16x16x32_bf16 v[38:41], v[226:229], v[118:121], v[42:45]
	v_mfma_f32_16x16x32_bf16 v[150:153], v[230:233], v[130:133], v[38:41]
	v_mfma_f32_16x16x32_bf16 v[38:41], v[234:237], v[118:121], v[46:49]
	v_mfma_f32_16x16x32_bf16 v[134:137], v[226:229], v[102:105], v[166:169]
	v_mfma_f32_16x16x32_bf16 v[146:149], v[238:241], v[130:133], v[38:41]
	v_mfma_f32_16x16x32_bf16 v[38:41], v[226:229], v[178:181], v[54:57]
	v_mfma_f32_16x16x32_bf16 v[166:169], v[230:233], v[114:117], v[134:137]
	v_mfma_f32_16x16x32_bf16 v[134:137], v[230:233], v[190:193], v[38:41]
	v_mfma_f32_16x16x32_bf16 v[38:41], v[234:237], v[178:181], v[58:61]
	v_mfma_f32_16x16x32_bf16 v[130:133], v[238:241], v[190:193], v[38:41]
	v_mfma_f32_16x16x32_bf16 v[38:41], v[226:229], v[200:203], v[62:65]
	v_mfma_f32_16x16x32_bf16 v[118:121], v[230:233], v[222:225], v[38:41]
	v_mfma_f32_16x16x32_bf16 v[38:41], v[234:237], v[200:203], v[66:69]
	v_mfma_f32_16x16x32_bf16 v[114:117], v[238:241], v[222:225], v[38:41]
	s_setprio 0
	s_mov_b32 m0, s64
	v_lshl_add_u64 v[102:103], v[242:243], 0, s[22:23]
	s_barrier
	s_nop 2
	ds_read_b128 v[38:41], v209 offset:49152
	ds_read_b128 v[42:45], v209 offset:50176
	ds_read_b128 v[46:49], v209 offset:51200
	ds_read_b128 v[54:57], v209 offset:52224
	ds_read_b128 v[58:61], v209 offset:53248
	ds_read_b128 v[62:65], v209 offset:54272
	ds_read_b128 v[66:69], v209 offset:55296
	ds_read_b128 v[178:181], v209 offset:56320
	global_load_lds_dwordx4 v[102:103], off
	v_lshl_add_u64 v[102:103], v[244:245], 0, s[22:23]
	s_mov_b32 m0, s65
	s_nop 0
	global_load_lds_dwordx4 v[102:103], off
	s_barrier
	s_waitcnt lgkmcnt(0)
	s_setprio 1
	s_waitcnt lgkmcnt(0)
	v_mfma_f32_16x16x32_bf16 v[102:105], v[18:21], v[38:41], v[110:113]
	v_mfma_f32_16x16x32_bf16 v[110:113], v[82:85], v[42:45], v[102:105]
	v_mfma_f32_16x16x32_bf16 v[102:105], v[86:89], v[38:41], v[106:109]
	v_mfma_f32_16x16x32_bf16 v[94:97], v[18:21], v[46:49], v[94:97]
	v_mfma_f32_16x16x32_bf16 v[90:93], v[86:89], v[46:49], v[90:93]
	v_mfma_f32_16x16x32_bf16 v[78:81], v[18:21], v[58:61], v[78:81]
	v_mfma_f32_16x16x32_bf16 v[74:77], v[86:89], v[58:61], v[74:77]
	v_mfma_f32_16x16x32_bf16 v[14:17], v[18:21], v[66:69], v[14:17]
	v_mfma_f32_16x16x32_bf16 v[10:13], v[86:89], v[66:69], v[10:13]
	v_mfma_f32_16x16x32_bf16 v[106:109], v[98:101], v[42:45], v[102:105]
	v_mfma_f32_16x16x32_bf16 v[94:97], v[82:85], v[54:57], v[94:97]
	v_mfma_f32_16x16x32_bf16 v[90:93], v[98:101], v[54:57], v[90:93]
	v_mfma_f32_16x16x32_bf16 v[78:81], v[82:85], v[62:65], v[78:81]
	v_mfma_f32_16x16x32_bf16 v[74:77], v[98:101], v[62:65], v[74:77]
	v_mfma_f32_16x16x32_bf16 v[18:21], v[82:85], v[178:181], v[14:17]
	v_mfma_f32_16x16x32_bf16 v[10:13], v[98:101], v[178:181], v[10:13]
	s_setprio 0
	s_barrier
	s_add_u32 s4, s42, 0x40080
	s_addc_u32 s5, s43, 0
	s_add_i32 s42, s44, s59
	v_lshl_add_u64 v[14:15], s[4:5], 0, v[184:185]
	s_mov_b32 m0, s42
	s_nop 0
	global_load_lds_dwordx4 v[14:15], off
	v_lshl_add_u64 v[14:15], s[4:5], 0, v[182:183]
	s_add_i32 m0, s42, 0x2000
	s_nop 0
	global_load_lds_dwordx4 v[14:15], off
	s_waitcnt vmcnt(6)
	s_barrier
	s_setprio 1
	v_mfma_f32_16x16x32_bf16 v[14:17], v[226:229], v[38:41], v[22:25]
	v_mfma_f32_16x16x32_bf16 v[102:105], v[230:233], v[42:45], v[14:17]
	v_mfma_f32_16x16x32_bf16 v[14:17], v[234:237], v[38:41], v[26:29]
	v_mfma_f32_16x16x32_bf16 v[98:101], v[238:241], v[42:45], v[14:17]
	v_mfma_f32_16x16x32_bf16 v[14:17], v[226:229], v[46:49], v[30:33]
	v_mfma_f32_16x16x32_bf16 v[86:89], v[230:233], v[54:57], v[14:17]
	v_mfma_f32_16x16x32_bf16 v[14:17], v[234:237], v[46:49], v[70:73]
	v_mfma_f32_16x16x32_bf16 v[82:85], v[238:241], v[54:57], v[14:17]
	v_mfma_f32_16x16x32_bf16 v[14:17], v[226:229], v[58:61], v[50:53]
	v_mfma_f32_16x16x32_bf16 v[50:53], v[230:233], v[62:65], v[14:17]
	v_mfma_f32_16x16x32_bf16 v[14:17], v[234:237], v[58:61], v[34:37]
	v_mfma_f32_16x16x32_bf16 v[6:9], v[226:229], v[66:69], v[6:9]
	v_mfma_f32_16x16x32_bf16 v[2:5], v[234:237], v[66:69], v[2:5]
	v_mfma_f32_16x16x32_bf16 v[34:37], v[238:241], v[62:65], v[14:17]
	v_mfma_f32_16x16x32_bf16 v[6:9], v[230:233], v[178:181], v[6:9]
	v_mfma_f32_16x16x32_bf16 v[2:5], v[238:241], v[178:181], v[2:5]
	s_setprio 0
	s_add_i32 s57, s57, 2
	s_add_u32 s55, s55, 0x100
	s_addc_u32 s56, s56, 0
	s_cmp_gt_u32 s57, 13
	s_mov_b64 s[4:5], s[36:37]

.LBB0_396:
	s_add_u32 s36, s4, 0x100
	s_addc_u32 s37, s5, 0
	s_add_i32 s68, 0, 0x10000
	v_add_u32_e32 v30, s68, v204
	ds_read_b128 v[14:17], v30
	ds_read_b128 v[22:25], v30 offset:1024
	ds_read_b128 v[26:29], v30 offset:2048
	ds_read_b128 v[30:33], v30 offset:3072
	s_cmp_eq_u32 s57, 12
	s_cselect_b32 s45, s46, s37
	s_cselect_b32 s44, s47, s36
	s_cselect_b32 s43, s51, s56
	s_cselect_b32 s42, s54, s55
	v_lshl_add_u64 v[178:179], s[4:5], 0, v[188:189]
	s_add_i32 m0, s60, 0xc000
	ds_read_b128 v[38:41], v209
	ds_read_b128 v[42:45], v209 offset:1024
	ds_read_b128 v[46:49], v209 offset:2048
	ds_read_b128 v[54:57], v209 offset:3072
	ds_read_b128 v[58:61], v209 offset:4096
	ds_read_b128 v[62:65], v209 offset:5120
	ds_read_b128 v[66:69], v209 offset:6144
	ds_read_b128 v[70:73], v209 offset:7168
	global_load_lds_dwordx4 v[178:179], off
	v_lshl_add_u64 v[178:179], s[4:5], 0, v[186:187]
	s_add_i32 m0, s60, 0xe000
	s_nop 0
	global_load_lds_dwordx4 v[178:179], off
	s_waitcnt lgkmcnt(8)
	s_barrier
	s_waitcnt lgkmcnt(0)
	s_setprio 1
	s_waitcnt lgkmcnt(0)
	v_mfma_f32_16x16x32_bf16 v[174:177], v[14:17], v[38:41], v[174:177]
	v_mfma_f32_16x16x32_bf16 v[170:173], v[26:29], v[38:41], v[170:173]
	v_mfma_f32_16x16x32_bf16 v[158:161], v[14:17], v[46:49], v[158:161]
	v_mfma_f32_16x16x32_bf16 v[154:157], v[26:29], v[46:49], v[154:157]
	v_mfma_f32_16x16x32_bf16 v[142:145], v[14:17], v[58:61], v[142:145]
	v_mfma_f32_16x16x32_bf16 v[138:141], v[26:29], v[58:61], v[138:141]
	v_mfma_f32_16x16x32_bf16 v[126:129], v[14:17], v[66:69], v[126:129]
	v_mfma_f32_16x16x32_bf16 v[122:125], v[26:29], v[66:69], v[122:125]
	v_mfma_f32_16x16x32_bf16 v[174:177], v[22:25], v[42:45], v[174:177]
	v_mfma_f32_16x16x32_bf16 v[170:173], v[30:33], v[42:45], v[170:173]
	v_mfma_f32_16x16x32_bf16 v[158:161], v[22:25], v[54:57], v[158:161]
	v_mfma_f32_16x16x32_bf16 v[154:157], v[30:33], v[54:57], v[154:157]
	v_mfma_f32_16x16x32_bf16 v[142:145], v[22:25], v[62:65], v[142:145]
	v_mfma_f32_16x16x32_bf16 v[138:141], v[30:33], v[62:65], v[138:141]
	v_mfma_f32_16x16x32_bf16 v[126:129], v[22:25], v[70:73], v[126:129]
	v_mfma_f32_16x16x32_bf16 v[122:125], v[30:33], v[70:73], v[122:125]
	s_setprio 0
	s_barrier
	s_add_i32 s69, 0, 0x14000
	v_add_u32_e32 v210, s69, v204
	s_add_i32 s4, s68, s59
	ds_read_b128 v[178:181], v210
	ds_read_b128 v[190:193], v210 offset:1024
	ds_read_b128 v[200:203], v210 offset:2048
	ds_read_b128 v[222:225], v210 offset:3072
	v_lshl_add_u64 v[210:211], s[42:43], 0, v[184:185]
	s_mov_b32 m0, s4
	v_lshl_add_u64 v[214:215], s[42:43], 0, v[182:183]
	global_load_lds_dwordx4 v[210:211], off
	s_add_i32 m0, s4, 0x2000
	s_nop 0
	global_load_lds_dwordx4 v[214:215], off
	s_barrier
	s_waitcnt lgkmcnt(0)
	s_setprio 1
	s_waitcnt lgkmcnt(0)
	v_mfma_f32_16x16x32_bf16 v[166:169], v[178:181], v[38:41], v[166:169]
	v_mfma_f32_16x16x32_bf16 v[38:41], v[200:203], v[38:41], v[162:165]
	v_mfma_f32_16x16x32_bf16 v[166:169], v[190:193], v[42:45], v[166:169]
	v_mfma_f32_16x16x32_bf16 v[38:41], v[222:225], v[42:45], v[38:41]
	v_mfma_f32_16x16x32_bf16 v[42:45], v[178:181], v[46:49], v[150:153]
	v_mfma_f32_16x16x32_bf16 v[46:49], v[200:203], v[46:49], v[146:149]
	v_mfma_f32_16x16x32_bf16 v[42:45], v[190:193], v[54:57], v[42:45]
	v_mfma_f32_16x16x32_bf16 v[46:49], v[222:225], v[54:57], v[46:49]
	v_mfma_f32_16x16x32_bf16 v[54:57], v[178:181], v[58:61], v[134:137]
	v_mfma_f32_16x16x32_bf16 v[58:61], v[200:203], v[58:61], v[130:133]
	v_mfma_f32_16x16x32_bf16 v[54:57], v[190:193], v[62:65], v[54:57]
	v_mfma_f32_16x16x32_bf16 v[58:61], v[222:225], v[62:65], v[58:61]
	v_mfma_f32_16x16x32_bf16 v[62:65], v[178:181], v[66:69], v[118:121]
	v_mfma_f32_16x16x32_bf16 v[66:69], v[200:203], v[66:69], v[114:117]
	v_mfma_f32_16x16x32_bf16 v[62:65], v[190:193], v[70:73], v[62:65]
	v_mfma_f32_16x16x32_bf16 v[66:69], v[222:225], v[70:73], v[66:69]
	s_setprio 0
	s_mov_b32 m0, s60
	v_lshl_add_u64 v[242:243], s[44:45], 0, v[184:185]
	s_barrier
	ds_read_b128 v[70:73], v209 offset:16384
	ds_read_b128 v[114:117], v209 offset:17408
	ds_read_b128 v[118:121], v209 offset:18432
	ds_read_b128 v[130:133], v209 offset:19456
	ds_read_b128 v[134:137], v209 offset:20480
	ds_read_b128 v[146:149], v209 offset:21504
	ds_read_b128 v[150:153], v209 offset:22528
	ds_read_b128 v[162:165], v209 offset:23552
	global_load_lds_dwordx4 v[242:243], off
	v_lshl_add_u64 v[244:245], s[44:45], 0, v[182:183]
	s_mov_b32 m0, s61
	s_nop 0
	global_load_lds_dwordx4 v[244:245], off
	s_barrier
	s_waitcnt lgkmcnt(0)
	s_setprio 1
	s_waitcnt lgkmcnt(0)
	v_mfma_f32_16x16x32_bf16 v[110:113], v[14:17], v[70:73], v[110:113]
	v_mfma_f32_16x16x32_bf16 v[106:109], v[26:29], v[70:73], v[106:109]
	v_mfma_f32_16x16x32_bf16 v[94:97], v[14:17], v[118:121], v[94:97]
	v_mfma_f32_16x16x32_bf16 v[90:93], v[26:29], v[118:121], v[90:93]
	v_mfma_f32_16x16x32_bf16 v[78:81], v[14:17], v[134:137], v[78:81]
	v_mfma_f32_16x16x32_bf16 v[74:77], v[26:29], v[134:137], v[74:77]
	v_mfma_f32_16x16x32_bf16 v[10:13], v[26:29], v[150:153], v[10:13]
	v_mfma_f32_16x16x32_bf16 v[110:113], v[22:25], v[114:117], v[110:113]
	v_mfma_f32_16x16x32_bf16 v[106:109], v[30:33], v[114:117], v[106:109]
	v_mfma_f32_16x16x32_bf16 v[94:97], v[22:25], v[130:133], v[94:97]
	v_mfma_f32_16x16x32_bf16 v[90:93], v[30:33], v[130:133], v[90:93]
	v_mfma_f32_16x16x32_bf16 v[78:81], v[22:25], v[146:149], v[78:81]
	v_mfma_f32_16x16x32_bf16 v[74:77], v[30:33], v[146:149], v[74:77]
	v_mfma_f32_16x16x32_bf16 v[14:17], v[14:17], v[150:153], v[18:21]
	v_mfma_f32_16x16x32_bf16 v[10:13], v[30:33], v[162:165], v[10:13]
	v_mfma_f32_16x16x32_bf16 v[14:17], v[22:25], v[162:165], v[14:17]
	s_setprio 0
	s_barrier
	s_add_u32 s4, s42, 0x40000
	s_addc_u32 s5, s43, 0
	s_add_i32 s68, s69, s59
	v_lshl_add_u64 v[18:19], s[4:5], 0, v[184:185]
	s_mov_b32 m0, s68
	s_nop 0
	global_load_lds_dwordx4 v[18:19], off
	v_lshl_add_u64 v[18:19], s[4:5], 0, v[182:183]
	s_add_i32 m0, s68, 0x2000
	s_nop 0
	global_load_lds_dwordx4 v[18:19], off
	s_waitcnt vmcnt(6)
	s_barrier
	s_setprio 1
	v_mfma_f32_16x16x32_bf16 v[18:21], v[178:181], v[70:73], v[102:105]
	v_mfma_f32_16x16x32_bf16 v[22:25], v[190:193], v[114:117], v[18:21]
	v_mfma_f32_16x16x32_bf16 v[18:21], v[200:203], v[70:73], v[98:101]
	v_mfma_f32_16x16x32_bf16 v[26:29], v[222:225], v[114:117], v[18:21]
	v_mfma_f32_16x16x32_bf16 v[18:21], v[178:181], v[118:121], v[86:89]
	v_mfma_f32_16x16x32_bf16 v[30:33], v[190:193], v[130:133], v[18:21]
	v_mfma_f32_16x16x32_bf16 v[18:21], v[200:203], v[118:121], v[82:85]
	v_mfma_f32_16x16x32_bf16 v[70:73], v[222:225], v[130:133], v[18:21]
	v_mfma_f32_16x16x32_bf16 v[18:21], v[178:181], v[134:137], v[50:53]
	v_mfma_f32_16x16x32_bf16 v[50:53], v[190:193], v[146:149], v[18:21]
	v_mfma_f32_16x16x32_bf16 v[18:21], v[200:203], v[134:137], v[34:37]
	v_mfma_f32_16x16x32_bf16 v[6:9], v[178:181], v[150:153], v[6:9]
	v_mfma_f32_16x16x32_bf16 v[2:5], v[200:203], v[150:153], v[2:5]
	v_mfma_f32_16x16x32_bf16 v[34:37], v[222:225], v[146:149], v[18:21]
	v_mfma_f32_16x16x32_bf16 v[6:9], v[190:193], v[162:165], v[6:9]
	v_mfma_f32_16x16x32_bf16 v[2:5], v[222:225], v[162:165], v[2:5]
	s_setprio 0
	s_add_i32 s68, 0, 0x18000
	v_add_u32_e32 v98, s68, v204
	s_barrier
	ds_read_b128 v[18:21], v98
	ds_read_b128 v[82:85], v98 offset:1024
	ds_read_b128 v[86:89], v98 offset:2048
	ds_read_b128 v[98:101], v98 offset:3072
	s_add_u32 s4, s44, 0x40000
	s_addc_u32 s5, s45, 0
	s_mov_b32 m0, s62
	v_lshl_add_u64 v[134:135], s[4:5], 0, v[184:185]
	ds_read_b128 v[102:105], v209 offset:32768
	ds_read_b128 v[114:117], v209 offset:33792
	ds_read_b128 v[118:121], v209 offset:34816
	ds_read_b128 v[130:133], v209 offset:35840
	ds_read_b128 v[178:181], v209 offset:36864
	ds_read_b128 v[190:193], v209 offset:37888
	ds_read_b128 v[200:203], v209 offset:38912
	ds_read_b128 v[222:225], v209 offset:39936
	global_load_lds_dwordx4 v[134:135], off
	v_lshl_add_u64 v[134:135], s[4:5], 0, v[182:183]
	s_mov_b32 m0, s63
	s_nop 0
	global_load_lds_dwordx4 v[134:135], off
	s_waitcnt lgkmcnt(8)
	s_barrier
	s_waitcnt lgkmcnt(0)
	s_setprio 1
	s_waitcnt lgkmcnt(0)
	v_mfma_f32_16x16x32_bf16 v[134:137], v[18:21], v[102:105], v[174:177]
	v_mfma_f32_16x16x32_bf16 v[174:177], v[82:85], v[114:117], v[134:137]
	v_mfma_f32_16x16x32_bf16 v[134:137], v[86:89], v[102:105], v[170:173]
	v_mfma_f32_16x16x32_bf16 v[170:173], v[98:101], v[114:117], v[134:137]
	v_mfma_f32_16x16x32_bf16 v[134:137], v[18:21], v[118:121], v[158:161]
	v_mfma_f32_16x16x32_bf16 v[158:161], v[82:85], v[130:133], v[134:137]
	v_mfma_f32_16x16x32_bf16 v[134:137], v[86:89], v[118:121], v[154:157]
	v_mfma_f32_16x16x32_bf16 v[154:157], v[98:101], v[130:133], v[134:137]
	v_mfma_f32_16x16x32_bf16 v[134:137], v[18:21], v[178:181], v[142:145]
	v_mfma_f32_16x16x32_bf16 v[142:145], v[82:85], v[190:193], v[134:137]
	v_mfma_f32_16x16x32_bf16 v[134:137], v[86:89], v[178:181], v[138:141]
	v_mfma_f32_16x16x32_bf16 v[126:129], v[18:21], v[200:203], v[126:129]
	v_mfma_f32_16x16x32_bf16 v[122:125], v[86:89], v[200:203], v[122:125]
	v_mfma_f32_16x16x32_bf16 v[138:141], v[98:101], v[190:193], v[134:137]
	v_mfma_f32_16x16x32_bf16 v[126:129], v[82:85], v[222:225], v[126:129]
	v_mfma_f32_16x16x32_bf16 v[122:125], v[98:101], v[222:225], v[122:125]
	s_setprio 0
	s_barrier
	s_add_i32 s44, 0, 0x1c000
	v_add_u32_e32 v134, s44, v204
	s_add_i32 s4, s68, s59
	ds_read_b128 v[226:229], v134
	ds_read_b128 v[230:233], v134 offset:1024
	ds_read_b128 v[234:237], v134 offset:2048
	ds_read_b128 v[238:241], v134 offset:3072
	v_lshl_add_u64 v[134:135], v[210:211], 0, s[22:23]
	s_mov_b32 m0, s4
	s_nop 0
	global_load_lds_dwordx4 v[134:135], off
	v_lshl_add_u64 v[134:135], v[214:215], 0, s[22:23]
	s_add_i32 m0, s4, 0x2000
	s_nop 0
	global_load_lds_dwordx4 v[134:135], off
	s_barrier
	s_waitcnt lgkmcnt(0)
	s_setprio 1
	s_waitcnt lgkmcnt(0)
	v_mfma_f32_16x16x32_bf16 v[38:41], v[234:237], v[102:105], v[38:41]
	v_mfma_f32_16x16x32_bf16 v[162:165], v[238:241], v[114:117], v[38:41]
	v_mfma_f32_16x16x32_bf16 v[38:41], v[226:229], v[118:121], v[42:45]
	v_mfma_f32_16x16x32_bf16 v[150:153], v[230:233], v[130:133], v[38:41]
	v_mfma_f32_16x16x32_bf16 v[38:41], v[234:237], v[118:121], v[46:49]
	v_mfma_f32_16x16x32_bf16 v[134:137], v[226:229], v[102:105], v[166:169]
	v_mfma_f32_16x16x32_bf16 v[146:149], v[238:241], v[130:133], v[38:41]
	v_mfma_f32_16x16x32_bf16 v[38:41], v[226:229], v[178:181], v[54:57]
	v_mfma_f32_16x16x32_bf16 v[166:169], v[230:233], v[114:117], v[134:137]
	v_mfma_f32_16x16x32_bf16 v[134:137], v[230:233], v[190:193], v[38:41]
	v_mfma_f32_16x16x32_bf16 v[38:41], v[234:237], v[178:181], v[58:61]
	v_mfma_f32_16x16x32_bf16 v[130:133], v[238:241], v[190:193], v[38:41]
	v_mfma_f32_16x16x32_bf16 v[38:41], v[226:229], v[200:203], v[62:65]
	v_mfma_f32_16x16x32_bf16 v[118:121], v[230:233], v[222:225], v[38:41]
	v_mfma_f32_16x16x32_bf16 v[38:41], v[234:237], v[200:203], v[66:69]
	v_mfma_f32_16x16x32_bf16 v[114:117], v[238:241], v[222:225], v[38:41]
	s_setprio 0
	s_mov_b32 m0, s64
	v_lshl_add_u64 v[102:103], v[242:243], 0, s[22:23]
	s_barrier
	s_nop 2
	ds_read_b128 v[38:41], v209 offset:49152
	ds_read_b128 v[42:45], v209 offset:50176
	ds_read_b128 v[46:49], v209 offset:51200
	ds_read_b128 v[54:57], v209 offset:52224
	ds_read_b128 v[58:61], v209 offset:53248
	ds_read_b128 v[62:65], v209 offset:54272
	ds_read_b128 v[66:69], v209 offset:55296
	ds_read_b128 v[178:181], v209 offset:56320
	global_load_lds_dwordx4 v[102:103], off
	v_lshl_add_u64 v[102:103], v[244:245], 0, s[22:23]
	s_mov_b32 m0, s65
	s_nop 0
	global_load_lds_dwordx4 v[102:103], off
	s_barrier
	s_waitcnt lgkmcnt(0)
	s_setprio 1
	s_waitcnt lgkmcnt(0)
	v_mfma_f32_16x16x32_bf16 v[102:105], v[18:21], v[38:41], v[110:113]
	v_mfma_f32_16x16x32_bf16 v[110:113], v[82:85], v[42:45], v[102:105]
	v_mfma_f32_16x16x32_bf16 v[102:105], v[86:89], v[38:41], v[106:109]
	v_mfma_f32_16x16x32_bf16 v[94:97], v[18:21], v[46:49], v[94:97]
	v_mfma_f32_16x16x32_bf16 v[90:93], v[86:89], v[46:49], v[90:93]
	v_mfma_f32_16x16x32_bf16 v[78:81], v[18:21], v[58:61], v[78:81]
	v_mfma_f32_16x16x32_bf16 v[74:77], v[86:89], v[58:61], v[74:77]
	v_mfma_f32_16x16x32_bf16 v[14:17], v[18:21], v[66:69], v[14:17]
	v_mfma_f32_16x16x32_bf16 v[10:13], v[86:89], v[66:69], v[10:13]
	v_mfma_f32_16x16x32_bf16 v[106:109], v[98:101], v[42:45], v[102:105]
	v_mfma_f32_16x16x32_bf16 v[94:97], v[82:85], v[54:57], v[94:97]
	v_mfma_f32_16x16x32_bf16 v[90:93], v[98:101], v[54:57], v[90:93]
	v_mfma_f32_16x16x32_bf16 v[78:81], v[82:85], v[62:65], v[78:81]
	v_mfma_f32_16x16x32_bf16 v[74:77], v[98:101], v[62:65], v[74:77]
	v_mfma_f32_16x16x32_bf16 v[18:21], v[82:85], v[178:181], v[14:17]
	v_mfma_f32_16x16x32_bf16 v[10:13], v[98:101], v[178:181], v[10:13]
	s_setprio 0
	s_barrier
	s_add_u32 s4, s42, 0x40080
	s_addc_u32 s5, s43, 0
	s_add_i32 s42, s44, s59
	v_lshl_add_u64 v[14:15], s[4:5], 0, v[184:185]
	s_mov_b32 m0, s42
	s_nop 0
	global_load_lds_dwordx4 v[14:15], off
	v_lshl_add_u64 v[14:15], s[4:5], 0, v[182:183]
	s_add_i32 m0, s42, 0x2000
	s_nop 0
	global_load_lds_dwordx4 v[14:15], off
	s_waitcnt vmcnt(6)
	s_barrier
	s_setprio 1
	v_mfma_f32_16x16x32_bf16 v[14:17], v[226:229], v[38:41], v[22:25]
	v_mfma_f32_16x16x32_bf16 v[102:105], v[230:233], v[42:45], v[14:17]
	v_mfma_f32_16x16x32_bf16 v[14:17], v[234:237], v[38:41], v[26:29]
	v_mfma_f32_16x16x32_bf16 v[98:101], v[238:241], v[42:45], v[14:17]
	v_mfma_f32_16x16x32_bf16 v[14:17], v[226:229], v[46:49], v[30:33]
	v_mfma_f32_16x16x32_bf16 v[86:89], v[230:233], v[54:57], v[14:17]
	v_mfma_f32_16x16x32_bf16 v[14:17], v[234:237], v[46:49], v[70:73]
	v_mfma_f32_16x16x32_bf16 v[82:85], v[238:241], v[54:57], v[14:17]
	v_mfma_f32_16x16x32_bf16 v[14:17], v[226:229], v[58:61], v[50:53]
	v_mfma_f32_16x16x32_bf16 v[50:53], v[230:233], v[62:65], v[14:17]
	v_mfma_f32_16x16x32_bf16 v[14:17], v[234:237], v[58:61], v[34:37]
	v_mfma_f32_16x16x32_bf16 v[6:9], v[226:229], v[66:69], v[6:9]
	v_mfma_f32_16x16x32_bf16 v[2:5], v[234:237], v[66:69], v[2:5]
	v_mfma_f32_16x16x32_bf16 v[34:37], v[238:241], v[62:65], v[14:17]
	v_mfma_f32_16x16x32_bf16 v[6:9], v[230:233], v[178:181], v[6:9]
	v_mfma_f32_16x16x32_bf16 v[2:5], v[238:241], v[178:181], v[2:5]
	s_setprio 0
	s_add_i32 s57, s57, 2
	s_add_u32 s55, s55, 0x100
	s_addc_u32 s56, s56, 0
	s_cmp_gt_u32 s57, 13
	s_mov_b64 s[4:5], s[36:37]
	s_cbranch_scc0 .Lrot_0
	s_barrier
	v_lshl_or_b32 v202, s27, 8, v208
	s_and_b32 s4, s27, -4
	v_ashrrev_i32_e32 v203, 31, v202
	v_lshlrev_b64 v[14:15], 2, v[202:203]
	v_lshl_add_u64 v[16:17], s[10:11], 0, v[14:15]
	v_lshl_add_u64 v[22:23], s[12:13], 0, v[14:15]
	flat_load_dwordx4 v[70:73], v[16:17]
	flat_load_dwordx4 v[66:69], v[22:23]
	s_cmp_eq_u32 s4, 4
	s_cselect_b64 s[36:37], -1, 0
	s_cmp_lg_u32 s4, 4
	v_mov_b32_e32 v46, 0
	v_and_b32_e32 v210, 0x3ff, v202
	v_mov_b32_e32 v62, 0
	v_mov_b32_e32 v63, 0
	v_mov_b32_e32 v64, 0
	v_mov_b32_e32 v65, 0
	s_cbranch_scc1 .LBB0_399
	v_lshlrev_b32_e32 v14, 2, v210
	v_mov_b32_e32 v15, v0
	v_lshl_add_u64 v[14:15], s[14:15], 0, v[14:15]
	flat_load_dwordx4 v[62:65], v[14:15]

.LBB0_1098:
	s_add_i32 s76, s76, 1
	s_mov_b64 s[62:63], s[54:55]
	s_mul_i32 s54, s76, s26
	s_add_i32 s64, s54, s2
	s_cmpk_gt_i32 s64, 0x57f
	s_cselect_b64 s[60:61], -1, 0
	s_lshl_b32 s54, s64, 3
	s_and_b32 s54, s54, 56
	s_bfe_u32 s55, s64, 0x30003
	s_or_b32 s77, s54, s55
	s_ashr_i32 s58, s64, 6
	s_lshl_b32 s54, s77, 19
	s_mov_b64 s[36:37], s[56:57]
	s_add_u32 s56, s52, s54
	s_addc_u32 s57, s53, 0
	s_ashr_i32 s59, s58, 31
	s_lshl_b64 s[54:55], s[58:59], 19
	s_add_u32 s54, s4, s54
	s_addc_u32 s55, s5, s55
	s_cmpk_lt_i32 s64, 0x580
	s_cselect_b32 s59, s57, s37
	s_cselect_b32 s78, s56, s36
	s_cselect_b32 s79, s55, s63
	s_cselect_b32 s80, s54, s62
	s_add_u32 s81, s62, 0x100
	s_addc_u32 s82, s63, 0
	s_mov_b32 s83, -2
	s_add_u32 s62, s36, 0x100
	s_addc_u32 s63, s37, 0
	s_add_i32 s84, 0, 0x10000
	v_add_u32_e32 v70, s84, v170
	ds_read_b128 v[58:61], v70
	ds_read_b128 v[62:65], v70 offset:1024
	ds_read_b128 v[66:69], v70 offset:2048
	ds_read_b128 v[70:73], v70 offset:3072
	s_cmp_eq_u32 s83, 12
	s_cselect_b32 s67, s59, s63
	s_cselect_b32 s66, s78, s62
	s_cselect_b32 s65, s79, s82
	s_cselect_b32 s64, s80, s81
	v_lshl_add_u64 v[192:193], s[36:37], 0, v[168:169]
	s_add_i32 m0, s69, 0xc000
	ds_read_b128 v[78:81], v175
	ds_read_b128 v[86:89], v175 offset:1024
	ds_read_b128 v[90:93], v175 offset:2048
	ds_read_b128 v[94:97], v175 offset:3072
	ds_read_b128 v[176:179], v175 offset:4096
	ds_read_b128 v[180:183], v175 offset:5120
	ds_read_b128 v[184:187], v175 offset:6144
	ds_read_b128 v[188:191], v175 offset:7168
	global_load_lds_dwordx4 v[192:193], off
	v_lshl_add_u64 v[192:193], s[36:37], 0, v[166:167]
	s_add_i32 m0, s69, 0xe000
	s_nop 0
	global_load_lds_dwordx4 v[192:193], off
	s_waitcnt lgkmcnt(8)
	s_barrier
	s_waitcnt lgkmcnt(0)
	s_setprio 1
	s_waitcnt lgkmcnt(0)
	v_mfma_f32_16x16x32_bf16 v[158:161], v[58:61], v[78:81], 0
	v_mfma_f32_16x16x32_bf16 v[150:153], v[66:69], v[78:81], 0
	v_mfma_f32_16x16x32_bf16 v[142:145], v[58:61], v[90:93], 0
	v_mfma_f32_16x16x32_bf16 v[134:137], v[66:69], v[90:93], 0
	v_mfma_f32_16x16x32_bf16 v[126:129], v[58:61], v[176:179], 0
	v_mfma_f32_16x16x32_bf16 v[118:121], v[66:69], v[176:179], 0
	v_mfma_f32_16x16x32_bf16 v[110:113], v[58:61], v[184:187], 0
	v_mfma_f32_16x16x32_bf16 v[102:105], v[66:69], v[184:187], 0
	v_mfma_f32_16x16x32_bf16 v[158:161], v[62:65], v[86:89], v[158:161]
	v_mfma_f32_16x16x32_bf16 v[150:153], v[70:73], v[86:89], v[150:153]
	v_mfma_f32_16x16x32_bf16 v[142:145], v[62:65], v[94:97], v[142:145]
	v_mfma_f32_16x16x32_bf16 v[134:137], v[70:73], v[94:97], v[134:137]
	v_mfma_f32_16x16x32_bf16 v[126:129], v[62:65], v[180:183], v[126:129]
	v_mfma_f32_16x16x32_bf16 v[118:121], v[70:73], v[180:183], v[118:121]
	v_mfma_f32_16x16x32_bf16 v[110:113], v[62:65], v[188:191], v[110:113]
	v_mfma_f32_16x16x32_bf16 v[102:105], v[70:73], v[188:191], v[102:105]
	s_setprio 0
	s_barrier
	s_add_i32 s85, 0, 0x14000
	v_add_u32_e32 v192, s85, v170
	s_add_i32 s36, s84, s68
	ds_read_b128 v[200:203], v192
	ds_read_b128 v[204:207], v192 offset:1024
	ds_read_b128 v[208:211], v192 offset:2048
	ds_read_b128 v[222:225], v192 offset:3072
	v_lshl_add_u64 v[192:193], s[64:65], 0, v[164:165]
	s_mov_b32 m0, s36
	v_lshl_add_u64 v[214:215], s[64:65], 0, v[162:163]
	global_load_lds_dwordx4 v[192:193], off
	s_add_i32 m0, s36, 0x2000
	s_nop 0
	global_load_lds_dwordx4 v[214:215], off
	s_barrier
	s_waitcnt lgkmcnt(0)
	s_setprio 1
	s_waitcnt lgkmcnt(0)
	v_mfma_f32_16x16x32_bf16 v[154:157], v[200:203], v[78:81], 0
	v_mfma_f32_16x16x32_bf16 v[78:81], v[208:211], v[78:81], 0
	v_mfma_f32_16x16x32_bf16 v[154:157], v[204:207], v[86:89], v[154:157]
	v_mfma_f32_16x16x32_bf16 v[78:81], v[222:225], v[86:89], v[78:81]
	v_mfma_f32_16x16x32_bf16 v[86:89], v[200:203], v[90:93], 0
	v_mfma_f32_16x16x32_bf16 v[90:93], v[208:211], v[90:93], 0
	v_mfma_f32_16x16x32_bf16 v[114:117], v[208:211], v[176:179], 0
	v_mfma_f32_16x16x32_bf16 v[106:109], v[200:203], v[184:187], 0
	v_mfma_f32_16x16x32_bf16 v[98:101], v[208:211], v[184:187], 0
	v_mfma_f32_16x16x32_bf16 v[86:89], v[204:207], v[94:97], v[86:89]
	v_mfma_f32_16x16x32_bf16 v[90:93], v[222:225], v[94:97], v[90:93]
	v_mfma_f32_16x16x32_bf16 v[94:97], v[200:203], v[176:179], 0
	v_mfma_f32_16x16x32_bf16 v[114:117], v[222:225], v[180:183], v[114:117]
	v_mfma_f32_16x16x32_bf16 v[106:109], v[204:207], v[188:191], v[106:109]
	v_mfma_f32_16x16x32_bf16 v[98:101], v[222:225], v[188:191], v[98:101]
	v_mfma_f32_16x16x32_bf16 v[94:97], v[204:207], v[180:183], v[94:97]
	s_setprio 0
	s_mov_b32 m0, s69
	v_lshl_add_u64 v[234:235], s[66:67], 0, v[164:165]
	s_barrier
	ds_read_b128 v[122:125], v175 offset:16384
	ds_read_b128 v[130:133], v175 offset:17408
	ds_read_b128 v[138:141], v175 offset:18432
	ds_read_b128 v[146:149], v175 offset:19456
	ds_read_b128 v[176:179], v175 offset:20480
	ds_read_b128 v[180:183], v175 offset:21504
	ds_read_b128 v[184:187], v175 offset:22528
	ds_read_b128 v[188:191], v175 offset:23552
	global_load_lds_dwordx4 v[234:235], off
	v_lshl_add_u64 v[236:237], s[66:67], 0, v[162:163]
	s_mov_b32 m0, s70
	s_nop 0
	global_load_lds_dwordx4 v[236:237], off
	s_barrier
	s_waitcnt lgkmcnt(0)
	s_setprio 1
	s_waitcnt lgkmcnt(0)
	v_mfma_f32_16x16x32_bf16 v[82:85], v[58:61], v[122:125], 0
	v_mfma_f32_16x16x32_bf16 v[54:57], v[66:69], v[122:125], 0
	v_mfma_f32_16x16x32_bf16 v[46:49], v[58:61], v[138:141], 0
	v_mfma_f32_16x16x32_bf16 v[38:41], v[66:69], v[138:141], 0
	v_mfma_f32_16x16x32_bf16 v[30:33], v[58:61], v[176:179], 0
	v_mfma_f32_16x16x32_bf16 v[22:25], v[66:69], v[176:179], 0
	v_mfma_f32_16x16x32_bf16 v[14:17], v[58:61], v[184:187], 0
	v_mfma_f32_16x16x32_bf16 v[6:9], v[66:69], v[184:187], 0
	v_mfma_f32_16x16x32_bf16 v[82:85], v[62:65], v[130:133], v[82:85]
	v_mfma_f32_16x16x32_bf16 v[54:57], v[70:73], v[130:133], v[54:57]
	v_mfma_f32_16x16x32_bf16 v[46:49], v[62:65], v[146:149], v[46:49]
	v_mfma_f32_16x16x32_bf16 v[38:41], v[70:73], v[146:149], v[38:41]
	v_mfma_f32_16x16x32_bf16 v[30:33], v[62:65], v[180:183], v[30:33]
	v_mfma_f32_16x16x32_bf16 v[22:25], v[70:73], v[180:183], v[22:25]
	v_mfma_f32_16x16x32_bf16 v[14:17], v[62:65], v[188:191], v[14:17]
	v_mfma_f32_16x16x32_bf16 v[6:9], v[70:73], v[188:191], v[6:9]
	s_setprio 0
	s_barrier
	s_add_u32 s36, s64, 0x40000
	s_addc_u32 s37, s65, 0
	s_add_i32 s84, s85, s68
	v_lshl_add_u64 v[58:59], s[36:37], 0, v[164:165]
	s_mov_b32 m0, s84
	s_nop 0
	global_load_lds_dwordx4 v[58:59], off
	v_lshl_add_u64 v[58:59], s[36:37], 0, v[162:163]
	s_add_i32 m0, s84, 0x2000
	s_nop 0
	global_load_lds_dwordx4 v[58:59], off
	s_waitcnt vmcnt(6)
	s_barrier
	s_setprio 1
	v_mfma_f32_16x16x32_bf16 v[50:53], v[208:211], v[122:125], 0
	v_mfma_f32_16x16x32_bf16 v[42:45], v[200:203], v[138:141], 0
	v_mfma_f32_16x16x32_bf16 v[34:37], v[208:211], v[138:141], 0
	v_mfma_f32_16x16x32_bf16 v[26:29], v[200:203], v[176:179], 0
	v_mfma_f32_16x16x32_bf16 v[18:21], v[208:211], v[176:179], 0
	v_mfma_f32_16x16x32_bf16 v[10:13], v[200:203], v[184:187], 0
	v_mfma_f32_16x16x32_bf16 v[2:5], v[208:211], v[184:187], 0
	v_mfma_f32_16x16x32_bf16 v[58:61], v[200:203], v[122:125], 0
	v_mfma_f32_16x16x32_bf16 v[50:53], v[222:225], v[130:133], v[50:53]
	v_mfma_f32_16x16x32_bf16 v[42:45], v[204:207], v[146:149], v[42:45]
	v_mfma_f32_16x16x32_bf16 v[34:37], v[222:225], v[146:149], v[34:37]
	v_mfma_f32_16x16x32_bf16 v[26:29], v[204:207], v[180:183], v[26:29]
	v_mfma_f32_16x16x32_bf16 v[18:21], v[222:225], v[180:183], v[18:21]
	v_mfma_f32_16x16x32_bf16 v[10:13], v[204:207], v[188:191], v[10:13]
	v_mfma_f32_16x16x32_bf16 v[2:5], v[222:225], v[188:191], v[2:5]
	v_mfma_f32_16x16x32_bf16 v[58:61], v[204:207], v[130:133], v[58:61]
	s_setprio 0
	s_add_i32 s84, 0, 0x18000
	v_add_u32_e32 v74, s84, v170
	s_barrier
	ds_read_b128 v[62:65], v74
	ds_read_b128 v[66:69], v74 offset:1024
	ds_read_b128 v[70:73], v74 offset:2048
	ds_read_b128 v[74:77], v74 offset:3072
	s_add_u32 s36, s66, 0x40000
	s_addc_u32 s37, s67, 0
	s_mov_b32 m0, s71
	v_lshl_add_u64 v[138:139], s[36:37], 0, v[164:165]
	ds_read_b128 v[122:125], v175 offset:32768
	ds_read_b128 v[130:133], v175 offset:33792
	ds_read_b128 v[176:179], v175 offset:34816
	ds_read_b128 v[180:183], v175 offset:35840
	ds_read_b128 v[184:187], v175 offset:36864
	ds_read_b128 v[188:191], v175 offset:37888
	ds_read_b128 v[200:203], v175 offset:38912
	ds_read_b128 v[204:207], v175 offset:39936
	global_load_lds_dwordx4 v[138:139], off
	v_lshl_add_u64 v[138:139], s[36:37], 0, v[162:163]
	s_mov_b32 m0, s72
	s_nop 0
	global_load_lds_dwordx4 v[138:139], off
	s_waitcnt lgkmcnt(8)
	s_barrier
	s_waitcnt lgkmcnt(0)
	s_setprio 1
	s_waitcnt lgkmcnt(0)
	v_mfma_f32_16x16x32_bf16 v[138:141], v[62:65], v[122:125], v[158:161]
	v_mfma_f32_16x16x32_bf16 v[158:161], v[66:69], v[130:133], v[138:141]
	v_mfma_f32_16x16x32_bf16 v[138:141], v[70:73], v[122:125], v[150:153]
	v_mfma_f32_16x16x32_bf16 v[150:153], v[74:77], v[130:133], v[138:141]
	v_mfma_f32_16x16x32_bf16 v[138:141], v[62:65], v[176:179], v[142:145]
	v_mfma_f32_16x16x32_bf16 v[134:137], v[70:73], v[176:179], v[134:137]
	v_mfma_f32_16x16x32_bf16 v[126:129], v[62:65], v[184:187], v[126:129]
	v_mfma_f32_16x16x32_bf16 v[118:121], v[70:73], v[184:187], v[118:121]
	v_mfma_f32_16x16x32_bf16 v[110:113], v[62:65], v[200:203], v[110:113]
	v_mfma_f32_16x16x32_bf16 v[102:105], v[70:73], v[200:203], v[102:105]
	v_mfma_f32_16x16x32_bf16 v[142:145], v[66:69], v[180:183], v[138:141]
	v_mfma_f32_16x16x32_bf16 v[134:137], v[74:77], v[180:183], v[134:137]
	v_mfma_f32_16x16x32_bf16 v[126:129], v[66:69], v[188:191], v[126:129]
	v_mfma_f32_16x16x32_bf16 v[118:121], v[74:77], v[188:191], v[118:121]
	v_mfma_f32_16x16x32_bf16 v[110:113], v[66:69], v[204:207], v[110:113]
	v_mfma_f32_16x16x32_bf16 v[102:105], v[74:77], v[204:207], v[102:105]
	s_setprio 0
	s_barrier
	s_add_i32 s66, 0, 0x1c000
	v_add_u32_e32 v138, s66, v170
	s_add_i32 s36, s84, s68
	ds_read_b128 v[208:211], v138
	ds_read_b128 v[222:225], v138 offset:1024
	ds_read_b128 v[226:229], v138 offset:2048
	ds_read_b128 v[230:233], v138 offset:3072
	v_lshl_add_u64 v[138:139], v[192:193], 0, s[22:23]
	s_mov_b32 m0, s36
	s_nop 0
	global_load_lds_dwordx4 v[138:139], off
	v_lshl_add_u64 v[138:139], v[214:215], 0, s[22:23]
	s_add_i32 m0, s36, 0x2000
	s_nop 0
	global_load_lds_dwordx4 v[138:139], off
	s_barrier
	s_waitcnt lgkmcnt(0)
	s_setprio 1
	s_waitcnt lgkmcnt(0)
	v_mfma_f32_16x16x32_bf16 v[78:81], v[226:229], v[122:125], v[78:81]
	v_mfma_f32_16x16x32_bf16 v[138:141], v[208:211], v[122:125], v[154:157]
	v_mfma_f32_16x16x32_bf16 v[146:149], v[230:233], v[130:133], v[78:81]
	v_mfma_f32_16x16x32_bf16 v[78:81], v[208:211], v[176:179], v[86:89]
	v_mfma_f32_16x16x32_bf16 v[154:157], v[222:225], v[130:133], v[138:141]
	v_mfma_f32_16x16x32_bf16 v[138:141], v[222:225], v[180:183], v[78:81]
	v_mfma_f32_16x16x32_bf16 v[78:81], v[226:229], v[176:179], v[90:93]
	v_mfma_f32_16x16x32_bf16 v[130:133], v[230:233], v[180:183], v[78:81]
	v_mfma_f32_16x16x32_bf16 v[78:81], v[208:211], v[184:187], v[94:97]
	v_mfma_f32_16x16x32_bf16 v[122:125], v[222:225], v[188:191], v[78:81]
	v_mfma_f32_16x16x32_bf16 v[78:81], v[226:229], v[184:187], v[114:117]
	v_mfma_f32_16x16x32_bf16 v[114:117], v[230:233], v[188:191], v[78:81]
	v_mfma_f32_16x16x32_bf16 v[78:81], v[208:211], v[200:203], v[106:109]
	v_mfma_f32_16x16x32_bf16 v[106:109], v[222:225], v[204:207], v[78:81]
	v_mfma_f32_16x16x32_bf16 v[78:81], v[226:229], v[200:203], v[98:101]
	v_mfma_f32_16x16x32_bf16 v[98:101], v[230:233], v[204:207], v[78:81]
	s_setprio 0
	s_mov_b32 m0, s73
	v_lshl_add_u64 v[192:193], v[234:235], 0, s[22:23]
	s_barrier
	s_nop 2
	ds_read_b128 v[78:81], v175 offset:49152
	ds_read_b128 v[86:89], v175 offset:50176
	ds_read_b128 v[90:93], v175 offset:51200
	ds_read_b128 v[94:97], v175 offset:52224
	ds_read_b128 v[176:179], v175 offset:53248
	ds_read_b128 v[180:183], v175 offset:54272
	ds_read_b128 v[184:187], v175 offset:55296
	ds_read_b128 v[188:191], v175 offset:56320
	global_load_lds_dwordx4 v[192:193], off
	v_lshl_add_u64 v[192:193], v[236:237], 0, s[22:23]
	s_mov_b32 m0, s75
	s_nop 0
	global_load_lds_dwordx4 v[192:193], off
	s_barrier
	s_waitcnt lgkmcnt(0)
	s_setprio 1
	s_waitcnt lgkmcnt(0)
	v_mfma_f32_16x16x32_bf16 v[82:85], v[62:65], v[78:81], v[82:85]
	v_mfma_f32_16x16x32_bf16 v[54:57], v[70:73], v[78:81], v[54:57]
	v_mfma_f32_16x16x32_bf16 v[46:49], v[62:65], v[90:93], v[46:49]
	v_mfma_f32_16x16x32_bf16 v[38:41], v[70:73], v[90:93], v[38:41]
	v_mfma_f32_16x16x32_bf16 v[30:33], v[62:65], v[176:179], v[30:33]
	v_mfma_f32_16x16x32_bf16 v[22:25], v[70:73], v[176:179], v[22:25]
	v_mfma_f32_16x16x32_bf16 v[14:17], v[62:65], v[184:187], v[14:17]
	v_mfma_f32_16x16x32_bf16 v[6:9], v[70:73], v[184:187], v[6:9]
	v_mfma_f32_16x16x32_bf16 v[82:85], v[66:69], v[86:89], v[82:85]
	v_mfma_f32_16x16x32_bf16 v[54:57], v[74:77], v[86:89], v[54:57]
	v_mfma_f32_16x16x32_bf16 v[46:49], v[66:69], v[94:97], v[46:49]
	v_mfma_f32_16x16x32_bf16 v[38:41], v[74:77], v[94:97], v[38:41]
	v_mfma_f32_16x16x32_bf16 v[30:33], v[66:69], v[180:183], v[30:33]
	v_mfma_f32_16x16x32_bf16 v[22:25], v[74:77], v[180:183], v[22:25]
	v_mfma_f32_16x16x32_bf16 v[14:17], v[66:69], v[188:191], v[14:17]
	v_mfma_f32_16x16x32_bf16 v[6:9], v[74:77], v[188:191], v[6:9]
	s_setprio 0
	s_barrier
	s_add_u32 s36, s64, 0x40080
	s_addc_u32 s37, s65, 0
	s_add_i32 s64, s66, s68
	v_lshl_add_u64 v[62:63], s[36:37], 0, v[164:165]
	s_mov_b32 m0, s64
	s_nop 0
	global_load_lds_dwordx4 v[62:63], off
	v_lshl_add_u64 v[62:63], s[36:37], 0, v[162:163]
	s_add_i32 m0, s64, 0x2000
	s_nop 0
	global_load_lds_dwordx4 v[62:63], off
	s_waitcnt vmcnt(6)
	s_barrier
	s_setprio 1
	v_mfma_f32_16x16x32_bf16 v[58:61], v[208:211], v[78:81], v[58:61]
	v_mfma_f32_16x16x32_bf16 v[50:53], v[226:229], v[78:81], v[50:53]
	v_mfma_f32_16x16x32_bf16 v[42:45], v[208:211], v[90:93], v[42:45]
	v_mfma_f32_16x16x32_bf16 v[34:37], v[226:229], v[90:93], v[34:37]
	v_mfma_f32_16x16x32_bf16 v[26:29], v[208:211], v[176:179], v[26:29]
	v_mfma_f32_16x16x32_bf16 v[18:21], v[226:229], v[176:179], v[18:21]
	v_mfma_f32_16x16x32_bf16 v[10:13], v[208:211], v[184:187], v[10:13]
	v_mfma_f32_16x16x32_bf16 v[2:5], v[226:229], v[184:187], v[2:5]
	v_mfma_f32_16x16x32_bf16 v[74:77], v[222:225], v[86:89], v[58:61]
	v_mfma_f32_16x16x32_bf16 v[50:53], v[230:233], v[86:89], v[50:53]
	v_mfma_f32_16x16x32_bf16 v[42:45], v[222:225], v[94:97], v[42:45]
	v_mfma_f32_16x16x32_bf16 v[34:37], v[230:233], v[94:97], v[34:37]
	v_mfma_f32_16x16x32_bf16 v[26:29], v[222:225], v[180:183], v[26:29]
	v_mfma_f32_16x16x32_bf16 v[18:21], v[230:233], v[180:183], v[18:21]
	v_mfma_f32_16x16x32_bf16 v[10:13], v[222:225], v[188:191], v[10:13]
	v_mfma_f32_16x16x32_bf16 v[2:5], v[230:233], v[188:191], v[2:5]
	s_setprio 0
	s_add_i32 s83, s83, 2
	s_add_u32 s81, s81, 0x100
	s_addc_u32 s82, s82, 0
	s_cmp_gt_u32 s83, 13
	s_mov_b64 s[36:37], s[62:63]

.LBB0_1099:
	s_add_u32 s62, s36, 0x100
	s_addc_u32 s63, s37, 0
	s_add_i32 s84, 0, 0x10000
	v_add_u32_e32 v70, s84, v170
	ds_read_b128 v[58:61], v70
	ds_read_b128 v[62:65], v70 offset:1024
	ds_read_b128 v[66:69], v70 offset:2048
	ds_read_b128 v[70:73], v70 offset:3072
	s_cmp_eq_u32 s83, 12
	s_cselect_b32 s67, s59, s63
	s_cselect_b32 s66, s78, s62
	s_cselect_b32 s65, s79, s82
	s_cselect_b32 s64, s80, s81
	v_lshl_add_u64 v[192:193], s[36:37], 0, v[168:169]
	s_add_i32 m0, s69, 0xc000
	ds_read_b128 v[78:81], v175
	ds_read_b128 v[86:89], v175 offset:1024
	ds_read_b128 v[90:93], v175 offset:2048
	ds_read_b128 v[94:97], v175 offset:3072
	ds_read_b128 v[176:179], v175 offset:4096
	ds_read_b128 v[180:183], v175 offset:5120
	ds_read_b128 v[184:187], v175 offset:6144
	ds_read_b128 v[188:191], v175 offset:7168
	global_load_lds_dwordx4 v[192:193], off
	v_lshl_add_u64 v[192:193], s[36:37], 0, v[166:167]
	s_add_i32 m0, s69, 0xe000
	s_nop 0
	global_load_lds_dwordx4 v[192:193], off
	s_waitcnt lgkmcnt(8)
	s_barrier
	s_waitcnt lgkmcnt(0)
	s_setprio 1
	s_waitcnt lgkmcnt(0)
	v_mfma_f32_16x16x32_bf16 v[158:161], v[58:61], v[78:81], v[158:161]
	v_mfma_f32_16x16x32_bf16 v[150:153], v[66:69], v[78:81], v[150:153]
	v_mfma_f32_16x16x32_bf16 v[142:145], v[58:61], v[90:93], v[142:145]
	v_mfma_f32_16x16x32_bf16 v[134:137], v[66:69], v[90:93], v[134:137]
	v_mfma_f32_16x16x32_bf16 v[126:129], v[58:61], v[176:179], v[126:129]
	v_mfma_f32_16x16x32_bf16 v[118:121], v[66:69], v[176:179], v[118:121]
	v_mfma_f32_16x16x32_bf16 v[110:113], v[58:61], v[184:187], v[110:113]
	v_mfma_f32_16x16x32_bf16 v[102:105], v[66:69], v[184:187], v[102:105]
	v_mfma_f32_16x16x32_bf16 v[158:161], v[62:65], v[86:89], v[158:161]
	v_mfma_f32_16x16x32_bf16 v[150:153], v[70:73], v[86:89], v[150:153]
	v_mfma_f32_16x16x32_bf16 v[142:145], v[62:65], v[94:97], v[142:145]
	v_mfma_f32_16x16x32_bf16 v[134:137], v[70:73], v[94:97], v[134:137]
	v_mfma_f32_16x16x32_bf16 v[126:129], v[62:65], v[180:183], v[126:129]
	v_mfma_f32_16x16x32_bf16 v[118:121], v[70:73], v[180:183], v[118:121]
	v_mfma_f32_16x16x32_bf16 v[110:113], v[62:65], v[188:191], v[110:113]
	v_mfma_f32_16x16x32_bf16 v[102:105], v[70:73], v[188:191], v[102:105]
	s_setprio 0
	s_barrier
	s_add_i32 s85, 0, 0x14000
	v_add_u32_e32 v192, s85, v170
	s_add_i32 s36, s84, s68
	ds_read_b128 v[200:203], v192
	ds_read_b128 v[204:207], v192 offset:1024
	ds_read_b128 v[208:211], v192 offset:2048
	ds_read_b128 v[222:225], v192 offset:3072
	v_lshl_add_u64 v[192:193], s[64:65], 0, v[164:165]
	s_mov_b32 m0, s36
	v_lshl_add_u64 v[214:215], s[64:65], 0, v[162:163]
	global_load_lds_dwordx4 v[192:193], off
	s_add_i32 m0, s36, 0x2000
	s_nop 0
	global_load_lds_dwordx4 v[214:215], off
	s_barrier
	s_waitcnt lgkmcnt(0)
	s_setprio 1
	s_waitcnt lgkmcnt(0)
	v_mfma_f32_16x16x32_bf16 v[154:157], v[200:203], v[78:81], v[154:157]
	v_mfma_f32_16x16x32_bf16 v[78:81], v[208:211], v[78:81], v[146:149]
	v_mfma_f32_16x16x32_bf16 v[154:157], v[204:207], v[86:89], v[154:157]
	v_mfma_f32_16x16x32_bf16 v[78:81], v[222:225], v[86:89], v[78:81]
	v_mfma_f32_16x16x32_bf16 v[86:89], v[200:203], v[90:93], v[138:141]
	v_mfma_f32_16x16x32_bf16 v[90:93], v[208:211], v[90:93], v[130:133]
	v_mfma_f32_16x16x32_bf16 v[114:117], v[208:211], v[176:179], v[114:117]
	v_mfma_f32_16x16x32_bf16 v[106:109], v[200:203], v[184:187], v[106:109]
	v_mfma_f32_16x16x32_bf16 v[98:101], v[208:211], v[184:187], v[98:101]
	v_mfma_f32_16x16x32_bf16 v[86:89], v[204:207], v[94:97], v[86:89]
	v_mfma_f32_16x16x32_bf16 v[90:93], v[222:225], v[94:97], v[90:93]
	v_mfma_f32_16x16x32_bf16 v[94:97], v[200:203], v[176:179], v[122:125]
	v_mfma_f32_16x16x32_bf16 v[114:117], v[222:225], v[180:183], v[114:117]
	v_mfma_f32_16x16x32_bf16 v[106:109], v[204:207], v[188:191], v[106:109]
	v_mfma_f32_16x16x32_bf16 v[98:101], v[222:225], v[188:191], v[98:101]
	v_mfma_f32_16x16x32_bf16 v[94:97], v[204:207], v[180:183], v[94:97]
	s_setprio 0
	s_mov_b32 m0, s69
	v_lshl_add_u64 v[234:235], s[66:67], 0, v[164:165]
	s_barrier
	ds_read_b128 v[122:125], v175 offset:16384
	ds_read_b128 v[130:133], v175 offset:17408
	ds_read_b128 v[138:141], v175 offset:18432
	ds_read_b128 v[146:149], v175 offset:19456
	ds_read_b128 v[176:179], v175 offset:20480
	ds_read_b128 v[180:183], v175 offset:21504
	ds_read_b128 v[184:187], v175 offset:22528
	ds_read_b128 v[188:191], v175 offset:23552
	global_load_lds_dwordx4 v[234:235], off
	v_lshl_add_u64 v[236:237], s[66:67], 0, v[162:163]
	s_mov_b32 m0, s70
	s_nop 0
	global_load_lds_dwordx4 v[236:237], off
	s_barrier
	s_waitcnt lgkmcnt(0)
	s_setprio 1
	s_waitcnt lgkmcnt(0)
	v_mfma_f32_16x16x32_bf16 v[82:85], v[58:61], v[122:125], v[82:85]
	v_mfma_f32_16x16x32_bf16 v[54:57], v[66:69], v[122:125], v[54:57]
	v_mfma_f32_16x16x32_bf16 v[46:49], v[58:61], v[138:141], v[46:49]
	v_mfma_f32_16x16x32_bf16 v[38:41], v[66:69], v[138:141], v[38:41]
	v_mfma_f32_16x16x32_bf16 v[30:33], v[58:61], v[176:179], v[30:33]
	v_mfma_f32_16x16x32_bf16 v[22:25], v[66:69], v[176:179], v[22:25]
	v_mfma_f32_16x16x32_bf16 v[14:17], v[58:61], v[184:187], v[14:17]
	v_mfma_f32_16x16x32_bf16 v[6:9], v[66:69], v[184:187], v[6:9]
	v_mfma_f32_16x16x32_bf16 v[82:85], v[62:65], v[130:133], v[82:85]
	v_mfma_f32_16x16x32_bf16 v[54:57], v[70:73], v[130:133], v[54:57]
	v_mfma_f32_16x16x32_bf16 v[46:49], v[62:65], v[146:149], v[46:49]
	v_mfma_f32_16x16x32_bf16 v[38:41], v[70:73], v[146:149], v[38:41]
	v_mfma_f32_16x16x32_bf16 v[30:33], v[62:65], v[180:183], v[30:33]
	v_mfma_f32_16x16x32_bf16 v[22:25], v[70:73], v[180:183], v[22:25]
	v_mfma_f32_16x16x32_bf16 v[14:17], v[62:65], v[188:191], v[14:17]
	v_mfma_f32_16x16x32_bf16 v[6:9], v[70:73], v[188:191], v[6:9]
	s_setprio 0
	s_barrier
	s_add_u32 s36, s64, 0x40000
	s_addc_u32 s37, s65, 0
	s_add_i32 s84, s85, s68
	v_lshl_add_u64 v[58:59], s[36:37], 0, v[164:165]
	s_mov_b32 m0, s84
	s_nop 0
	global_load_lds_dwordx4 v[58:59], off
	v_lshl_add_u64 v[58:59], s[36:37], 0, v[162:163]
	s_add_i32 m0, s84, 0x2000
	s_nop 0
	global_load_lds_dwordx4 v[58:59], off
	s_waitcnt vmcnt(6)
	s_barrier
	s_setprio 1
	v_mfma_f32_16x16x32_bf16 v[50:53], v[208:211], v[122:125], v[50:53]
	v_mfma_f32_16x16x32_bf16 v[42:45], v[200:203], v[138:141], v[42:45]
	v_mfma_f32_16x16x32_bf16 v[34:37], v[208:211], v[138:141], v[34:37]
	v_mfma_f32_16x16x32_bf16 v[26:29], v[200:203], v[176:179], v[26:29]
	v_mfma_f32_16x16x32_bf16 v[18:21], v[208:211], v[176:179], v[18:21]
	v_mfma_f32_16x16x32_bf16 v[10:13], v[200:203], v[184:187], v[10:13]
	v_mfma_f32_16x16x32_bf16 v[2:5], v[208:211], v[184:187], v[2:5]
	v_mfma_f32_16x16x32_bf16 v[58:61], v[200:203], v[122:125], v[74:77]
	v_mfma_f32_16x16x32_bf16 v[50:53], v[222:225], v[130:133], v[50:53]
	v_mfma_f32_16x16x32_bf16 v[42:45], v[204:207], v[146:149], v[42:45]
	v_mfma_f32_16x16x32_bf16 v[34:37], v[222:225], v[146:149], v[34:37]
	v_mfma_f32_16x16x32_bf16 v[26:29], v[204:207], v[180:183], v[26:29]
	v_mfma_f32_16x16x32_bf16 v[18:21], v[222:225], v[180:183], v[18:21]
	v_mfma_f32_16x16x32_bf16 v[10:13], v[204:207], v[188:191], v[10:13]
	v_mfma_f32_16x16x32_bf16 v[2:5], v[222:225], v[188:191], v[2:5]
	v_mfma_f32_16x16x32_bf16 v[58:61], v[204:207], v[130:133], v[58:61]
	s_setprio 0
	s_add_i32 s84, 0, 0x18000
	v_add_u32_e32 v74, s84, v170
	s_barrier
	ds_read_b128 v[62:65], v74
	ds_read_b128 v[66:69], v74 offset:1024
	ds_read_b128 v[70:73], v74 offset:2048
	ds_read_b128 v[74:77], v74 offset:3072
	s_add_u32 s36, s66, 0x40000
	s_addc_u32 s37, s67, 0
	s_mov_b32 m0, s71
	v_lshl_add_u64 v[138:139], s[36:37], 0, v[164:165]
	ds_read_b128 v[122:125], v175 offset:32768
	ds_read_b128 v[130:133], v175 offset:33792
	ds_read_b128 v[176:179], v175 offset:34816
	ds_read_b128 v[180:183], v175 offset:35840
	ds_read_b128 v[184:187], v175 offset:36864
	ds_read_b128 v[188:191], v175 offset:37888
	ds_read_b128 v[200:203], v175 offset:38912
	ds_read_b128 v[204:207], v175 offset:39936
	global_load_lds_dwordx4 v[138:139], off
	v_lshl_add_u64 v[138:139], s[36:37], 0, v[162:163]
	s_mov_b32 m0, s72
	s_nop 0
	global_load_lds_dwordx4 v[138:139], off
	s_waitcnt lgkmcnt(8)
	s_barrier
	s_waitcnt lgkmcnt(0)
	s_setprio 1
	s_waitcnt lgkmcnt(0)
	v_mfma_f32_16x16x32_bf16 v[138:141], v[62:65], v[122:125], v[158:161]
	v_mfma_f32_16x16x32_bf16 v[158:161], v[66:69], v[130:133], v[138:141]
	v_mfma_f32_16x16x32_bf16 v[138:141], v[70:73], v[122:125], v[150:153]
	v_mfma_f32_16x16x32_bf16 v[150:153], v[74:77], v[130:133], v[138:141]
	v_mfma_f32_16x16x32_bf16 v[138:141], v[62:65], v[176:179], v[142:145]
	v_mfma_f32_16x16x32_bf16 v[134:137], v[70:73], v[176:179], v[134:137]
	v_mfma_f32_16x16x32_bf16 v[126:129], v[62:65], v[184:187], v[126:129]
	v_mfma_f32_16x16x32_bf16 v[118:121], v[70:73], v[184:187], v[118:121]
	v_mfma_f32_16x16x32_bf16 v[110:113], v[62:65], v[200:203], v[110:113]
	v_mfma_f32_16x16x32_bf16 v[102:105], v[70:73], v[200:203], v[102:105]
	v_mfma_f32_16x16x32_bf16 v[142:145], v[66:69], v[180:183], v[138:141]
	v_mfma_f32_16x16x32_bf16 v[134:137], v[74:77], v[180:183], v[134:137]
	v_mfma_f32_16x16x32_bf16 v[126:129], v[66:69], v[188:191], v[126:129]
	v_mfma_f32_16x16x32_bf16 v[118:121], v[74:77], v[188:191], v[118:121]
	v_mfma_f32_16x16x32_bf16 v[110:113], v[66:69], v[204:207], v[110:113]
	v_mfma_f32_16x16x32_bf16 v[102:105], v[74:77], v[204:207], v[102:105]
	s_setprio 0
	s_barrier
	s_add_i32 s66, 0, 0x1c000
	v_add_u32_e32 v138, s66, v170
	s_add_i32 s36, s84, s68
	ds_read_b128 v[208:211], v138
	ds_read_b128 v[222:225], v138 offset:1024
	ds_read_b128 v[226:229], v138 offset:2048
	ds_read_b128 v[230:233], v138 offset:3072
	v_lshl_add_u64 v[138:139], v[192:193], 0, s[22:23]
	s_mov_b32 m0, s36
	s_nop 0
	global_load_lds_dwordx4 v[138:139], off
	v_lshl_add_u64 v[138:139], v[214:215], 0, s[22:23]
	s_add_i32 m0, s36, 0x2000
	s_nop 0
	global_load_lds_dwordx4 v[138:139], off
	s_barrier
	s_waitcnt lgkmcnt(0)
	s_setprio 1
	s_waitcnt lgkmcnt(0)
	v_mfma_f32_16x16x32_bf16 v[78:81], v[226:229], v[122:125], v[78:81]
	v_mfma_f32_16x16x32_bf16 v[138:141], v[208:211], v[122:125], v[154:157]
	v_mfma_f32_16x16x32_bf16 v[146:149], v[230:233], v[130:133], v[78:81]
	v_mfma_f32_16x16x32_bf16 v[78:81], v[208:211], v[176:179], v[86:89]
	v_mfma_f32_16x16x32_bf16 v[154:157], v[222:225], v[130:133], v[138:141]
	v_mfma_f32_16x16x32_bf16 v[138:141], v[222:225], v[180:183], v[78:81]
	v_mfma_f32_16x16x32_bf16 v[78:81], v[226:229], v[176:179], v[90:93]
	v_mfma_f32_16x16x32_bf16 v[130:133], v[230:233], v[180:183], v[78:81]
	v_mfma_f32_16x16x32_bf16 v[78:81], v[208:211], v[184:187], v[94:97]
	v_mfma_f32_16x16x32_bf16 v[122:125], v[222:225], v[188:191], v[78:81]
	v_mfma_f32_16x16x32_bf16 v[78:81], v[226:229], v[184:187], v[114:117]
	v_mfma_f32_16x16x32_bf16 v[114:117], v[230:233], v[188:191], v[78:81]
	v_mfma_f32_16x16x32_bf16 v[78:81], v[208:211], v[200:203], v[106:109]
	v_mfma_f32_16x16x32_bf16 v[106:109], v[222:225], v[204:207], v[78:81]
	v_mfma_f32_16x16x32_bf16 v[78:81], v[226:229], v[200:203], v[98:101]
	v_mfma_f32_16x16x32_bf16 v[98:101], v[230:233], v[204:207], v[78:81]
	s_setprio 0
	s_mov_b32 m0, s73
	v_lshl_add_u64 v[192:193], v[234:235], 0, s[22:23]
	s_barrier
	s_nop 2
	ds_read_b128 v[78:81], v175 offset:49152
	ds_read_b128 v[86:89], v175 offset:50176
	ds_read_b128 v[90:93], v175 offset:51200
	ds_read_b128 v[94:97], v175 offset:52224
	ds_read_b128 v[176:179], v175 offset:53248
	ds_read_b128 v[180:183], v175 offset:54272
	ds_read_b128 v[184:187], v175 offset:55296
	ds_read_b128 v[188:191], v175 offset:56320
	global_load_lds_dwordx4 v[192:193], off
	v_lshl_add_u64 v[192:193], v[236:237], 0, s[22:23]
	s_mov_b32 m0, s75
	s_nop 0
	global_load_lds_dwordx4 v[192:193], off
	s_barrier
	s_waitcnt lgkmcnt(0)
	s_setprio 1
	s_waitcnt lgkmcnt(0)
	v_mfma_f32_16x16x32_bf16 v[82:85], v[62:65], v[78:81], v[82:85]
	v_mfma_f32_16x16x32_bf16 v[54:57], v[70:73], v[78:81], v[54:57]
	v_mfma_f32_16x16x32_bf16 v[46:49], v[62:65], v[90:93], v[46:49]
	v_mfma_f32_16x16x32_bf16 v[38:41], v[70:73], v[90:93], v[38:41]
	v_mfma_f32_16x16x32_bf16 v[30:33], v[62:65], v[176:179], v[30:33]
	v_mfma_f32_16x16x32_bf16 v[22:25], v[70:73], v[176:179], v[22:25]
	v_mfma_f32_16x16x32_bf16 v[14:17], v[62:65], v[184:187], v[14:17]
	v_mfma_f32_16x16x32_bf16 v[6:9], v[70:73], v[184:187], v[6:9]
	v_mfma_f32_16x16x32_bf16 v[82:85], v[66:69], v[86:89], v[82:85]
	v_mfma_f32_16x16x32_bf16 v[54:57], v[74:77], v[86:89], v[54:57]
	v_mfma_f32_16x16x32_bf16 v[46:49], v[66:69], v[94:97], v[46:49]
	v_mfma_f32_16x16x32_bf16 v[38:41], v[74:77], v[94:97], v[38:41]
	v_mfma_f32_16x16x32_bf16 v[30:33], v[66:69], v[180:183], v[30:33]
	v_mfma_f32_16x16x32_bf16 v[22:25], v[74:77], v[180:183], v[22:25]
	v_mfma_f32_16x16x32_bf16 v[14:17], v[66:69], v[188:191], v[14:17]
	v_mfma_f32_16x16x32_bf16 v[6:9], v[74:77], v[188:191], v[6:9]
	s_setprio 0
	s_barrier
	s_add_u32 s36, s64, 0x40080
	s_addc_u32 s37, s65, 0
	s_add_i32 s64, s66, s68
	v_lshl_add_u64 v[62:63], s[36:37], 0, v[164:165]
	s_mov_b32 m0, s64
	s_nop 0
	global_load_lds_dwordx4 v[62:63], off
	v_lshl_add_u64 v[62:63], s[36:37], 0, v[162:163]
	s_add_i32 m0, s64, 0x2000
	s_nop 0
	global_load_lds_dwordx4 v[62:63], off
	s_waitcnt vmcnt(6)
	s_barrier
	s_setprio 1
	v_mfma_f32_16x16x32_bf16 v[58:61], v[208:211], v[78:81], v[58:61]
	v_mfma_f32_16x16x32_bf16 v[50:53], v[226:229], v[78:81], v[50:53]
	v_mfma_f32_16x16x32_bf16 v[42:45], v[208:211], v[90:93], v[42:45]
	v_mfma_f32_16x16x32_bf16 v[34:37], v[226:229], v[90:93], v[34:37]
	v_mfma_f32_16x16x32_bf16 v[26:29], v[208:211], v[176:179], v[26:29]
	v_mfma_f32_16x16x32_bf16 v[18:21], v[226:229], v[176:179], v[18:21]
	v_mfma_f32_16x16x32_bf16 v[10:13], v[208:211], v[184:187], v[10:13]
	v_mfma_f32_16x16x32_bf16 v[2:5], v[226:229], v[184:187], v[2:5]
	v_mfma_f32_16x16x32_bf16 v[74:77], v[222:225], v[86:89], v[58:61]
	v_mfma_f32_16x16x32_bf16 v[50:53], v[230:233], v[86:89], v[50:53]
	v_mfma_f32_16x16x32_bf16 v[42:45], v[222:225], v[94:97], v[42:45]
	v_mfma_f32_16x16x32_bf16 v[34:37], v[230:233], v[94:97], v[34:37]
	v_mfma_f32_16x16x32_bf16 v[26:29], v[222:225], v[180:183], v[26:29]
	v_mfma_f32_16x16x32_bf16 v[18:21], v[230:233], v[180:183], v[18:21]
	v_mfma_f32_16x16x32_bf16 v[10:13], v[222:225], v[188:191], v[10:13]
	v_mfma_f32_16x16x32_bf16 v[2:5], v[230:233], v[188:191], v[2:5]
	s_setprio 0
	s_add_i32 s83, s83, 2
	s_add_u32 s81, s81, 0x100
	s_addc_u32 s82, s82, 0
	s_cmp_gt_u32 s83, 13
	s_mov_b64 s[36:37], s[62:63]
	s_cbranch_scc0 .Lrot_2
	s_barrier
	v_lshl_or_b32 v58, s27, 8, v174
	v_mov_b32_e32 v177, v1
	v_ashrrev_i32_e32 v59, 31, v58
	v_lshlrev_b64 v[58:59], 2, v[58:59]
	v_lshl_add_u64 v[66:67], s[46:47], 0, v[58:59]
	v_lshl_add_u64 v[70:71], s[48:49], 0, v[58:59]
	flat_load_dwordx4 v[86:89], v[66:67]
	flat_load_dwordx4 v[78:81], v[70:71]
	flat_load_dwordx4 v[62:65], v[66:67] offset:16
	flat_load_dwordx4 v[58:61], v[70:71] offset:16
	flat_load_dwordx4 v[94:97], v[66:67] offset:512
	flat_load_dwordx4 v[90:93], v[70:71] offset:512
	s_nop 0
	flat_load_dwordx4 v[66:69], v[66:67] offset:528
	s_nop 0
	flat_load_dwordx4 v[70:73], v[70:71] offset:528
	s_lshl_b32 s3, s3, 8
	v_lshl_or_b32 v176, s27, 7, v174
	v_add_u32_e32 v184, s3, v177
	v_lshl_add_u32 v177, v177, 3, s33
	s_waitcnt vmcnt(0)
	ds_read_b64 v[178:179], v177
	s_movk_i32 s27, 0xb00
	s_and_b64 vcc, exec, s[60:61]
	s_waitcnt lgkmcnt(0)
	v_xor_b32_e32 v89, 0x80000000, v89
	v_xor_b32_e32 v88, 0x80000000, v88
	v_pk_fma_f32 v[160:161], v[88:89], v[178:179], v[160:161] op_sel_hi:[1,0,1]
	v_pk_fma_f32 v[158:159], v[86:87], v[178:179], v[158:159] op_sel_hi:[1,0,1] neg_lo:[1,0,0] neg_hi:[1,0,0]
	v_pk_fma_f32 v[160:161], v[178:179], v[160:161], v[80:81] op_sel:[1,0,0]
	v_pk_fma_f32 v[158:159], v[178:179], v[158:159], v[78:79] op_sel:[1,0,0]
	v_pk_fma_f32 v[154:155], v[94:95], v[178:179], v[154:155] op_sel_hi:[1,0,1] neg_lo:[1,0,0] neg_hi:[1,0,0]
	v_mul_f32_e32 v182, 0xbfb8aa3b, v160
	v_pk_fma_f32 v[180:181], v[178:179], v[154:155], v[90:91] op_sel:[1,0,0]
	v_mul_f32_e32 v154, 0xbfb8aa3b, v158
	v_mul_f32_e32 v155, 0xbfb8aa3b, v159
	v_mul_f32_e32 v183, 0xbfb8aa3b, v161
	v_exp_f32_e32 v154, v154
	v_exp_f32_e32 v155, v155
	v_exp_f32_e32 v182, v182
	v_exp_f32_e32 v183, v183
	v_add_f32_e32 v154, 1.0, v154
	v_add_f32_e32 v155, 1.0, v155
	v_add_f32_e32 v182, 1.0, v182
	v_add_f32_e32 v183, 1.0, v183
	v_rcp_f32_e32 v154, v154
	v_rcp_f32_e32 v155, v155
	v_rcp_f32_e32 v182, v182
	v_rcp_f32_e32 v183, v183
	v_xor_b32_e32 v97, 0x80000000, v97
	v_xor_b32_e32 v96, 0x80000000, v96
	v_xor_b32_e32 v65, 0x80000000, v65
	v_xor_b32_e32 v64, 0x80000000, v64
	v_pk_fma_f32 v[156:157], v[96:97], v[178:179], v[156:157] op_sel_hi:[1,0,1]
	v_pk_fma_f32 v[152:153], v[64:65], v[178:179], v[152:153] op_sel_hi:[1,0,1]
	v_pk_fma_f32 v[150:151], v[62:63], v[178:179], v[150:151] op_sel_hi:[1,0,1] neg_lo:[1,0,0] neg_hi:[1,0,0]
	v_pk_fma_f32 v[156:157], v[178:179], v[156:157], v[92:93] op_sel:[1,0,0]
	v_pk_mul_f32 v[160:161], v[160:161], v[182:183]
	v_pk_mul_f32 v[158:159], v[158:159], v[154:155]
	v_pk_fma_f32 v[152:153], v[178:179], v[152:153], v[60:61] op_sel:[1,0,0]
	v_pk_fma_f32 v[150:151], v[178:179], v[150:151], v[58:59] op_sel:[1,0,0]
	v_pk_mul_f32 v[154:155], v[156:157], v[160:161]
	v_pk_mul_f32 v[156:157], v[180:181], v[158:159]
	v_mul_f32_e32 v158, 0xbfb8aa3b, v150
	v_mul_f32_e32 v159, 0xbfb8aa3b, v151
	v_mul_f32_e32 v160, 0xbfb8aa3b, v152
	v_mul_f32_e32 v161, 0xbfb8aa3b, v153
	v_exp_f32_e32 v158, v158
	v_exp_f32_e32 v159, v159
	v_exp_f32_e32 v160, v160
	v_exp_f32_e32 v161, v161
	v_add_f32_e32 v158, 1.0, v158
	v_add_f32_e32 v159, 1.0, v159
	v_add_f32_e32 v160, 1.0, v160
	v_add_f32_e32 v161, 1.0, v161
	v_rcp_f32_e32 v158, v158
	v_rcp_f32_e32 v159, v159
	v_rcp_f32_e32 v160, v160
	v_rcp_f32_e32 v161, v161
	v_xor_b32_e32 v69, 0x80000000, v69
	v_xor_b32_e32 v68, 0x80000000, v68
	v_pk_fma_f32 v[148:149], v[68:69], v[178:179], v[148:149] op_sel_hi:[1,0,1]
	v_pk_fma_f32 v[146:147], v[66:67], v[178:179], v[146:147] op_sel_hi:[1,0,1] neg_lo:[1,0,0] neg_hi:[1,0,0]
	v_pk_fma_f32 v[148:149], v[178:179], v[148:149], v[72:73] op_sel:[1,0,0]
	v_pk_fma_f32 v[146:147], v[178:179], v[146:147], v[70:71] op_sel:[1,0,0]
	v_pk_mul_f32 v[152:153], v[152:153], v[160:161]
	v_pk_mul_f32 v[150:151], v[150:151], v[158:159]
	v_mul_lo_u32 v158, v184, s27
	v_pk_mul_f32 v[152:153], v[148:149], v[152:153]
	v_pk_mul_f32 v[148:149], v[146:147], v[150:151]
	v_add_lshl_u32 v150, v158, v176, 1
	v_cvt_pk_bf16_f32 v146, v156, v157
	v_cvt_pk_bf16_f32 v147, v154, v155
	v_cvt_pk_bf16_f32 v148, v148, v149
	v_cvt_pk_bf16_f32 v149, v152, v153
	buffer_store_dwordx4 v[146:149], v150, s[28:31], 0 offen sc1
	ds_read_b64 v[146:147], v177 offset:128
	s_waitcnt lgkmcnt(0)
	v_pk_fma_f32 v[142:143], v[86:87], v[146:147], v[142:143] op_sel_hi:[1,0,1] neg_lo:[1,0,0] neg_hi:[1,0,0]
	s_nop 0
	v_pk_fma_f32 v[142:143], v[146:147], v[142:143], v[78:79] op_sel:[1,0,0]
	v_pk_fma_f32 v[144:145], v[88:89], v[146:147], v[144:145] op_sel_hi:[1,0,1]
	v_mul_f32_e32 v148, 0xbfb8aa3b, v142
	v_mul_f32_e32 v149, 0xbfb8aa3b, v143
	v_pk_fma_f32 v[144:145], v[146:147], v[144:145], v[80:81] op_sel:[1,0,0]
	v_exp_f32_e32 v148, v148
	v_exp_f32_e32 v149, v149
	v_mul_f32_e32 v150, 0xbfb8aa3b, v144
	v_mul_f32_e32 v151, 0xbfb8aa3b, v145
	v_exp_f32_e32 v150, v150
	v_exp_f32_e32 v151, v151
	v_add_f32_e32 v148, 1.0, v148
	v_add_f32_e32 v149, 1.0, v149
	v_rcp_f32_e32 v148, v148
	v_rcp_f32_e32 v149, v149
	v_add_f32_e32 v150, 1.0, v150
	v_add_f32_e32 v151, 1.0, v151
	v_rcp_f32_e32 v150, v150
	v_rcp_f32_e32 v151, v151
	v_pk_fma_f32 v[138:139], v[94:95], v[146:147], v[138:139] op_sel_hi:[1,0,1] neg_lo:[1,0,0] neg_hi:[1,0,0]
	v_pk_fma_f32 v[134:135], v[62:63], v[146:147], v[134:135] op_sel_hi:[1,0,1] neg_lo:[1,0,0] neg_hi:[1,0,0]
	v_pk_fma_f32 v[138:139], v[146:147], v[138:139], v[90:91] op_sel:[1,0,0]
	v_pk_mul_f32 v[142:143], v[142:143], v[148:149]
	v_pk_fma_f32 v[134:135], v[146:147], v[134:135], v[58:59] op_sel:[1,0,0]
	v_pk_fma_f32 v[140:141], v[96:97], v[146:147], v[140:141] op_sel_hi:[1,0,1]
	v_pk_mul_f32 v[138:139], v[138:139], v[142:143]
	v_pk_fma_f32 v[136:137], v[64:65], v[146:147], v[136:137] op_sel_hi:[1,0,1]
	v_mul_f32_e32 v142, 0xbfb8aa3b, v134
	v_mul_f32_e32 v143, 0xbfb8aa3b, v135
	v_pk_fma_f32 v[140:141], v[146:147], v[140:141], v[92:93] op_sel:[1,0,0]
	v_pk_mul_f32 v[144:145], v[144:145], v[150:151]
	v_pk_fma_f32 v[136:137], v[146:147], v[136:137], v[60:61] op_sel:[1,0,0]
	v_exp_f32_e32 v142, v142
	v_exp_f32_e32 v143, v143
	v_pk_mul_f32 v[140:141], v[140:141], v[144:145]
	v_mul_f32_e32 v144, 0xbfb8aa3b, v136
	v_mul_f32_e32 v145, 0xbfb8aa3b, v137
	v_exp_f32_e32 v144, v144
	v_exp_f32_e32 v145, v145
	v_add_f32_e32 v142, 1.0, v142
	v_add_f32_e32 v143, 1.0, v143
	v_rcp_f32_e32 v142, v142
	v_rcp_f32_e32 v143, v143
	v_add_f32_e32 v144, 1.0, v144
	v_add_f32_e32 v145, 1.0, v145
	v_rcp_f32_e32 v144, v144
	v_rcp_f32_e32 v145, v145
	v_pk_fma_f32 v[130:131], v[66:67], v[146:147], v[130:131] op_sel_hi:[1,0,1] neg_lo:[1,0,0] neg_hi:[1,0,0]
	v_pk_mul_f32 v[134:135], v[134:135], v[142:143]
	v_pk_fma_f32 v[130:131], v[146:147], v[130:131], v[70:71] op_sel:[1,0,0]
	v_pk_fma_f32 v[132:133], v[68:69], v[146:147], v[132:133] op_sel_hi:[1,0,1]
	v_pk_mul_f32 v[134:135], v[130:131], v[134:135]
	v_add_u32_e32 v130, 0xb000, v176
	v_pk_fma_f32 v[132:133], v[146:147], v[132:133], v[72:73] op_sel:[1,0,0]
	v_pk_mul_f32 v[136:137], v[136:137], v[144:145]
	v_add_lshl_u32 v131, v158, v130, 1
	v_pk_mul_f32 v[136:137], v[132:133], v[136:137]
	v_cvt_pk_bf16_f32 v132, v138, v139
	v_cvt_pk_bf16_f32 v133, v140, v141
	v_cvt_pk_bf16_f32 v134, v134, v135
	s_nop 0
	v_cvt_pk_bf16_f32 v135, v136, v137
	buffer_store_dwordx4 v[132:135], v131, s[28:31], 0 offen sc1
	v_mov_b32_e32 v131, v171
	s_nop 0
	v_add_u32_e32 v138, s3, v131
	v_lshl_add_u32 v131, v131, 3, s33
	ds_read_b64 v[132:133], v131
	s_waitcnt lgkmcnt(0)
	v_pk_fma_f32 v[128:129], v[88:89], v[132:133], v[128:129] op_sel_hi:[1,0,1]
	v_pk_fma_f32 v[126:127], v[86:87], v[132:133], v[126:127] op_sel_hi:[1,0,1] neg_lo:[1,0,0] neg_hi:[1,0,0]
	v_pk_fma_f32 v[128:129], v[132:133], v[128:129], v[80:81] op_sel:[1,0,0]
	v_pk_fma_f32 v[126:127], v[132:133], v[126:127], v[78:79] op_sel:[1,0,0]
	v_mul_f32_e32 v136, 0xbfb8aa3b, v128
	v_mul_f32_e32 v134, 0xbfb8aa3b, v126
	v_mul_f32_e32 v135, 0xbfb8aa3b, v127
	v_mul_f32_e32 v137, 0xbfb8aa3b, v129
	v_exp_f32_e32 v134, v134
	v_exp_f32_e32 v135, v135
	v_exp_f32_e32 v136, v136
	v_exp_f32_e32 v137, v137
	v_add_f32_e32 v134, 1.0, v134
	v_add_f32_e32 v135, 1.0, v135
	v_add_f32_e32 v136, 1.0, v136
	v_add_f32_e32 v137, 1.0, v137
	v_rcp_f32_e32 v134, v134
	v_rcp_f32_e32 v135, v135
	v_rcp_f32_e32 v136, v136
	v_rcp_f32_e32 v137, v137
	v_pk_fma_f32 v[124:125], v[96:97], v[132:133], v[124:125] op_sel_hi:[1,0,1]
	v_pk_fma_f32 v[122:123], v[94:95], v[132:133], v[122:123] op_sel_hi:[1,0,1] neg_lo:[1,0,0] neg_hi:[1,0,0]
	v_pk_fma_f32 v[120:121], v[64:65], v[132:133], v[120:121] op_sel_hi:[1,0,1]
	v_pk_fma_f32 v[118:119], v[62:63], v[132:133], v[118:119] op_sel_hi:[1,0,1] neg_lo:[1,0,0] neg_hi:[1,0,0]
	v_pk_fma_f32 v[124:125], v[132:133], v[124:125], v[92:93] op_sel:[1,0,0]
	v_pk_fma_f32 v[122:123], v[132:133], v[122:123], v[90:91] op_sel:[1,0,0]
	v_pk_mul_f32 v[128:129], v[128:129], v[136:137]
	v_pk_mul_f32 v[126:127], v[126:127], v[134:135]
	v_pk_fma_f32 v[120:121], v[132:133], v[120:121], v[60:61] op_sel:[1,0,0]
	v_pk_fma_f32 v[118:119], v[132:133], v[118:119], v[58:59] op_sel:[1,0,0]
	v_pk_mul_f32 v[124:125], v[124:125], v[128:129]
	v_pk_mul_f32 v[122:123], v[122:123], v[126:127]
	v_mul_f32_e32 v126, 0xbfb8aa3b, v118
	v_mul_f32_e32 v127, 0xbfb8aa3b, v119
	v_mul_f32_e32 v128, 0xbfb8aa3b, v120
	v_mul_f32_e32 v129, 0xbfb8aa3b, v121
	v_exp_f32_e32 v126, v126
	v_exp_f32_e32 v127, v127
	v_exp_f32_e32 v128, v128
	v_exp_f32_e32 v129, v129
	v_add_f32_e32 v126, 1.0, v126
	v_add_f32_e32 v127, 1.0, v127
	v_add_f32_e32 v128, 1.0, v128
	v_add_f32_e32 v129, 1.0, v129
	v_rcp_f32_e32 v126, v126
	v_rcp_f32_e32 v127, v127
	v_rcp_f32_e32 v128, v128
	v_rcp_f32_e32 v129, v129
	v_pk_fma_f32 v[116:117], v[68:69], v[132:133], v[116:117] op_sel_hi:[1,0,1]
	v_pk_fma_f32 v[114:115], v[66:67], v[132:133], v[114:115] op_sel_hi:[1,0,1] neg_lo:[1,0,0] neg_hi:[1,0,0]
	v_pk_fma_f32 v[116:117], v[132:133], v[116:117], v[72:73] op_sel:[1,0,0]
	v_pk_fma_f32 v[114:115], v[132:133], v[114:115], v[70:71] op_sel:[1,0,0]
	v_pk_mul_f32 v[120:121], v[120:121], v[128:129]
	v_pk_mul_f32 v[118:119], v[118:119], v[126:127]
	v_mul_lo_u32 v126, v138, s27
	v_pk_mul_f32 v[120:121], v[116:117], v[120:121]
	v_pk_mul_f32 v[116:117], v[114:115], v[118:119]
	v_add_lshl_u32 v118, v126, v176, 1
	v_cvt_pk_bf16_f32 v114, v122, v123
	v_cvt_pk_bf16_f32 v115, v124, v125
	v_cvt_pk_bf16_f32 v116, v116, v117
	v_cvt_pk_bf16_f32 v117, v120, v121
	buffer_store_dwordx4 v[114:117], v118, s[28:31], 0 offen sc1
	ds_read_b64 v[114:115], v131 offset:128
	s_waitcnt lgkmcnt(0)
	v_pk_fma_f32 v[112:113], v[88:89], v[114:115], v[112:113] op_sel_hi:[1,0,1]
	v_pk_fma_f32 v[110:111], v[86:87], v[114:115], v[110:111] op_sel_hi:[1,0,1] neg_lo:[1,0,0] neg_hi:[1,0,0]
	v_pk_fma_f32 v[112:113], v[114:115], v[112:113], v[80:81] op_sel:[1,0,0]
	v_pk_fma_f32 v[110:111], v[114:115], v[110:111], v[78:79] op_sel:[1,0,0]
	v_mul_f32_e32 v118, 0xbfb8aa3b, v112
	v_mul_f32_e32 v116, 0xbfb8aa3b, v110
	v_mul_f32_e32 v117, 0xbfb8aa3b, v111
	v_mul_f32_e32 v119, 0xbfb8aa3b, v113
	v_exp_f32_e32 v116, v116
	v_exp_f32_e32 v117, v117
	v_exp_f32_e32 v118, v118
	v_exp_f32_e32 v119, v119
	v_add_f32_e32 v116, 1.0, v116
	v_add_f32_e32 v117, 1.0, v117
	v_add_f32_e32 v118, 1.0, v118
	v_add_f32_e32 v119, 1.0, v119
	v_rcp_f32_e32 v116, v116
	v_rcp_f32_e32 v117, v117
	v_rcp_f32_e32 v118, v118
	v_rcp_f32_e32 v119, v119
	v_pk_fma_f32 v[108:109], v[96:97], v[114:115], v[108:109] op_sel_hi:[1,0,1]
	v_pk_fma_f32 v[106:107], v[94:95], v[114:115], v[106:107] op_sel_hi:[1,0,1] neg_lo:[1,0,0] neg_hi:[1,0,0]
	v_pk_fma_f32 v[104:105], v[64:65], v[114:115], v[104:105] op_sel_hi:[1,0,1]
	v_pk_fma_f32 v[102:103], v[62:63], v[114:115], v[102:103] op_sel_hi:[1,0,1] neg_lo:[1,0,0] neg_hi:[1,0,0]
	v_pk_fma_f32 v[108:109], v[114:115], v[108:109], v[92:93] op_sel:[1,0,0]
	v_pk_fma_f32 v[106:107], v[114:115], v[106:107], v[90:91] op_sel:[1,0,0]
	v_pk_mul_f32 v[112:113], v[112:113], v[118:119]
	v_pk_mul_f32 v[110:111], v[110:111], v[116:117]
	v_pk_fma_f32 v[104:105], v[114:115], v[104:105], v[60:61] op_sel:[1,0,0]
	v_pk_fma_f32 v[102:103], v[114:115], v[102:103], v[58:59] op_sel:[1,0,0]
	v_pk_mul_f32 v[108:109], v[108:109], v[112:113]
	v_pk_mul_f32 v[106:107], v[106:107], v[110:111]
	v_mul_f32_e32 v110, 0xbfb8aa3b, v102
	v_mul_f32_e32 v111, 0xbfb8aa3b, v103
	v_mul_f32_e32 v112, 0xbfb8aa3b, v104
	v_mul_f32_e32 v113, 0xbfb8aa3b, v105
	v_exp_f32_e32 v110, v110
	v_exp_f32_e32 v111, v111
	v_exp_f32_e32 v112, v112
	v_exp_f32_e32 v113, v113
	v_add_f32_e32 v110, 1.0, v110
	v_add_f32_e32 v111, 1.0, v111
	v_add_f32_e32 v112, 1.0, v112
	v_add_f32_e32 v113, 1.0, v113
	v_rcp_f32_e32 v110, v110
	v_rcp_f32_e32 v111, v111
	v_rcp_f32_e32 v112, v112
	v_rcp_f32_e32 v113, v113
	v_pk_fma_f32 v[100:101], v[68:69], v[114:115], v[100:101] op_sel_hi:[1,0,1]
	v_pk_fma_f32 v[98:99], v[66:67], v[114:115], v[98:99] op_sel_hi:[1,0,1] neg_lo:[1,0,0] neg_hi:[1,0,0]
	v_pk_fma_f32 v[100:101], v[114:115], v[100:101], v[72:73] op_sel:[1,0,0]
	v_pk_fma_f32 v[98:99], v[114:115], v[98:99], v[70:71] op_sel:[1,0,0]
	v_pk_mul_f32 v[104:105], v[104:105], v[112:113]
	v_pk_mul_f32 v[102:103], v[102:103], v[110:111]
	v_pk_mul_f32 v[104:105], v[100:101], v[104:105]
	v_pk_mul_f32 v[100:101], v[98:99], v[102:103]
	v_add_lshl_u32 v102, v126, v130, 1
	v_cvt_pk_bf16_f32 v98, v106, v107
	v_cvt_pk_bf16_f32 v99, v108, v109
	v_cvt_pk_bf16_f32 v100, v100, v101
	v_cvt_pk_bf16_f32 v101, v104, v105
	buffer_store_dwordx4 v[98:101], v102, s[28:31], 0 offen sc1
	s_nop 1
	v_mov_b32_e32 v98, v172
	s_nop 0
	v_lshl_add_u32 v105, v98, 3, s33
	v_add_u32_e32 v104, s3, v98
	ds_read_b64 v[98:99], v105
	s_waitcnt lgkmcnt(0)
	v_pk_fma_f32 v[84:85], v[88:89], v[98:99], v[84:85] op_sel_hi:[1,0,1]
	v_pk_fma_f32 v[82:83], v[86:87], v[98:99], v[82:83] op_sel_hi:[1,0,1] neg_lo:[1,0,0] neg_hi:[1,0,0]
	v_pk_fma_f32 v[84:85], v[98:99], v[84:85], v[80:81] op_sel:[1,0,0]
	v_pk_fma_f32 v[82:83], v[98:99], v[82:83], v[78:79] op_sel:[1,0,0]
	v_mul_f32_e32 v102, 0xbfb8aa3b, v84
	v_mul_f32_e32 v100, 0xbfb8aa3b, v82
	v_mul_f32_e32 v101, 0xbfb8aa3b, v83
	v_mul_f32_e32 v103, 0xbfb8aa3b, v85
	v_exp_f32_e32 v100, v100
	v_exp_f32_e32 v101, v101
	v_exp_f32_e32 v102, v102
	v_exp_f32_e32 v103, v103
	v_add_f32_e32 v100, 1.0, v100
	v_add_f32_e32 v101, 1.0, v101
	v_add_f32_e32 v102, 1.0, v102
	v_add_f32_e32 v103, 1.0, v103
	v_rcp_f32_e32 v100, v100
	v_rcp_f32_e32 v101, v101
	v_rcp_f32_e32 v102, v102
	v_rcp_f32_e32 v103, v103
	v_pk_fma_f32 v[76:77], v[96:97], v[98:99], v[76:77] op_sel_hi:[1,0,1]
	v_pk_fma_f32 v[74:75], v[94:95], v[98:99], v[74:75] op_sel_hi:[1,0,1] neg_lo:[1,0,0] neg_hi:[1,0,0]
	v_pk_fma_f32 v[56:57], v[64:65], v[98:99], v[56:57] op_sel_hi:[1,0,1]
	v_pk_fma_f32 v[54:55], v[62:63], v[98:99], v[54:55] op_sel_hi:[1,0,1] neg_lo:[1,0,0] neg_hi:[1,0,0]
	v_pk_fma_f32 v[76:77], v[98:99], v[76:77], v[92:93] op_sel:[1,0,0]
	v_pk_fma_f32 v[74:75], v[98:99], v[74:75], v[90:91] op_sel:[1,0,0]
	v_pk_mul_f32 v[84:85], v[84:85], v[102:103]
	v_pk_mul_f32 v[82:83], v[82:83], v[100:101]
	v_pk_fma_f32 v[56:57], v[98:99], v[56:57], v[60:61] op_sel:[1,0,0]
	v_pk_fma_f32 v[54:55], v[98:99], v[54:55], v[58:59] op_sel:[1,0,0]
	v_pk_mul_f32 v[76:77], v[76:77], v[84:85]
	v_pk_mul_f32 v[74:75], v[74:75], v[82:83]
	v_mul_f32_e32 v82, 0xbfb8aa3b, v54
	v_mul_f32_e32 v83, 0xbfb8aa3b, v55
	v_mul_f32_e32 v84, 0xbfb8aa3b, v56
	v_mul_f32_e32 v85, 0xbfb8aa3b, v57
	v_exp_f32_e32 v82, v82
	v_exp_f32_e32 v83, v83
	v_exp_f32_e32 v84, v84
	v_exp_f32_e32 v85, v85
	v_add_f32_e32 v82, 1.0, v82
	v_add_f32_e32 v83, 1.0, v83
	v_add_f32_e32 v84, 1.0, v84
	v_add_f32_e32 v85, 1.0, v85
	v_rcp_f32_e32 v82, v82
	v_rcp_f32_e32 v83, v83
	v_rcp_f32_e32 v84, v84
	v_rcp_f32_e32 v85, v85
	v_pk_fma_f32 v[52:53], v[68:69], v[98:99], v[52:53] op_sel_hi:[1,0,1]
	v_pk_fma_f32 v[50:51], v[66:67], v[98:99], v[50:51] op_sel_hi:[1,0,1] neg_lo:[1,0,0] neg_hi:[1,0,0]
	v_pk_fma_f32 v[52:53], v[98:99], v[52:53], v[72:73] op_sel:[1,0,0]
	v_pk_fma_f32 v[50:51], v[98:99], v[50:51], v[70:71] op_sel:[1,0,0]
	v_pk_mul_f32 v[56:57], v[56:57], v[84:85]
	v_pk_mul_f32 v[54:55], v[54:55], v[82:83]
	v_mul_lo_u32 v82, v104, s27
	v_pk_mul_f32 v[56:57], v[52:53], v[56:57]
	v_pk_mul_f32 v[52:53], v[50:51], v[54:55]
	v_add_lshl_u32 v54, v82, v176, 1
	v_cvt_pk_bf16_f32 v50, v74, v75
	v_cvt_pk_bf16_f32 v51, v76, v77
	v_cvt_pk_bf16_f32 v52, v52, v53
	v_cvt_pk_bf16_f32 v53, v56, v57
	buffer_store_dwordx4 v[50:53], v54, s[28:31], 0 offen sc1
	ds_read_b64 v[50:51], v105 offset:128
	s_waitcnt lgkmcnt(0)
	v_pk_fma_f32 v[48:49], v[88:89], v[50:51], v[48:49] op_sel_hi:[1,0,1]
	v_pk_fma_f32 v[46:47], v[86:87], v[50:51], v[46:47] op_sel_hi:[1,0,1] neg_lo:[1,0,0] neg_hi:[1,0,0]
	v_pk_fma_f32 v[48:49], v[50:51], v[48:49], v[80:81] op_sel:[1,0,0]
	v_pk_fma_f32 v[46:47], v[50:51], v[46:47], v[78:79] op_sel:[1,0,0]
	v_mul_f32_e32 v54, 0xbfb8aa3b, v48
	v_mul_f32_e32 v52, 0xbfb8aa3b, v46
	v_mul_f32_e32 v53, 0xbfb8aa3b, v47
	v_mul_f32_e32 v55, 0xbfb8aa3b, v49
	v_exp_f32_e32 v52, v52
	v_exp_f32_e32 v53, v53
	v_exp_f32_e32 v54, v54
	v_exp_f32_e32 v55, v55
	v_add_f32_e32 v52, 1.0, v52
	v_add_f32_e32 v53, 1.0, v53
	v_add_f32_e32 v54, 1.0, v54
	v_add_f32_e32 v55, 1.0, v55
	v_rcp_f32_e32 v52, v52
	v_rcp_f32_e32 v53, v53
	v_rcp_f32_e32 v54, v54
	v_rcp_f32_e32 v55, v55
	v_pk_fma_f32 v[44:45], v[96:97], v[50:51], v[44:45] op_sel_hi:[1,0,1]
	v_pk_fma_f32 v[42:43], v[94:95], v[50:51], v[42:43] op_sel_hi:[1,0,1] neg_lo:[1,0,0] neg_hi:[1,0,0]
	v_pk_fma_f32 v[40:41], v[64:65], v[50:51], v[40:41] op_sel_hi:[1,0,1]
	v_pk_fma_f32 v[38:39], v[62:63], v[50:51], v[38:39] op_sel_hi:[1,0,1] neg_lo:[1,0,0] neg_hi:[1,0,0]
	v_pk_fma_f32 v[44:45], v[50:51], v[44:45], v[92:93] op_sel:[1,0,0]
	v_pk_fma_f32 v[42:43], v[50:51], v[42:43], v[90:91] op_sel:[1,0,0]
	v_pk_mul_f32 v[48:49], v[48:49], v[54:55]
	v_pk_mul_f32 v[46:47], v[46:47], v[52:53]
	v_pk_fma_f32 v[40:41], v[50:51], v[40:41], v[60:61] op_sel:[1,0,0]
	v_pk_fma_f32 v[38:39], v[50:51], v[38:39], v[58:59] op_sel:[1,0,0]
	v_pk_mul_f32 v[44:45], v[44:45], v[48:49]
	v_pk_mul_f32 v[42:43], v[42:43], v[46:47]
	v_mul_f32_e32 v46, 0xbfb8aa3b, v38
	v_mul_f32_e32 v47, 0xbfb8aa3b, v39
	v_mul_f32_e32 v48, 0xbfb8aa3b, v40
	v_mul_f32_e32 v49, 0xbfb8aa3b, v41
	v_exp_f32_e32 v46, v46
	v_exp_f32_e32 v47, v47
	v_exp_f32_e32 v48, v48
	v_exp_f32_e32 v49, v49
	v_add_f32_e32 v46, 1.0, v46
	v_add_f32_e32 v47, 1.0, v47
	v_add_f32_e32 v48, 1.0, v48
	v_add_f32_e32 v49, 1.0, v49
	v_rcp_f32_e32 v46, v46
	v_rcp_f32_e32 v47, v47
	v_rcp_f32_e32 v48, v48
	v_rcp_f32_e32 v49, v49
	v_pk_fma_f32 v[36:37], v[68:69], v[50:51], v[36:37] op_sel_hi:[1,0,1]
	v_pk_fma_f32 v[34:35], v[66:67], v[50:51], v[34:35] op_sel_hi:[1,0,1] neg_lo:[1,0,0] neg_hi:[1,0,0]
	v_pk_fma_f32 v[36:37], v[50:51], v[36:37], v[72:73] op_sel:[1,0,0]
	v_pk_fma_f32 v[34:35], v[50:51], v[34:35], v[70:71] op_sel:[1,0,0]
	v_pk_mul_f32 v[40:41], v[40:41], v[48:49]
	v_pk_mul_f32 v[38:39], v[38:39], v[46:47]
	v_pk_mul_f32 v[40:41], v[36:37], v[40:41]
	v_pk_mul_f32 v[36:37], v[34:35], v[38:39]
	v_add_lshl_u32 v38, v82, v130, 1
	v_cvt_pk_bf16_f32 v34, v42, v43
	v_cvt_pk_bf16_f32 v35, v44, v45
	v_cvt_pk_bf16_f32 v36, v36, v37
	v_cvt_pk_bf16_f32 v37, v40, v41
	buffer_store_dwordx4 v[34:37], v38, s[28:31], 0 offen sc1
	s_nop 1
	v_mov_b32_e32 v34, v173
	s_nop 0
	v_lshl_add_u32 v41, v34, 3, s33
	v_add_u32_e32 v40, s3, v34
	ds_read_b64 v[34:35], v41
	s_mov_b32 s3, s77
	s_waitcnt lgkmcnt(0)
	v_pk_fma_f32 v[32:33], v[88:89], v[34:35], v[32:33] op_sel_hi:[1,0,1]
	v_pk_fma_f32 v[30:31], v[86:87], v[34:35], v[30:31] op_sel_hi:[1,0,1] neg_lo:[1,0,0] neg_hi:[1,0,0]
	v_pk_fma_f32 v[32:33], v[34:35], v[32:33], v[80:81] op_sel:[1,0,0]
	v_pk_fma_f32 v[30:31], v[34:35], v[30:31], v[78:79] op_sel:[1,0,0]
	v_mul_f32_e32 v38, 0xbfb8aa3b, v32
	v_mul_f32_e32 v36, 0xbfb8aa3b, v30
	v_mul_f32_e32 v37, 0xbfb8aa3b, v31
	v_mul_f32_e32 v39, 0xbfb8aa3b, v33
	v_exp_f32_e32 v36, v36
	v_exp_f32_e32 v37, v37
	v_exp_f32_e32 v38, v38
	v_exp_f32_e32 v39, v39
	v_add_f32_e32 v36, 1.0, v36
	v_add_f32_e32 v37, 1.0, v37
	v_add_f32_e32 v38, 1.0, v38
	v_add_f32_e32 v39, 1.0, v39
	v_rcp_f32_e32 v36, v36
	v_rcp_f32_e32 v37, v37
	v_rcp_f32_e32 v38, v38
	v_rcp_f32_e32 v39, v39
	v_pk_fma_f32 v[28:29], v[96:97], v[34:35], v[28:29] op_sel_hi:[1,0,1]
	v_pk_fma_f32 v[26:27], v[94:95], v[34:35], v[26:27] op_sel_hi:[1,0,1] neg_lo:[1,0,0] neg_hi:[1,0,0]
	v_pk_fma_f32 v[24:25], v[64:65], v[34:35], v[24:25] op_sel_hi:[1,0,1]
	v_pk_fma_f32 v[22:23], v[62:63], v[34:35], v[22:23] op_sel_hi:[1,0,1] neg_lo:[1,0,0] neg_hi:[1,0,0]
	v_pk_fma_f32 v[28:29], v[34:35], v[28:29], v[92:93] op_sel:[1,0,0]
	v_pk_fma_f32 v[26:27], v[34:35], v[26:27], v[90:91] op_sel:[1,0,0]
	v_pk_mul_f32 v[32:33], v[32:33], v[38:39]
	v_pk_mul_f32 v[30:31], v[30:31], v[36:37]
	v_pk_fma_f32 v[24:25], v[34:35], v[24:25], v[60:61] op_sel:[1,0,0]
	v_pk_fma_f32 v[22:23], v[34:35], v[22:23], v[58:59] op_sel:[1,0,0]
	v_pk_mul_f32 v[28:29], v[28:29], v[32:33]
	v_pk_mul_f32 v[26:27], v[26:27], v[30:31]
	v_mul_f32_e32 v30, 0xbfb8aa3b, v22
	v_mul_f32_e32 v31, 0xbfb8aa3b, v23
	v_mul_f32_e32 v32, 0xbfb8aa3b, v24
	v_mul_f32_e32 v33, 0xbfb8aa3b, v25
	v_exp_f32_e32 v30, v30
	v_exp_f32_e32 v31, v31
	v_exp_f32_e32 v32, v32
	v_exp_f32_e32 v33, v33
	v_add_f32_e32 v30, 1.0, v30
	v_add_f32_e32 v31, 1.0, v31
	v_add_f32_e32 v32, 1.0, v32
	v_add_f32_e32 v33, 1.0, v33
	v_rcp_f32_e32 v30, v30
	v_rcp_f32_e32 v31, v31
	v_rcp_f32_e32 v32, v32
	v_rcp_f32_e32 v33, v33
	v_pk_fma_f32 v[20:21], v[68:69], v[34:35], v[20:21] op_sel_hi:[1,0,1]
	v_pk_fma_f32 v[18:19], v[66:67], v[34:35], v[18:19] op_sel_hi:[1,0,1] neg_lo:[1,0,0] neg_hi:[1,0,0]
	v_pk_fma_f32 v[20:21], v[34:35], v[20:21], v[72:73] op_sel:[1,0,0]
	v_pk_fma_f32 v[18:19], v[34:35], v[18:19], v[70:71] op_sel:[1,0,0]
	v_pk_mul_f32 v[24:25], v[24:25], v[32:33]
	v_pk_mul_f32 v[22:23], v[22:23], v[30:31]
	v_mul_lo_u32 v30, v40, s27
	v_pk_mul_f32 v[24:25], v[20:21], v[24:25]
	v_pk_mul_f32 v[20:21], v[18:19], v[22:23]
	v_add_lshl_u32 v22, v30, v176, 1
	v_cvt_pk_bf16_f32 v18, v26, v27
	v_cvt_pk_bf16_f32 v19, v28, v29
	v_cvt_pk_bf16_f32 v20, v20, v21
	v_cvt_pk_bf16_f32 v21, v24, v25
	buffer_store_dwordx4 v[18:21], v22, s[28:31], 0 offen sc1
	ds_read_b64 v[18:19], v41 offset:128
	s_mov_b32 s27, s58
	s_waitcnt lgkmcnt(0)
	v_pk_fma_f32 v[16:17], v[88:89], v[18:19], v[16:17] op_sel_hi:[1,0,1]
	v_pk_fma_f32 v[14:15], v[86:87], v[18:19], v[14:15] op_sel_hi:[1,0,1] neg_lo:[1,0,0] neg_hi:[1,0,0]
	v_pk_fma_f32 v[16:17], v[18:19], v[16:17], v[80:81] op_sel:[1,0,0]
	v_pk_fma_f32 v[14:15], v[18:19], v[14:15], v[78:79] op_sel:[1,0,0]
	v_mul_f32_e32 v22, 0xbfb8aa3b, v16
	v_mul_f32_e32 v20, 0xbfb8aa3b, v14
	v_mul_f32_e32 v21, 0xbfb8aa3b, v15
	v_mul_f32_e32 v23, 0xbfb8aa3b, v17
	v_exp_f32_e32 v20, v20
	v_exp_f32_e32 v21, v21
	v_exp_f32_e32 v22, v22
	v_exp_f32_e32 v23, v23
	v_add_f32_e32 v20, 1.0, v20
	v_add_f32_e32 v21, 1.0, v21
	v_add_f32_e32 v22, 1.0, v22
	v_add_f32_e32 v23, 1.0, v23
	v_rcp_f32_e32 v20, v20
	v_rcp_f32_e32 v21, v21
	v_rcp_f32_e32 v22, v22
	v_rcp_f32_e32 v23, v23
	v_pk_fma_f32 v[12:13], v[96:97], v[18:19], v[12:13] op_sel_hi:[1,0,1]
	v_pk_fma_f32 v[10:11], v[94:95], v[18:19], v[10:11] op_sel_hi:[1,0,1] neg_lo:[1,0,0] neg_hi:[1,0,0]
	v_pk_fma_f32 v[8:9], v[64:65], v[18:19], v[8:9] op_sel_hi:[1,0,1]
	v_pk_fma_f32 v[6:7], v[62:63], v[18:19], v[6:7] op_sel_hi:[1,0,1] neg_lo:[1,0,0] neg_hi:[1,0,0]
	v_pk_fma_f32 v[12:13], v[18:19], v[12:13], v[92:93] op_sel:[1,0,0]
	v_pk_fma_f32 v[10:11], v[18:19], v[10:11], v[90:91] op_sel:[1,0,0]
	v_pk_mul_f32 v[16:17], v[16:17], v[22:23]
	v_pk_mul_f32 v[14:15], v[14:15], v[20:21]
	v_pk_fma_f32 v[8:9], v[18:19], v[8:9], v[60:61] op_sel:[1,0,0]
	v_pk_fma_f32 v[6:7], v[18:19], v[6:7], v[58:59] op_sel:[1,0,0]
	v_pk_mul_f32 v[12:13], v[12:13], v[16:17]
	v_pk_mul_f32 v[10:11], v[10:11], v[14:15]
	v_mul_f32_e32 v14, 0xbfb8aa3b, v6
	v_mul_f32_e32 v15, 0xbfb8aa3b, v7
	v_mul_f32_e32 v16, 0xbfb8aa3b, v8
	v_mul_f32_e32 v17, 0xbfb8aa3b, v9
	v_exp_f32_e32 v14, v14
	v_exp_f32_e32 v15, v15
	v_exp_f32_e32 v16, v16
	v_exp_f32_e32 v17, v17
	v_add_f32_e32 v14, 1.0, v14
	v_add_f32_e32 v15, 1.0, v15
	v_add_f32_e32 v16, 1.0, v16
	v_add_f32_e32 v17, 1.0, v17
	v_rcp_f32_e32 v14, v14
	v_rcp_f32_e32 v15, v15
	v_rcp_f32_e32 v16, v16
	v_rcp_f32_e32 v17, v17
	v_pk_fma_f32 v[4:5], v[68:69], v[18:19], v[4:5] op_sel_hi:[1,0,1]
	v_pk_fma_f32 v[2:3], v[66:67], v[18:19], v[2:3] op_sel_hi:[1,0,1] neg_lo:[1,0,0] neg_hi:[1,0,0]
	v_pk_fma_f32 v[4:5], v[18:19], v[4:5], v[72:73] op_sel:[1,0,0]
	v_pk_fma_f32 v[2:3], v[18:19], v[2:3], v[70:71] op_sel:[1,0,0]
	v_pk_mul_f32 v[8:9], v[8:9], v[16:17]
	v_pk_mul_f32 v[6:7], v[6:7], v[14:15]
	v_pk_mul_f32 v[8:9], v[4:5], v[8:9]
	v_pk_mul_f32 v[4:5], v[2:3], v[6:7]
	v_add_lshl_u32 v6, v30, v130, 1
	v_cvt_pk_bf16_f32 v2, v10, v11
	v_cvt_pk_bf16_f32 v3, v12, v13
	v_cvt_pk_bf16_f32 v4, v4, v5
	v_cvt_pk_bf16_f32 v5, v8, v9
	buffer_store_dwordx4 v[2:5], v6, s[28:31], 0 offen sc1
	s_cbranch_vccz .LBB0_1098
	s_waitcnt vmcnt(0)
	v_readlane_b32 s76, v255, 13
	s_cmpk_gt_u32 s38, 0xff
	v_readlane_b32 s77, v255, 14
	s_cbranch_scc1 .LBB0_1103
	s_barrier

.LBB0_1178:
	s_add_u32 s27, s36, 0x100
	s_addc_u32 s91, s37, 0
	s_add_u32 s36, s42, 0x80
	s_addc_u32 s37, s43, 0
	s_mov_b32 s42, 0
	s_waitcnt lgkmcnt(0)
	s_add_i32 s92, s42, 2
	s_add_u32 s72, s36, 0x80
	s_addc_u32 s43, s37, 0
	s_add_i32 s93, 0, 0x10000
	v_add_u32_e32 v1, s93, v223
	ds_read_b128 v[50:53], v1
	ds_read_b128 v[54:57], v1 offset:1024
	ds_read_b128 v[58:61], v1 offset:2048
	ds_read_b128 v[62:65], v1 offset:3072
	s_cmp_eq_u32 s88, s42
	s_cselect_b32 s42, s66, s72
	s_cselect_b32 s43, s67, s43
	s_cselect_b32 s73, s71, s91
	s_cselect_b32 s72, s70, s27
	v_lshl_add_u64 v[178:179], s[36:37], 0, v[206:207]
	s_add_i32 m0, s79, 0xc000
	ds_read_b128 v[66:69], v230
	ds_read_b128 v[70:73], v230 offset:1024
	ds_read_b128 v[74:77], v230 offset:2048
	ds_read_b128 v[78:81], v230 offset:3072
	ds_read_b128 v[146:149], v230 offset:4096
	ds_read_b128 v[154:157], v230 offset:5120
	ds_read_b128 v[170:173], v230 offset:6144
	ds_read_b128 v[174:177], v230 offset:7168
	global_load_lds_dwordx4 v[178:179], off
	v_lshl_add_u64 v[178:179], s[36:37], 0, v[204:205]
	s_add_i32 m0, s79, 0xe000
	s_nop 0
	global_load_lds_dwordx4 v[178:179], off
	s_waitcnt lgkmcnt(8)
	s_barrier
	s_waitcnt lgkmcnt(0)
	s_setprio 1
	s_waitcnt lgkmcnt(0)
	v_mfma_f32_16x16x32_bf16 v[166:169], v[50:53], v[66:69], 0
	v_mfma_f32_16x16x32_bf16 v[162:165], v[58:61], v[66:69], 0
	v_mfma_f32_16x16x32_bf16 v[142:145], v[50:53], v[74:77], 0
	v_mfma_f32_16x16x32_bf16 v[138:141], v[58:61], v[74:77], 0
	v_mfma_f32_16x16x32_bf16 v[126:129], v[50:53], v[146:149], 0
	v_mfma_f32_16x16x32_bf16 v[122:125], v[58:61], v[146:149], 0
	v_mfma_f32_16x16x32_bf16 v[110:113], v[50:53], v[170:173], 0
	v_mfma_f32_16x16x32_bf16 v[106:109], v[58:61], v[170:173], 0
	v_mfma_f32_16x16x32_bf16 v[166:169], v[54:57], v[70:73], v[166:169]
	v_mfma_f32_16x16x32_bf16 v[162:165], v[62:65], v[70:73], v[162:165]
	v_mfma_f32_16x16x32_bf16 v[142:145], v[54:57], v[78:81], v[142:145]
	v_mfma_f32_16x16x32_bf16 v[138:141], v[62:65], v[78:81], v[138:141]
	v_mfma_f32_16x16x32_bf16 v[126:129], v[54:57], v[154:157], v[126:129]
	v_mfma_f32_16x16x32_bf16 v[122:125], v[62:65], v[154:157], v[122:125]
	v_mfma_f32_16x16x32_bf16 v[110:113], v[54:57], v[174:177], v[110:113]
	v_mfma_f32_16x16x32_bf16 v[106:109], v[62:65], v[174:177], v[106:109]
	s_setprio 0
	s_barrier
	s_add_i32 s94, 0, 0x14000
	s_add_i32 s93, s93, s78
	v_add_u32_e32 v1, s94, v223
	v_lshl_add_u64 v[214:215], s[72:73], 0, v[202:203]
	s_mov_b32 m0, s93
	ds_read_b128 v[178:181], v1
	ds_read_b128 v[182:185], v1 offset:1024
	ds_read_b128 v[186:189], v1 offset:2048
	ds_read_b128 v[190:193], v1 offset:3072
	global_load_lds_dwordx4 v[214:215], off
	v_lshl_add_u64 v[236:237], s[72:73], 0, v[200:201]
	s_add_i32 m0, s93, 0x2000
	s_nop 0
	global_load_lds_dwordx4 v[236:237], off
	s_barrier
	s_waitcnt lgkmcnt(0)
	s_setprio 1
	s_waitcnt lgkmcnt(0)
	v_mfma_f32_16x16x32_bf16 v[158:161], v[178:181], v[66:69], 0
	v_mfma_f32_16x16x32_bf16 v[66:69], v[186:189], v[66:69], 0
	v_mfma_f32_16x16x32_bf16 v[158:161], v[182:185], v[70:73], v[158:161]
	v_mfma_f32_16x16x32_bf16 v[66:69], v[190:193], v[70:73], v[66:69]
	v_mfma_f32_16x16x32_bf16 v[70:73], v[178:181], v[74:77], 0
	v_mfma_f32_16x16x32_bf16 v[74:77], v[186:189], v[74:77], 0
	v_mfma_f32_16x16x32_bf16 v[114:117], v[186:189], v[146:149], 0
	v_mfma_f32_16x16x32_bf16 v[102:105], v[178:181], v[170:173], 0
	v_mfma_f32_16x16x32_bf16 v[98:101], v[186:189], v[170:173], 0
	v_mfma_f32_16x16x32_bf16 v[70:73], v[182:185], v[78:81], v[70:73]
	v_mfma_f32_16x16x32_bf16 v[74:77], v[190:193], v[78:81], v[74:77]
	v_mfma_f32_16x16x32_bf16 v[78:81], v[178:181], v[146:149], 0
	v_mfma_f32_16x16x32_bf16 v[114:117], v[190:193], v[154:157], v[114:117]
	v_mfma_f32_16x16x32_bf16 v[102:105], v[182:185], v[174:177], v[102:105]
	v_mfma_f32_16x16x32_bf16 v[98:101], v[190:193], v[174:177], v[98:101]
	v_mfma_f32_16x16x32_bf16 v[78:81], v[182:185], v[154:157], v[78:81]
	s_setprio 0
	s_mov_b32 m0, s79
	v_lshl_add_u64 v[238:239], s[42:43], 0, v[202:203]
	s_barrier
	ds_read_b128 v[118:121], v230 offset:16384
	ds_read_b128 v[130:133], v230 offset:17408
	ds_read_b128 v[134:137], v230 offset:18432
	ds_read_b128 v[146:149], v230 offset:19456
	ds_read_b128 v[150:153], v230 offset:20480
	ds_read_b128 v[154:157], v230 offset:21504
	ds_read_b128 v[170:173], v230 offset:22528
	ds_read_b128 v[174:177], v230 offset:23552
	global_load_lds_dwordx4 v[238:239], off
	v_lshl_add_u64 v[240:241], s[42:43], 0, v[200:201]
	s_mov_b32 m0, s80
	s_nop 0
	global_load_lds_dwordx4 v[240:241], off
	s_barrier
	s_waitcnt lgkmcnt(0)
	s_setprio 1
	s_waitcnt lgkmcnt(0)
	v_mfma_f32_16x16x32_bf16 v[94:97], v[50:53], v[118:121], 0
	v_mfma_f32_16x16x32_bf16 v[90:93], v[58:61], v[118:121], 0
	v_mfma_f32_16x16x32_bf16 v[46:49], v[50:53], v[134:137], 0
	v_mfma_f32_16x16x32_bf16 v[42:45], v[58:61], v[134:137], 0
	v_mfma_f32_16x16x32_bf16 v[30:33], v[50:53], v[150:153], 0
	v_mfma_f32_16x16x32_bf16 v[26:29], v[58:61], v[150:153], 0
	v_mfma_f32_16x16x32_bf16 v[14:17], v[50:53], v[170:173], 0
	v_mfma_f32_16x16x32_bf16 v[10:13], v[58:61], v[170:173], 0
	v_mfma_f32_16x16x32_bf16 v[94:97], v[54:57], v[130:133], v[94:97]
	v_mfma_f32_16x16x32_bf16 v[90:93], v[62:65], v[130:133], v[90:93]
	v_mfma_f32_16x16x32_bf16 v[46:49], v[54:57], v[146:149], v[46:49]
	v_mfma_f32_16x16x32_bf16 v[42:45], v[62:65], v[146:149], v[42:45]
	v_mfma_f32_16x16x32_bf16 v[30:33], v[54:57], v[154:157], v[30:33]
	v_mfma_f32_16x16x32_bf16 v[26:29], v[62:65], v[154:157], v[26:29]
	v_mfma_f32_16x16x32_bf16 v[14:17], v[54:57], v[174:177], v[14:17]
	v_mfma_f32_16x16x32_bf16 v[10:13], v[62:65], v[174:177], v[10:13]
	s_setprio 0
	s_barrier
	s_add_u32 s72, s72, s4
	s_addc_u32 s73, s73, 0
	s_add_i32 s93, s94, s78
	v_lshl_add_u64 v[242:243], s[72:73], 0, v[202:203]
	s_mov_b32 m0, s93
	v_lshl_add_u64 v[244:245], s[72:73], 0, v[200:201]
	global_load_lds_dwordx4 v[242:243], off
	s_add_i32 m0, s93, 0x2000
	s_nop 0
	global_load_lds_dwordx4 v[244:245], off
	s_waitcnt vmcnt(6)
	s_barrier
	s_setprio 1
	v_mfma_f32_16x16x32_bf16 v[38:41], v[178:181], v[134:137], 0
	v_mfma_f32_16x16x32_bf16 v[34:37], v[186:189], v[134:137], 0
	v_mfma_f32_16x16x32_bf16 v[22:25], v[178:181], v[150:153], 0
	v_mfma_f32_16x16x32_bf16 v[18:21], v[186:189], v[150:153], 0
	v_mfma_f32_16x16x32_bf16 v[6:9], v[178:181], v[170:173], 0
	v_mfma_f32_16x16x32_bf16 v[2:5], v[186:189], v[170:173], 0
	v_mfma_f32_16x16x32_bf16 v[50:53], v[178:181], v[118:121], 0
	v_mfma_f32_16x16x32_bf16 v[54:57], v[186:189], v[118:121], 0
	v_mfma_f32_16x16x32_bf16 v[38:41], v[182:185], v[146:149], v[38:41]
	v_mfma_f32_16x16x32_bf16 v[34:37], v[190:193], v[146:149], v[34:37]
	v_mfma_f32_16x16x32_bf16 v[22:25], v[182:185], v[154:157], v[22:25]
	v_mfma_f32_16x16x32_bf16 v[18:21], v[190:193], v[154:157], v[18:21]
	v_mfma_f32_16x16x32_bf16 v[6:9], v[182:185], v[174:177], v[6:9]
	v_mfma_f32_16x16x32_bf16 v[2:5], v[190:193], v[174:177], v[2:5]
	v_mfma_f32_16x16x32_bf16 v[50:53], v[182:185], v[130:133], v[50:53]
	v_mfma_f32_16x16x32_bf16 v[54:57], v[190:193], v[130:133], v[54:57]
	s_setprio 0
	s_add_i32 s72, 0, 0x18000
	v_add_u32_e32 v1, s72, v223
	s_barrier
	ds_read_b128 v[58:61], v1
	ds_read_b128 v[62:65], v1 offset:1024
	ds_read_b128 v[82:85], v1 offset:2048
	ds_read_b128 v[86:89], v1 offset:3072
	s_add_u32 s42, s42, s4
	s_addc_u32 s43, s43, 0
	s_mov_b32 m0, s81
	v_lshl_add_u64 v[134:135], s[42:43], 0, v[202:203]
	ds_read_b128 v[118:121], v230 offset:32768
	ds_read_b128 v[130:133], v230 offset:33792
	ds_read_b128 v[146:149], v230 offset:34816
	ds_read_b128 v[154:157], v230 offset:35840
	ds_read_b128 v[170:173], v230 offset:36864
	ds_read_b128 v[174:177], v230 offset:37888
	ds_read_b128 v[178:181], v230 offset:38912
	ds_read_b128 v[182:185], v230 offset:39936
	global_load_lds_dwordx4 v[134:135], off
	v_lshl_add_u64 v[134:135], s[42:43], 0, v[200:201]
	s_mov_b32 m0, s82
	s_nop 0
	global_load_lds_dwordx4 v[134:135], off
	s_waitcnt lgkmcnt(8)
	s_barrier
	s_waitcnt lgkmcnt(0)
	s_setprio 1
	s_waitcnt lgkmcnt(0)
	v_mfma_f32_16x16x32_bf16 v[134:137], v[58:61], v[118:121], v[166:169]
	v_mfma_f32_16x16x32_bf16 v[166:169], v[62:65], v[130:133], v[134:137]
	v_mfma_f32_16x16x32_bf16 v[134:137], v[82:85], v[118:121], v[162:165]
	v_mfma_f32_16x16x32_bf16 v[162:165], v[86:89], v[130:133], v[134:137]
	v_mfma_f32_16x16x32_bf16 v[134:137], v[58:61], v[146:149], v[142:145]
	v_mfma_f32_16x16x32_bf16 v[142:145], v[62:65], v[154:157], v[134:137]
	v_mfma_f32_16x16x32_bf16 v[134:137], v[82:85], v[146:149], v[138:141]
	v_mfma_f32_16x16x32_bf16 v[126:129], v[58:61], v[170:173], v[126:129]
	v_mfma_f32_16x16x32_bf16 v[122:125], v[82:85], v[170:173], v[122:125]
	v_mfma_f32_16x16x32_bf16 v[110:113], v[58:61], v[178:181], v[110:113]
	v_mfma_f32_16x16x32_bf16 v[106:109], v[82:85], v[178:181], v[106:109]
	v_mfma_f32_16x16x32_bf16 v[138:141], v[86:89], v[154:157], v[134:137]
	v_mfma_f32_16x16x32_bf16 v[126:129], v[62:65], v[174:177], v[126:129]
	v_mfma_f32_16x16x32_bf16 v[122:125], v[86:89], v[174:177], v[122:125]
	v_mfma_f32_16x16x32_bf16 v[110:113], v[62:65], v[182:185], v[110:113]
	v_mfma_f32_16x16x32_bf16 v[106:109], v[86:89], v[182:185], v[106:109]
	s_setprio 0
	s_barrier
	s_add_i32 s42, 0, 0x1c000
	s_add_i32 s43, s72, s78
	v_add_u32_e32 v1, s42, v223
	v_lshl_add_u64 v[134:135], v[214:215], 0, s[22:23]
	s_mov_b32 m0, s43
	ds_read_b128 v[186:189], v1
	ds_read_b128 v[190:193], v1 offset:1024
	ds_read_b128 v[208:211], v1 offset:2048
	ds_read_b128 v[232:235], v1 offset:3072
	global_load_lds_dwordx4 v[134:135], off
	v_lshl_add_u64 v[134:135], v[236:237], 0, s[22:23]
	s_add_i32 m0, s43, 0x2000
	s_nop 0
	global_load_lds_dwordx4 v[134:135], off
	s_barrier
	s_waitcnt lgkmcnt(0)
	s_setprio 1
	s_waitcnt lgkmcnt(0)
	v_mfma_f32_16x16x32_bf16 v[66:69], v[208:211], v[118:121], v[66:69]
	v_mfma_f32_16x16x32_bf16 v[134:137], v[186:189], v[118:121], v[158:161]
	v_mfma_f32_16x16x32_bf16 v[150:153], v[232:235], v[130:133], v[66:69]
	v_mfma_f32_16x16x32_bf16 v[66:69], v[186:189], v[146:149], v[70:73]
	v_mfma_f32_16x16x32_bf16 v[158:161], v[190:193], v[130:133], v[134:137]
	v_mfma_f32_16x16x32_bf16 v[134:137], v[190:193], v[154:157], v[66:69]
	v_mfma_f32_16x16x32_bf16 v[66:69], v[208:211], v[146:149], v[74:77]
	v_mfma_f32_16x16x32_bf16 v[130:133], v[232:235], v[154:157], v[66:69]
	v_mfma_f32_16x16x32_bf16 v[66:69], v[186:189], v[170:173], v[78:81]
	v_mfma_f32_16x16x32_bf16 v[118:121], v[190:193], v[174:177], v[66:69]
	v_mfma_f32_16x16x32_bf16 v[66:69], v[208:211], v[170:173], v[114:117]
	v_mfma_f32_16x16x32_bf16 v[114:117], v[232:235], v[174:177], v[66:69]
	v_mfma_f32_16x16x32_bf16 v[66:69], v[186:189], v[178:181], v[102:105]
	v_mfma_f32_16x16x32_bf16 v[102:105], v[190:193], v[182:185], v[66:69]
	v_mfma_f32_16x16x32_bf16 v[66:69], v[208:211], v[178:181], v[98:101]
	v_mfma_f32_16x16x32_bf16 v[98:101], v[232:235], v[182:185], v[66:69]
	s_setprio 0
	s_mov_b32 m0, s86
	v_lshl_add_u64 v[178:179], v[238:239], 0, s[22:23]
	s_barrier
	s_nop 2
	ds_read_b128 v[66:69], v230 offset:49152
	ds_read_b128 v[70:73], v230 offset:50176
	ds_read_b128 v[74:77], v230 offset:51200
	ds_read_b128 v[78:81], v230 offset:52224
	ds_read_b128 v[146:149], v230 offset:53248
	ds_read_b128 v[154:157], v230 offset:54272
	ds_read_b128 v[170:173], v230 offset:55296
	ds_read_b128 v[174:177], v230 offset:56320
	global_load_lds_dwordx4 v[178:179], off
	v_lshl_add_u64 v[178:179], v[240:241], 0, s[22:23]
	s_mov_b32 m0, s87
	s_nop 0
	global_load_lds_dwordx4 v[178:179], off
	s_barrier
	s_waitcnt lgkmcnt(0)
	s_setprio 1
	s_waitcnt lgkmcnt(0)
	v_mfma_f32_16x16x32_bf16 v[94:97], v[58:61], v[66:69], v[94:97]
	v_mfma_f32_16x16x32_bf16 v[90:93], v[82:85], v[66:69], v[90:93]
	v_mfma_f32_16x16x32_bf16 v[46:49], v[58:61], v[74:77], v[46:49]
	v_mfma_f32_16x16x32_bf16 v[42:45], v[82:85], v[74:77], v[42:45]
	v_mfma_f32_16x16x32_bf16 v[30:33], v[58:61], v[146:149], v[30:33]
	v_mfma_f32_16x16x32_bf16 v[26:29], v[82:85], v[146:149], v[26:29]
	v_mfma_f32_16x16x32_bf16 v[14:17], v[58:61], v[170:173], v[14:17]
	v_mfma_f32_16x16x32_bf16 v[10:13], v[82:85], v[170:173], v[10:13]
	v_mfma_f32_16x16x32_bf16 v[94:97], v[62:65], v[70:73], v[94:97]
	v_mfma_f32_16x16x32_bf16 v[90:93], v[86:89], v[70:73], v[90:93]
	v_mfma_f32_16x16x32_bf16 v[46:49], v[62:65], v[78:81], v[46:49]
	v_mfma_f32_16x16x32_bf16 v[42:45], v[86:89], v[78:81], v[42:45]
	v_mfma_f32_16x16x32_bf16 v[30:33], v[62:65], v[154:157], v[30:33]
	v_mfma_f32_16x16x32_bf16 v[26:29], v[86:89], v[154:157], v[26:29]
	v_mfma_f32_16x16x32_bf16 v[14:17], v[62:65], v[174:177], v[14:17]
	v_mfma_f32_16x16x32_bf16 v[10:13], v[86:89], v[174:177], v[10:13]
	s_setprio 0
	s_barrier
	s_add_i32 s42, s42, s78
	v_lshl_add_u64 v[58:59], v[242:243], 0, s[22:23]
	s_mov_b32 m0, s42
	s_nop 0
	global_load_lds_dwordx4 v[58:59], off
	v_lshl_add_u64 v[58:59], v[244:245], 0, s[22:23]
	s_add_i32 m0, s42, 0x2000
	s_nop 0
	global_load_lds_dwordx4 v[58:59], off
	s_waitcnt vmcnt(6)
	s_barrier
	s_setprio 1
	v_mfma_f32_16x16x32_bf16 v[50:53], v[186:189], v[66:69], v[50:53]
	v_mfma_f32_16x16x32_bf16 v[86:89], v[190:193], v[70:73], v[50:53]
	v_mfma_f32_16x16x32_bf16 v[50:53], v[208:211], v[66:69], v[54:57]
	v_mfma_f32_16x16x32_bf16 v[38:41], v[186:189], v[74:77], v[38:41]
	v_mfma_f32_16x16x32_bf16 v[34:37], v[208:211], v[74:77], v[34:37]
	v_mfma_f32_16x16x32_bf16 v[22:25], v[186:189], v[146:149], v[22:25]
	v_mfma_f32_16x16x32_bf16 v[18:21], v[208:211], v[146:149], v[18:21]
	v_mfma_f32_16x16x32_bf16 v[6:9], v[186:189], v[170:173], v[6:9]
	v_mfma_f32_16x16x32_bf16 v[2:5], v[208:211], v[170:173], v[2:5]
	v_mfma_f32_16x16x32_bf16 v[82:85], v[232:235], v[70:73], v[50:53]
	v_mfma_f32_16x16x32_bf16 v[38:41], v[190:193], v[78:81], v[38:41]
	v_mfma_f32_16x16x32_bf16 v[34:37], v[232:235], v[78:81], v[34:37]
	v_mfma_f32_16x16x32_bf16 v[22:25], v[190:193], v[154:157], v[22:25]
	v_mfma_f32_16x16x32_bf16 v[18:21], v[232:235], v[154:157], v[18:21]
	v_mfma_f32_16x16x32_bf16 v[6:9], v[190:193], v[174:177], v[6:9]
	v_mfma_f32_16x16x32_bf16 v[2:5], v[232:235], v[174:177], v[2:5]
	s_setprio 0
	s_add_u32 s27, s27, 0x100
	s_addc_u32 s91, s91, 0
	s_add_u32 s36, s36, 0x100
	s_addc_u32 s37, s37, 0
	s_cmp_ge_u32 s92, s84
	s_mov_b32 s42, s92
.Lrot_1:
	s_barrier
.LBB0_1179:
	s_add_i32 s92, s42, 2
	s_add_u32 s72, s36, 0x80
	s_addc_u32 s43, s37, 0
	s_add_i32 s93, 0, 0x10000
	v_add_u32_e32 v1, s93, v223
	ds_read_b128 v[50:53], v1
	ds_read_b128 v[54:57], v1 offset:1024
	ds_read_b128 v[58:61], v1 offset:2048
	ds_read_b128 v[62:65], v1 offset:3072
	s_cmp_eq_u32 s88, s42
	s_cselect_b32 s42, s66, s72
	s_cselect_b32 s43, s67, s43
	s_cselect_b32 s73, s71, s91
	s_cselect_b32 s72, s70, s27
	v_lshl_add_u64 v[178:179], s[36:37], 0, v[206:207]
	s_add_i32 m0, s79, 0xc000
	ds_read_b128 v[66:69], v230
	ds_read_b128 v[70:73], v230 offset:1024
	ds_read_b128 v[74:77], v230 offset:2048
	ds_read_b128 v[78:81], v230 offset:3072
	ds_read_b128 v[146:149], v230 offset:4096
	ds_read_b128 v[154:157], v230 offset:5120
	ds_read_b128 v[170:173], v230 offset:6144
	ds_read_b128 v[174:177], v230 offset:7168
	global_load_lds_dwordx4 v[178:179], off
	v_lshl_add_u64 v[178:179], s[36:37], 0, v[204:205]
	s_add_i32 m0, s79, 0xe000
	s_nop 0
	global_load_lds_dwordx4 v[178:179], off
	s_waitcnt lgkmcnt(8)
	s_barrier
	s_waitcnt lgkmcnt(0)
	s_setprio 1
	s_waitcnt lgkmcnt(0)
	v_mfma_f32_16x16x32_bf16 v[166:169], v[50:53], v[66:69], v[166:169]
	v_mfma_f32_16x16x32_bf16 v[162:165], v[58:61], v[66:69], v[162:165]
	v_mfma_f32_16x16x32_bf16 v[142:145], v[50:53], v[74:77], v[142:145]
	v_mfma_f32_16x16x32_bf16 v[138:141], v[58:61], v[74:77], v[138:141]
	v_mfma_f32_16x16x32_bf16 v[126:129], v[50:53], v[146:149], v[126:129]
	v_mfma_f32_16x16x32_bf16 v[122:125], v[58:61], v[146:149], v[122:125]
	v_mfma_f32_16x16x32_bf16 v[110:113], v[50:53], v[170:173], v[110:113]
	v_mfma_f32_16x16x32_bf16 v[106:109], v[58:61], v[170:173], v[106:109]
	v_mfma_f32_16x16x32_bf16 v[166:169], v[54:57], v[70:73], v[166:169]
	v_mfma_f32_16x16x32_bf16 v[162:165], v[62:65], v[70:73], v[162:165]
	v_mfma_f32_16x16x32_bf16 v[142:145], v[54:57], v[78:81], v[142:145]
	v_mfma_f32_16x16x32_bf16 v[138:141], v[62:65], v[78:81], v[138:141]
	v_mfma_f32_16x16x32_bf16 v[126:129], v[54:57], v[154:157], v[126:129]
	v_mfma_f32_16x16x32_bf16 v[122:125], v[62:65], v[154:157], v[122:125]
	v_mfma_f32_16x16x32_bf16 v[110:113], v[54:57], v[174:177], v[110:113]
	v_mfma_f32_16x16x32_bf16 v[106:109], v[62:65], v[174:177], v[106:109]
	s_setprio 0
	s_barrier
	s_add_i32 s94, 0, 0x14000
	s_add_i32 s93, s93, s78
	v_add_u32_e32 v1, s94, v223
	v_lshl_add_u64 v[214:215], s[72:73], 0, v[202:203]
	s_mov_b32 m0, s93
	ds_read_b128 v[178:181], v1
	ds_read_b128 v[182:185], v1 offset:1024
	ds_read_b128 v[186:189], v1 offset:2048
	ds_read_b128 v[190:193], v1 offset:3072
	global_load_lds_dwordx4 v[214:215], off
	v_lshl_add_u64 v[236:237], s[72:73], 0, v[200:201]
	s_add_i32 m0, s93, 0x2000
	s_nop 0
	global_load_lds_dwordx4 v[236:237], off
	s_barrier
	s_waitcnt lgkmcnt(0)
	s_setprio 1
	s_waitcnt lgkmcnt(0)
	v_mfma_f32_16x16x32_bf16 v[158:161], v[178:181], v[66:69], v[158:161]
	v_mfma_f32_16x16x32_bf16 v[66:69], v[186:189], v[66:69], v[150:153]
	v_mfma_f32_16x16x32_bf16 v[158:161], v[182:185], v[70:73], v[158:161]
	v_mfma_f32_16x16x32_bf16 v[66:69], v[190:193], v[70:73], v[66:69]
	v_mfma_f32_16x16x32_bf16 v[70:73], v[178:181], v[74:77], v[134:137]
	v_mfma_f32_16x16x32_bf16 v[74:77], v[186:189], v[74:77], v[130:133]
	v_mfma_f32_16x16x32_bf16 v[114:117], v[186:189], v[146:149], v[114:117]
	v_mfma_f32_16x16x32_bf16 v[102:105], v[178:181], v[170:173], v[102:105]
	v_mfma_f32_16x16x32_bf16 v[98:101], v[186:189], v[170:173], v[98:101]
	v_mfma_f32_16x16x32_bf16 v[70:73], v[182:185], v[78:81], v[70:73]
	v_mfma_f32_16x16x32_bf16 v[74:77], v[190:193], v[78:81], v[74:77]
	v_mfma_f32_16x16x32_bf16 v[78:81], v[178:181], v[146:149], v[118:121]
	v_mfma_f32_16x16x32_bf16 v[114:117], v[190:193], v[154:157], v[114:117]
	v_mfma_f32_16x16x32_bf16 v[102:105], v[182:185], v[174:177], v[102:105]
	v_mfma_f32_16x16x32_bf16 v[98:101], v[190:193], v[174:177], v[98:101]
	v_mfma_f32_16x16x32_bf16 v[78:81], v[182:185], v[154:157], v[78:81]
	s_setprio 0
	s_mov_b32 m0, s79
	v_lshl_add_u64 v[238:239], s[42:43], 0, v[202:203]
	s_barrier
	ds_read_b128 v[118:121], v230 offset:16384
	ds_read_b128 v[130:133], v230 offset:17408
	ds_read_b128 v[134:137], v230 offset:18432
	ds_read_b128 v[146:149], v230 offset:19456
	ds_read_b128 v[150:153], v230 offset:20480
	ds_read_b128 v[154:157], v230 offset:21504
	ds_read_b128 v[170:173], v230 offset:22528
	ds_read_b128 v[174:177], v230 offset:23552
	global_load_lds_dwordx4 v[238:239], off
	v_lshl_add_u64 v[240:241], s[42:43], 0, v[200:201]
	s_mov_b32 m0, s80
	s_nop 0
	global_load_lds_dwordx4 v[240:241], off
	s_barrier
	s_waitcnt lgkmcnt(0)
	s_setprio 1
	s_waitcnt lgkmcnt(0)
	v_mfma_f32_16x16x32_bf16 v[94:97], v[50:53], v[118:121], v[94:97]
	v_mfma_f32_16x16x32_bf16 v[90:93], v[58:61], v[118:121], v[90:93]
	v_mfma_f32_16x16x32_bf16 v[46:49], v[50:53], v[134:137], v[46:49]
	v_mfma_f32_16x16x32_bf16 v[42:45], v[58:61], v[134:137], v[42:45]
	v_mfma_f32_16x16x32_bf16 v[30:33], v[50:53], v[150:153], v[30:33]
	v_mfma_f32_16x16x32_bf16 v[26:29], v[58:61], v[150:153], v[26:29]
	v_mfma_f32_16x16x32_bf16 v[14:17], v[50:53], v[170:173], v[14:17]
	v_mfma_f32_16x16x32_bf16 v[10:13], v[58:61], v[170:173], v[10:13]
	v_mfma_f32_16x16x32_bf16 v[94:97], v[54:57], v[130:133], v[94:97]
	v_mfma_f32_16x16x32_bf16 v[90:93], v[62:65], v[130:133], v[90:93]
	v_mfma_f32_16x16x32_bf16 v[46:49], v[54:57], v[146:149], v[46:49]
	v_mfma_f32_16x16x32_bf16 v[42:45], v[62:65], v[146:149], v[42:45]
	v_mfma_f32_16x16x32_bf16 v[30:33], v[54:57], v[154:157], v[30:33]
	v_mfma_f32_16x16x32_bf16 v[26:29], v[62:65], v[154:157], v[26:29]
	v_mfma_f32_16x16x32_bf16 v[14:17], v[54:57], v[174:177], v[14:17]
	v_mfma_f32_16x16x32_bf16 v[10:13], v[62:65], v[174:177], v[10:13]
	s_setprio 0
	s_barrier
	s_add_u32 s72, s72, s4
	s_addc_u32 s73, s73, 0
	s_add_i32 s93, s94, s78
	v_lshl_add_u64 v[242:243], s[72:73], 0, v[202:203]
	s_mov_b32 m0, s93
	v_lshl_add_u64 v[244:245], s[72:73], 0, v[200:201]
	global_load_lds_dwordx4 v[242:243], off
	s_add_i32 m0, s93, 0x2000
	s_nop 0
	global_load_lds_dwordx4 v[244:245], off
	s_waitcnt vmcnt(6)
	s_barrier
	s_setprio 1
	v_mfma_f32_16x16x32_bf16 v[38:41], v[178:181], v[134:137], v[38:41]
	v_mfma_f32_16x16x32_bf16 v[34:37], v[186:189], v[134:137], v[34:37]
	v_mfma_f32_16x16x32_bf16 v[22:25], v[178:181], v[150:153], v[22:25]
	v_mfma_f32_16x16x32_bf16 v[18:21], v[186:189], v[150:153], v[18:21]
	v_mfma_f32_16x16x32_bf16 v[6:9], v[178:181], v[170:173], v[6:9]
	v_mfma_f32_16x16x32_bf16 v[2:5], v[186:189], v[170:173], v[2:5]
	v_mfma_f32_16x16x32_bf16 v[50:53], v[178:181], v[118:121], v[86:89]
	v_mfma_f32_16x16x32_bf16 v[54:57], v[186:189], v[118:121], v[82:85]
	v_mfma_f32_16x16x32_bf16 v[38:41], v[182:185], v[146:149], v[38:41]
	v_mfma_f32_16x16x32_bf16 v[34:37], v[190:193], v[146:149], v[34:37]
	v_mfma_f32_16x16x32_bf16 v[22:25], v[182:185], v[154:157], v[22:25]
	v_mfma_f32_16x16x32_bf16 v[18:21], v[190:193], v[154:157], v[18:21]
	v_mfma_f32_16x16x32_bf16 v[6:9], v[182:185], v[174:177], v[6:9]
	v_mfma_f32_16x16x32_bf16 v[2:5], v[190:193], v[174:177], v[2:5]
	v_mfma_f32_16x16x32_bf16 v[50:53], v[182:185], v[130:133], v[50:53]
	v_mfma_f32_16x16x32_bf16 v[54:57], v[190:193], v[130:133], v[54:57]
	s_setprio 0
	s_add_i32 s72, 0, 0x18000
	v_add_u32_e32 v1, s72, v223
	s_barrier
	ds_read_b128 v[58:61], v1
	ds_read_b128 v[62:65], v1 offset:1024
	ds_read_b128 v[82:85], v1 offset:2048
	ds_read_b128 v[86:89], v1 offset:3072
	s_add_u32 s42, s42, s4
	s_addc_u32 s43, s43, 0
	s_mov_b32 m0, s81
	v_lshl_add_u64 v[134:135], s[42:43], 0, v[202:203]
	ds_read_b128 v[118:121], v230 offset:32768
	ds_read_b128 v[130:133], v230 offset:33792
	ds_read_b128 v[146:149], v230 offset:34816
	ds_read_b128 v[154:157], v230 offset:35840
	ds_read_b128 v[170:173], v230 offset:36864
	ds_read_b128 v[174:177], v230 offset:37888
	ds_read_b128 v[178:181], v230 offset:38912
	ds_read_b128 v[182:185], v230 offset:39936
	global_load_lds_dwordx4 v[134:135], off
	v_lshl_add_u64 v[134:135], s[42:43], 0, v[200:201]
	s_mov_b32 m0, s82
	s_nop 0
	global_load_lds_dwordx4 v[134:135], off
	s_waitcnt lgkmcnt(8)
	s_barrier
	s_waitcnt lgkmcnt(0)
	s_setprio 1
	s_waitcnt lgkmcnt(0)
	v_mfma_f32_16x16x32_bf16 v[134:137], v[58:61], v[118:121], v[166:169]
	v_mfma_f32_16x16x32_bf16 v[166:169], v[62:65], v[130:133], v[134:137]
	v_mfma_f32_16x16x32_bf16 v[134:137], v[82:85], v[118:121], v[162:165]
	v_mfma_f32_16x16x32_bf16 v[162:165], v[86:89], v[130:133], v[134:137]
	v_mfma_f32_16x16x32_bf16 v[134:137], v[58:61], v[146:149], v[142:145]
	v_mfma_f32_16x16x32_bf16 v[142:145], v[62:65], v[154:157], v[134:137]
	v_mfma_f32_16x16x32_bf16 v[134:137], v[82:85], v[146:149], v[138:141]
	v_mfma_f32_16x16x32_bf16 v[126:129], v[58:61], v[170:173], v[126:129]
	v_mfma_f32_16x16x32_bf16 v[122:125], v[82:85], v[170:173], v[122:125]
	v_mfma_f32_16x16x32_bf16 v[110:113], v[58:61], v[178:181], v[110:113]
	v_mfma_f32_16x16x32_bf16 v[106:109], v[82:85], v[178:181], v[106:109]
	v_mfma_f32_16x16x32_bf16 v[138:141], v[86:89], v[154:157], v[134:137]
	v_mfma_f32_16x16x32_bf16 v[126:129], v[62:65], v[174:177], v[126:129]
	v_mfma_f32_16x16x32_bf16 v[122:125], v[86:89], v[174:177], v[122:125]
	v_mfma_f32_16x16x32_bf16 v[110:113], v[62:65], v[182:185], v[110:113]
	v_mfma_f32_16x16x32_bf16 v[106:109], v[86:89], v[182:185], v[106:109]
	s_setprio 0
	s_barrier
	s_add_i32 s42, 0, 0x1c000
	s_add_i32 s43, s72, s78
	v_add_u32_e32 v1, s42, v223
	v_lshl_add_u64 v[134:135], v[214:215], 0, s[22:23]
	s_mov_b32 m0, s43
	ds_read_b128 v[186:189], v1
	ds_read_b128 v[190:193], v1 offset:1024
	ds_read_b128 v[208:211], v1 offset:2048
	ds_read_b128 v[232:235], v1 offset:3072
	global_load_lds_dwordx4 v[134:135], off
	v_lshl_add_u64 v[134:135], v[236:237], 0, s[22:23]
	s_add_i32 m0, s43, 0x2000
	s_nop 0
	global_load_lds_dwordx4 v[134:135], off
	s_barrier
	s_waitcnt lgkmcnt(0)
	s_setprio 1
	s_waitcnt lgkmcnt(0)
	v_mfma_f32_16x16x32_bf16 v[66:69], v[208:211], v[118:121], v[66:69]
	v_mfma_f32_16x16x32_bf16 v[134:137], v[186:189], v[118:121], v[158:161]
	v_mfma_f32_16x16x32_bf16 v[150:153], v[232:235], v[130:133], v[66:69]
	v_mfma_f32_16x16x32_bf16 v[66:69], v[186:189], v[146:149], v[70:73]
	v_mfma_f32_16x16x32_bf16 v[158:161], v[190:193], v[130:133], v[134:137]
	v_mfma_f32_16x16x32_bf16 v[134:137], v[190:193], v[154:157], v[66:69]
	v_mfma_f32_16x16x32_bf16 v[66:69], v[208:211], v[146:149], v[74:77]
	v_mfma_f32_16x16x32_bf16 v[130:133], v[232:235], v[154:157], v[66:69]
	v_mfma_f32_16x16x32_bf16 v[66:69], v[186:189], v[170:173], v[78:81]
	v_mfma_f32_16x16x32_bf16 v[118:121], v[190:193], v[174:177], v[66:69]
	v_mfma_f32_16x16x32_bf16 v[66:69], v[208:211], v[170:173], v[114:117]
	v_mfma_f32_16x16x32_bf16 v[114:117], v[232:235], v[174:177], v[66:69]
	v_mfma_f32_16x16x32_bf16 v[66:69], v[186:189], v[178:181], v[102:105]
	v_mfma_f32_16x16x32_bf16 v[102:105], v[190:193], v[182:185], v[66:69]
	v_mfma_f32_16x16x32_bf16 v[66:69], v[208:211], v[178:181], v[98:101]
	v_mfma_f32_16x16x32_bf16 v[98:101], v[232:235], v[182:185], v[66:69]
	s_setprio 0
	s_mov_b32 m0, s86
	v_lshl_add_u64 v[178:179], v[238:239], 0, s[22:23]
	s_barrier
	s_nop 2
	ds_read_b128 v[66:69], v230 offset:49152
	ds_read_b128 v[70:73], v230 offset:50176
	ds_read_b128 v[74:77], v230 offset:51200
	ds_read_b128 v[78:81], v230 offset:52224
	ds_read_b128 v[146:149], v230 offset:53248
	ds_read_b128 v[154:157], v230 offset:54272
	ds_read_b128 v[170:173], v230 offset:55296
	ds_read_b128 v[174:177], v230 offset:56320
	global_load_lds_dwordx4 v[178:179], off
	v_lshl_add_u64 v[178:179], v[240:241], 0, s[22:23]
	s_mov_b32 m0, s87
	s_nop 0
	global_load_lds_dwordx4 v[178:179], off
	s_barrier
	s_waitcnt lgkmcnt(0)
	s_setprio 1
	s_waitcnt lgkmcnt(0)
	v_mfma_f32_16x16x32_bf16 v[94:97], v[58:61], v[66:69], v[94:97]
	v_mfma_f32_16x16x32_bf16 v[90:93], v[82:85], v[66:69], v[90:93]
	v_mfma_f32_16x16x32_bf16 v[46:49], v[58:61], v[74:77], v[46:49]
	v_mfma_f32_16x16x32_bf16 v[42:45], v[82:85], v[74:77], v[42:45]
	v_mfma_f32_16x16x32_bf16 v[30:33], v[58:61], v[146:149], v[30:33]
	v_mfma_f32_16x16x32_bf16 v[26:29], v[82:85], v[146:149], v[26:29]
	v_mfma_f32_16x16x32_bf16 v[14:17], v[58:61], v[170:173], v[14:17]
	v_mfma_f32_16x16x32_bf16 v[10:13], v[82:85], v[170:173], v[10:13]
	v_mfma_f32_16x16x32_bf16 v[94:97], v[62:65], v[70:73], v[94:97]
	v_mfma_f32_16x16x32_bf16 v[90:93], v[86:89], v[70:73], v[90:93]
	v_mfma_f32_16x16x32_bf16 v[46:49], v[62:65], v[78:81], v[46:49]
	v_mfma_f32_16x16x32_bf16 v[42:45], v[86:89], v[78:81], v[42:45]
	v_mfma_f32_16x16x32_bf16 v[30:33], v[62:65], v[154:157], v[30:33]
	v_mfma_f32_16x16x32_bf16 v[26:29], v[86:89], v[154:157], v[26:29]
	v_mfma_f32_16x16x32_bf16 v[14:17], v[62:65], v[174:177], v[14:17]
	v_mfma_f32_16x16x32_bf16 v[10:13], v[86:89], v[174:177], v[10:13]
	s_setprio 0
	s_barrier
	s_add_i32 s42, s42, s78
	v_lshl_add_u64 v[58:59], v[242:243], 0, s[22:23]
	s_mov_b32 m0, s42
	s_nop 0
	global_load_lds_dwordx4 v[58:59], off
	v_lshl_add_u64 v[58:59], v[244:245], 0, s[22:23]
	s_add_i32 m0, s42, 0x2000
	s_nop 0
	global_load_lds_dwordx4 v[58:59], off
	s_waitcnt vmcnt(6)
	s_barrier
	s_setprio 1
	v_mfma_f32_16x16x32_bf16 v[50:53], v[186:189], v[66:69], v[50:53]
	v_mfma_f32_16x16x32_bf16 v[86:89], v[190:193], v[70:73], v[50:53]
	v_mfma_f32_16x16x32_bf16 v[50:53], v[208:211], v[66:69], v[54:57]
	v_mfma_f32_16x16x32_bf16 v[38:41], v[186:189], v[74:77], v[38:41]
	v_mfma_f32_16x16x32_bf16 v[34:37], v[208:211], v[74:77], v[34:37]
	v_mfma_f32_16x16x32_bf16 v[22:25], v[186:189], v[146:149], v[22:25]
	v_mfma_f32_16x16x32_bf16 v[18:21], v[208:211], v[146:149], v[18:21]
	v_mfma_f32_16x16x32_bf16 v[6:9], v[186:189], v[170:173], v[6:9]
	v_mfma_f32_16x16x32_bf16 v[2:5], v[208:211], v[170:173], v[2:5]
	v_mfma_f32_16x16x32_bf16 v[82:85], v[232:235], v[70:73], v[50:53]
	v_mfma_f32_16x16x32_bf16 v[38:41], v[190:193], v[78:81], v[38:41]
	v_mfma_f32_16x16x32_bf16 v[34:37], v[232:235], v[78:81], v[34:37]
	v_mfma_f32_16x16x32_bf16 v[22:25], v[190:193], v[154:157], v[22:25]
	v_mfma_f32_16x16x32_bf16 v[18:21], v[232:235], v[154:157], v[18:21]
	v_mfma_f32_16x16x32_bf16 v[6:9], v[190:193], v[174:177], v[6:9]
	v_mfma_f32_16x16x32_bf16 v[2:5], v[232:235], v[174:177], v[2:5]
	s_setprio 0
	s_add_u32 s27, s27, 0x100
	s_addc_u32 s91, s91, 0
	s_add_u32 s36, s36, 0x100
	s_addc_u32 s37, s37, 0
	s_cmp_ge_u32 s92, s84
	s_mov_b32 s42, s92
	s_cbranch_scc0 .Lrot_1
	s_barrier
	s_lshl_b32 s3, s3, 8
	s_add_i32 s27, s3, s85
	v_lshl_or_b32 v210, s38, 8, v224
	v_or_b32_e32 v146, s27, v221
	v_ashrrev_i32_e32 v147, 31, v146
	v_ashrrev_i32_e32 v211, 31, v210
	v_lshlrev_b64 v[50:51], 2, v[210:211]
	v_lshl_add_u64 v[208:209], v[210:211], 1, s[48:49]
	v_lshlrev_b64 v[148:149], 11, v[146:147]
	v_lshl_add_u64 v[52:53], s[52:53], 0, v[50:51]
	v_lshl_add_u64 v[54:55], s[54:55], 0, v[50:51]
	v_lshl_add_u64 v[148:149], v[208:209], 0, v[148:149]
	global_load_dwordx4 v[74:77], v[52:53], off
	global_load_dwordx4 v[66:69], v[52:53], off offset:16
	global_load_dwordx4 v[78:81], v[54:55], off
	global_load_dwordx4 v[70:73], v[54:55], off offset:16
	global_load_dwordx4 v[58:61], v[52:53], off offset:512
	s_nop 0
	global_load_dwordx4 v[50:53], v[52:53], off offset:528
	s_nop 0
	global_load_dwordx4 v[62:65], v[54:55], off offset:512
	s_nop 0
	global_load_dwordx4 v[54:57], v[54:55], off offset:528
	global_load_dwordx4 v[190:193], v[148:149], off
	global_load_dwordx4 v[186:189], v[148:149], off offset:256
	v_or_b32_e32 v148, 16, v146
	v_ashrrev_i32_e32 v149, 31, v148
	v_lshlrev_b64 v[148:149], 11, v[148:149]
	v_lshl_add_u64 v[148:149], v[208:209], 0, v[148:149]
	global_load_dwordx4 v[182:185], v[148:149], off
	global_load_dwordx4 v[178:181], v[148:149], off offset:256
	v_or_b32_e32 v148, 32, v146
	v_or_b32_e32 v146, 48, v146
	v_ashrrev_i32_e32 v149, 31, v148
	v_ashrrev_i32_e32 v147, 31, v146
	v_lshlrev_b64 v[148:149], 11, v[148:149]
	v_lshlrev_b64 v[146:147], 11, v[146:147]
	v_mov_b32_e32 v1, v222
	v_lshl_add_u64 v[148:149], v[208:209], 0, v[148:149]
	v_lshl_add_u64 v[146:147], v[208:209], 0, v[146:147]
	global_load_dwordx4 v[174:177], v[148:149], off
	global_load_dwordx4 v[170:173], v[148:149], off offset:256
	global_load_dwordx4 v[154:157], v[146:147], off
	s_nop 0
	global_load_dwordx4 v[146:149], v[146:147], off offset:256
	v_cndmask_b32_e64 v211, 0, 1, s[56:57]
	v_cmp_ne_u32_e64 s[42:43], 1, v211
	s_andn2_b64 vcc, exec, s[56:57]
	v_lshl_add_u32 v231, v1, 3, s33
	s_cbranch_vccnz .LBB0_1182
	ds_read_b64 v[214:215], v231
	s_waitcnt lgkmcnt(0)
	v_mov_b32_e32 v212, v215
	s_branch .LBB0_1183
